# GVT workspace regrouped as [batch,head][chunk][token-half][row][64 B] (gla_in transposed-V stores and gla_scan V loads agree): each V load reads 1 KB contiguous
# speedup vs baseline: 1.0166x; 1.0087x over previous
; DI u32x2 pk4(float a, float b, float c, float d) { u32x2 r; r.x = pk2(a, b); r.y = pk2(c, d); return r; }
;     ...
;         if (vtile) {
; #pragma unroll
;             for (int mi = 0; mi < MI; ++mi)
; #pragma unroll
;                 for (int ch = 0; ch < 2; ++ch) {
;                     const int tok = mt * 256 + wr * C::WROWS + mi * 32 + ch * 16 + 4 * q, bb = tok >> 12, sq = tok & 4095;
; #pragma unroll
;                     for (int ni = 0; ni < 2; ++ni)
; #pragma unroll
;                         for (int rh = 0; rh < 2; ++rh) {
;                             const int n = (nt * C::BN + wc * 64 - 1024) + ni * 32 + rh * 16 + r16;
;                             const f32x4 v = acc[mi][ni][rh][ch];
;                             *(u32x2*)(GVT + ((size_t)(bb * 1024 + n)) * 4096 + sq) = pk4(v.x, v.y, v.z, v.w);
;                         }
;                 }
.LBB0_330:
	s_and_b64 vcc, exec, s[0:1]
	s_cbranch_vccz .LBB0_194
	v_and_b32_e32 v129, 0xf80, v128
	v_ashrrev_i32_e32 v128, 2, v128
	s_addk_i32 s52, 0xfc00
	v_lshlrev_b32_e32 v130, 6, v149
	v_and_b32_e32 v128, 0xfffffc00, v128
	v_or_b32_e32 v131, s52, v148
	v_add3_u32 v128, v131, v130, v128
	v_lshlrev_b32_e32 v129, 1, v129
	v_readlane_b32 s0, v253, 11
	v_cvt_pk_bf16_f32 v120, v120, v121
	v_cvt_pk_bf16_f32 v121, v122, v123
	v_or_b32_e32 v122, 16, v128
	v_lshl_or_b32 v176, v141, 3, v129
	v_readlane_b32 s1, v253, 12
	v_ashrrev_i32_e32 v123, 31, v122
	v_lshlrev_b64 v[122:123], 13, v[122:123]
	v_lshl_add_u64 v[130:131], s[0:1], 0, v[176:177]
	v_lshrrev_b32_e32 v238, 8, v128
	v_lshlrev_b32_e32 v238, 21, v238
	v_lshl_add_u32 v238, v129, 8, v238
	v_and_b32_e32 v240, 0xff, v128
	v_lshl_add_u32 v238, v240, 6, v238
	v_lshl_add_u32 v238, v141, 3, v238
	v_mov_b32_e32 v239, 0
	v_lshl_add_u64 v[230:231], s[0:1], 0, v[238:239]
	s_mov_b64 s[98:99], 0x4000
	v_lshl_add_u64 v[232:233], v[230:231], 0, s[98:99]
	v_lshl_add_u64 v[234:235], v[232:233], 0, s[98:99]
	v_lshl_add_u64 v[236:237], v[234:235], 0, s[98:99]
	v_lshl_add_u64 v[122:123], v[130:131], 0, v[122:123]
	v_cvt_pk_bf16_f32 v104, v104, v105
	v_cvt_pk_bf16_f32 v105, v106, v107
	v_or_b32_e32 v106, 48, v128
	global_store_dwordx2 v[230:231], v[120:121], off offset:1024
	v_or_b32_e32 v120, 32, v128
	v_ashrrev_i32_e32 v107, 31, v106
	v_ashrrev_i32_e32 v129, 31, v128
	v_ashrrev_i32_e32 v121, 31, v120
	v_lshlrev_b64 v[106:107], 13, v[106:107]
	v_cvt_pk_bf16_f32 v124, v124, v125
	v_cvt_pk_bf16_f32 v125, v126, v127
	v_lshlrev_b64 v[126:127], 13, v[128:129]
	v_cvt_pk_bf16_f32 v112, v112, v113
	v_cvt_pk_bf16_f32 v113, v114, v115
	v_lshlrev_b64 v[114:115], 13, v[120:121]
	v_lshl_add_u64 v[106:107], v[130:131], 0, v[106:107]
	v_cvt_pk_bf16_f32 v72, v72, v73
	v_cvt_pk_bf16_f32 v73, v74, v75
	v_cvt_pk_bf16_f32 v36, v36, v37
	v_cvt_pk_bf16_f32 v37, v38, v39
	v_cvt_pk_bf16_f32 v4, v4, v5
	v_cvt_pk_bf16_f32 v5, v6, v7
	v_lshl_add_u64 v[126:127], v[130:131], 0, v[126:127]
	v_lshl_add_u64 v[114:115], v[130:131], 0, v[114:115]
	global_store_dwordx2 v[230:231], v[104:105], off offset:3072
	v_cvt_pk_bf16_f32 v104, v116, v117
	v_cvt_pk_bf16_f32 v105, v118, v119
	global_store_dwordx2 v[232:233], v[72:73], off offset:3072
	v_cvt_pk_bf16_f32 v72, v84, v85
	v_cvt_pk_bf16_f32 v73, v86, v87
	global_store_dwordx2 v[234:235], v[36:37], off offset:3072
	v_cvt_pk_bf16_f32 v36, v48, v49
	v_cvt_pk_bf16_f32 v37, v50, v51
	global_store_dwordx2 v[236:237], v[4:5], off offset:3072
	v_cvt_pk_bf16_f32 v4, v16, v17
	v_cvt_pk_bf16_f32 v5, v18, v19
	v_cvt_pk_bf16_f32 v0, v0, v1
	v_cvt_pk_bf16_f32 v1, v2, v3
	global_store_dwordx2 v[230:231], v[104:105], off offset:32
	v_cvt_pk_bf16_f32 v104, v108, v109
	v_cvt_pk_bf16_f32 v105, v110, v111
	v_cvt_pk_bf16_f32 v100, v100, v101
	v_cvt_pk_bf16_f32 v101, v102, v103
	v_cvt_pk_bf16_f32 v96, v96, v97
	v_cvt_pk_bf16_f32 v97, v98, v99
	v_cvt_pk_bf16_f32 v92, v92, v93
	v_cvt_pk_bf16_f32 v93, v94, v95
	v_cvt_pk_bf16_f32 v88, v88, v89
	v_cvt_pk_bf16_f32 v89, v90, v91
	v_cvt_pk_bf16_f32 v80, v80, v81
	v_cvt_pk_bf16_f32 v81, v82, v83
	global_store_dwordx2 v[232:233], v[72:73], off offset:32
	v_cvt_pk_bf16_f32 v72, v76, v77
	v_cvt_pk_bf16_f32 v73, v78, v79
	v_cvt_pk_bf16_f32 v68, v68, v69
	v_cvt_pk_bf16_f32 v69, v70, v71
	v_cvt_pk_bf16_f32 v64, v64, v65
	v_cvt_pk_bf16_f32 v65, v66, v67
	v_cvt_pk_bf16_f32 v56, v56, v57
	v_cvt_pk_bf16_f32 v57, v58, v59
	v_cvt_pk_bf16_f32 v52, v52, v53
	v_cvt_pk_bf16_f32 v53, v54, v55
	v_cvt_pk_bf16_f32 v44, v44, v45
	v_cvt_pk_bf16_f32 v45, v46, v47
	global_store_dwordx2 v[234:235], v[36:37], off offset:32
	v_cvt_pk_bf16_f32 v36, v40, v41
	v_cvt_pk_bf16_f32 v37, v42, v43
	v_cvt_pk_bf16_f32 v32, v32, v33
	v_cvt_pk_bf16_f32 v33, v34, v35
	v_cvt_pk_bf16_f32 v28, v28, v29
	v_cvt_pk_bf16_f32 v29, v30, v31
	v_cvt_pk_bf16_f32 v24, v24, v25
	v_cvt_pk_bf16_f32 v25, v26, v27
	v_cvt_pk_bf16_f32 v20, v20, v21
	v_cvt_pk_bf16_f32 v21, v22, v23
	v_cvt_pk_bf16_f32 v12, v12, v13
	v_cvt_pk_bf16_f32 v13, v14, v15
	global_store_dwordx2 v[236:237], v[4:5], off offset:32
	v_cvt_pk_bf16_f32 v4, v8, v9
	v_cvt_pk_bf16_f32 v5, v10, v11
	global_store_dwordx2 v[236:237], v[0:1], off offset:2080
	v_cvt_pk_bf16_f32 v0, v60, v61
	v_cvt_pk_bf16_f32 v1, v62, v63
	global_store_dwordx2 v[230:231], v[124:125], off
	global_store_dwordx2 v[230:231], v[112:113], off offset:2048
	global_store_dwordx2 v[230:231], v[104:105], off offset:1056
	global_store_dwordx2 v[230:231], v[100:101], off offset:2080
	global_store_dwordx2 v[230:231], v[96:97], off offset:3104
	global_store_dwordx2 v[232:233], v[92:93], off
	global_store_dwordx2 v[232:233], v[88:89], off offset:1024
	global_store_dwordx2 v[232:233], v[80:81], off offset:2048
	global_store_dwordx2 v[232:233], v[72:73], off offset:1056
	global_store_dwordx2 v[232:233], v[68:69], off offset:2080
	global_store_dwordx2 v[232:233], v[64:65], off offset:3104
	global_store_dwordx2 v[234:235], v[56:57], off
	global_store_dwordx2 v[234:235], v[52:53], off offset:1024
	global_store_dwordx2 v[234:235], v[44:45], off offset:2048
	global_store_dwordx2 v[234:235], v[36:37], off offset:1056
	global_store_dwordx2 v[234:235], v[32:33], off offset:2080
	global_store_dwordx2 v[234:235], v[28:29], off offset:3104
	global_store_dwordx2 v[236:237], v[24:25], off
	global_store_dwordx2 v[236:237], v[20:21], off offset:1024
	global_store_dwordx2 v[236:237], v[12:13], off offset:2048
	global_store_dwordx2 v[236:237], v[4:5], off offset:1056
	global_store_dwordx2 v[236:237], v[0:1], off offset:3104
	s_branch .LBB0_194

;     ...
;     for (int u = vb; u < 256; u += nb) {
;         const int b = u >> 5, hh = (u >> 3) & 3, ksl = u & 7;
;         const int kc0 = hh * 128 + ksl * 16 + 2 * w;
;         float wa[2][16], bb[2];
; #pragma unroll
;         for (int e = 0; e < 2; ++e) { bb[e] = ba[kc0 + e];
; #pragma unroll
;             for (int jj = 0; jj < 16; ++jj) wa[e][jj] = w2[jj * 512 + kc0 + e]; }
;         f32x4 acc[2];
; #pragma unroll
;         for (int e = 0; e < 2; ++e) acc[e] = (f32x4){0.f, 0.f, 0.f, 0.f};
;         __syncthreads();
;         f32x4 a4n[4]; unsigned krawn; bf16x8 vfrn[2][2];
;         auto ldchunk = [&](int n) {
;             const int tok = b * 4096 + n * 64 + l;
; #pragma unroll
;             for (int q = 0; q < 4; ++q) a4n[q] = *(const f32x4*)(GA + (size_t)tok * 16 + 4 * q);
;             krawn = *(const unsigned*)(GK + (size_t)tok * 512 + kc0);
; #pragma unroll
;             for (int e = 0; e < 2; ++e)
; #pragma unroll
;                 for (int ks = 0; ks < 2; ++ks)
;                     vfrn[e][ks] = *(const bf16x8*)(GVT + ((size_t)(b * 1024 + hh * 256 + (2 * w + e) * 16 + (l & 15))) * 4096 + n * 64 + ks * 32 + (l >> 4) * 8);
;         };
;         ldchunk(0);
;         for (int n = 0; n < 64; ++n) {
;             const int buf = n & 1;
;             f32x4 a4[4]; bf16x8 vfr[2][2];
; #pragma unroll
;             for (int q = 0; q < 4; ++q) a4[q] = a4n[q];
;             const unsigned kraw = krawn;
; #pragma unroll
;             for (int e = 0; e < 2; ++e)
; #pragma unroll
;                 for (int ks = 0; ks < 2; ++ks) vfr[e][ks] = vfrn[e][ks];
;             if (n + 1 < 64) ldchunk(n + 1);
.LBB0_418:
	s_bfe_u32 s57, s56, 0x20003
	s_lshl_b32 s21, s56, 4
	s_and_b32 s21, s21, 0x70
	s_lshl_b32 s20, s57, 7
	s_or_b32 s20, s20, s21
	s_ashr_i32 s28, s56, 5
	v_mov_b32_e32 v220, 0xbfb8aa3b
	v_mov_b32_e32 v222, 1.0
	v_mov_b32_e32 v223, 1.0
	v_mov_b32_e32 v224, 0x3f317217
	v_mov_b32_e32 v225, 0x3f317217
	v_mov_b32_e32 v226, 0x3377d1cf
	v_mov_b32_e32 v227, 0x3377d1cf
	v_mov_b32_e32 v228, 0x3fb8aa3b
	v_mov_b32_e32 v229, 0x3fb8aa3b
	v_mov_b32_e32 v214, 0x3d800000
	v_mov_b32_e32 v215, 0x3d800000
	v_lshrrev_b32_e32 v27, 6, v249
	v_lshrrev_b32_e32 v61, 3, v160
	v_lshl_add_u32 v60, v27, 3, v61
	v_and_b32_e32 v62, 7, v160
	v_lshlrev_b32_e32 v230, 3, v160
	v_lshl_add_u32 v230, v27, 9, v230
	v_lshlrev_b32_e32 v231, 2, v62
	v_lshl_add_u32 v231, v60, 10, v231
	v_mul_u32_u24_e32 v28, 0x50, v60
	v_lshl_add_u32 v28, v62, 3, v28
	v_add_u32_e32 v28, 0x2010, v28
	v_mul_u32_u24_e32 v29, 0x50, v160
	v_add_u32_e32 v29, 0x2010, v29
	v_mul_u32_u24_e32 v30, 0x104, v62
	v_lshl_add_u32 v30, v60, 2, v30
	v_add_u32_e32 v30, 0x5010, v30
	v_mul_u32_u24_e32 v31, 0x104, v27
	v_lshl_add_u32 v31, v160, 2, v31
	v_add_u32_e32 v31, 0x5010, v31
	v_lshrrev_b32_e32 v64, 4, v160
	v_lshlrev_b32_e32 v232, 6, v72
	v_lshl_add_u32 v232, v64, 4, v232
	v_add_u32_e32 v233, 0x4000, v232
	v_lshrrev_b32_e32 v66, 2, v72
	v_lshlrev_b32_e32 v234, 10, v66
	v_and_b32_e32 v66, 3, v72
	v_lshl_add_u32 v234, v66, 5, v234
	v_lshl_add_u32 v234, v64, 3, v234
	v_add_u32_e32 v235, 0x1000, v234
	v_add_u32_e32 v65, s20, v161
	v_lshlrev_b32_e32 v65, 2, v65
	s_mov_b64 s[50:51], s[8:9]
	global_load_dwordx2 v[86:87], v65, s[50:51]
	global_load_dwordx2 v[88:89], v65, s[50:51] offset:2048
	s_add_u32 s50, s50, 0x1000
	s_addc_u32 s51, s51, 0
	global_load_dwordx2 v[90:91], v65, s[50:51]
	global_load_dwordx2 v[92:93], v65, s[50:51] offset:2048
	s_add_u32 s50, s50, 0x1000
	s_addc_u32 s51, s51, 0
	global_load_dwordx2 v[94:95], v65, s[50:51]
	global_load_dwordx2 v[96:97], v65, s[50:51] offset:2048
	s_add_u32 s50, s50, 0x1000
	s_addc_u32 s51, s51, 0
	global_load_dwordx2 v[98:99], v65, s[50:51]
	global_load_dwordx2 v[100:101], v65, s[50:51] offset:2048
	s_add_u32 s50, s50, 0x1000
	s_addc_u32 s51, s51, 0
	global_load_dwordx2 v[102:103], v65, s[50:51]
	global_load_dwordx2 v[104:105], v65, s[50:51] offset:2048
	s_add_u32 s50, s50, 0x1000
	s_addc_u32 s51, s51, 0
	global_load_dwordx2 v[106:107], v65, s[50:51]
	global_load_dwordx2 v[108:109], v65, s[50:51] offset:2048
	s_add_u32 s50, s50, 0x1000
	s_addc_u32 s51, s51, 0
	global_load_dwordx2 v[110:111], v65, s[50:51]
	global_load_dwordx2 v[112:113], v65, s[50:51] offset:2048
	s_add_u32 s50, s50, 0x1000
	s_addc_u32 s51, s51, 0
	global_load_dwordx2 v[114:115], v65, s[50:51]
	global_load_dwordx2 v[116:117], v65, s[50:51] offset:2048
	s_add_u32 s50, s50, 0x1000
	s_addc_u32 s51, s51, 0
	global_load_dwordx2 v[118:119], v65, s[18:19]
	v_readlane_b32 s26, v253, 13
	v_readlane_b32 s27, v253, 14
	v_readlane_b32 s58, v254, 26
	v_readlane_b32 s59, v254, 27
	v_readlane_b32 s34, v253, 11
	v_readlane_b32 s35, v253, 12
	v_readlane_b32 s100, v254, 28
	v_readlane_b32 s101, v254, 29
	s_lshl_b32 s52, s28, 18
	s_add_u32 s26, s26, s52
	s_addc_u32 s27, s27, 0
	s_lshl_b32 s52, s28, 22
	s_lshl_b32 s53, s20, 1
	s_add_u32 s52, s52, s53
	s_add_u32 s58, s58, s52
	s_addc_u32 s59, s59, 0
	s_lshl_b32 s52, s28, 23
	s_lshl_b32 s53, s57, 21
	s_add_u32 s52, s52, s53
	s_add_u32 s34, s34, s52
	s_addc_u32 s35, s35, 0
	s_lshl_b32 s52, s28, 8
	s_or_b32 s52, s52, s57
	s_lshl_b32 s52, s52, 16
	s_lshl_b32 s53, s21, 3
	s_add_u32 s52, s52, s53
	s_add_u32 s100, s100, s52
	s_addc_u32 s101, s101, 0
	v_mov_b32_e32 v0, 0
	v_mov_b32_e32 v1, 0
	v_mov_b32_e32 v2, 0
	v_mov_b32_e32 v3, 0
	v_mov_b32_e32 v4, 0
	v_mov_b32_e32 v5, 0
	v_mov_b32_e32 v6, 0
	v_mov_b32_e32 v7, 0
	s_barrier
	global_load_dwordx2 v[48:49], v230, s[26:27]
	global_load_dword v50, v231, s[58:59]
	s_add_u32 s26, s26, 0x1000
	s_addc_u32 s27, s27, 0
	s_add_u32 s58, s58, 0x10000
	s_addc_u32 s59, s59, 0
	global_load_dwordx2 v[52:53], v230, s[26:27]
	global_load_dword v54, v231, s[58:59]
	s_add_u32 s26, s26, 0x1000
	s_addc_u32 s27, s27, 0
	s_add_u32 s58, s58, 0x10000
	s_addc_u32 s59, s59, 0
	global_load_dwordx2 v[56:57], v230, s[26:27]
	global_load_dword v58, v231, s[58:59]
	s_add_u32 s26, s26, 0x1000
	s_addc_u32 s27, s27, 0
	s_add_u32 s58, s58, 0x10000
	s_addc_u32 s59, s59, 0
	global_load_dwordx4 v[32:35], v232, s[34:35]
	global_load_dwordx4 v[36:39], v233, s[34:35]
	global_load_dwordx4 v[40:43], v232, s[34:35] offset:1024
	global_load_dwordx4 v[44:47], v233, s[34:35] offset:1024
	s_add_u32 s34, s34, 0x8000
	s_addc_u32 s35, s35, 0
	s_waitcnt vmcnt(0)
	ds_write_b64 v28, v[48:49] offset:0
	ds_write_b32 v30, v50 offset:0
	s_waitcnt lgkmcnt(0)
	s_barrier
; DI bf16_t f2bf(float x) { return (bf16_t)(pk2(x, 0.f) & 0xffffu); }
;     ...
;         for (int n = 0; n < 64; ++n) {
;             const int buf = n & 1;
;             f32x4 a4[4]; bf16x8 vfr[2][2];
; #pragma unroll
;             for (int q = 0; q < 4; ++q) a4[q] = a4n[q];
;             const unsigned kraw = krawn;
; #pragma unroll
;             for (int e = 0; e < 2; ++e)
; #pragma unroll
;                 for (int ks = 0; ks < 2; ++ks) vfr[e][ks] = vfrn[e][ks];
;             if (n + 1 < 64) ldchunk(n + 1);
;             float cum[2];
; #pragma unroll
;             for (int e = 0; e < 2; ++e) {
;                 float z = bb[e];
; #pragma unroll
;                 for (int q = 0; q < 4; ++q) { z += a4[q].x * wa[e][4 * q] + a4[q].y * wa[e][4 * q + 1] + a4[q].z * wa[e][4 * q + 2] + a4[q].w * wa[e][4 * q + 3]; }
;                 cum[e] = (fminf(z, 0.f) - __logf(1.f + __expf(-fabsf(z)))) * (1.f / 16.f);
;             }
; #pragma unroll
;             for (int o = 1; o < 64; o <<= 1) {
;                 const float t0 = __shfl_up(cum[0], o), t1 = __shfl_up(cum[1], o);
;                 if (l >= o) { cum[0] += t0; cum[1] += t1; }
;             }
;             const float tot0 = __shfl(cum[0], 63), tot1 = __shfl(cum[1], 63);
;             kdl[(buf * 16 + 2 * w) * 64 + l] = f2bf(bf2f(kraw & 0xffffu) * __expf(tot0 - cum[0]));
;             kdl[(buf * 16 + 2 * w + 1) * 64 + l] = f2bf(bf2f(kraw >> 16) * __expf(tot1 - cum[1]));
;             if (l == 0) { decl[buf * 16 + 2 * w] = __expf(tot0); decl[buf * 16 + 2 * w + 1] = __expf(tot1); }
;             __syncthreads();
;             const f32x4 d4 = *(const f32x4*)(decl + buf * 16 + (l >> 4) * 4);
; #pragma unroll
;             for (int e = 0; e < 2; ++e) acc[e] = acc[e] * d4;
; #pragma unroll
;             for (int ks = 0; ks < 2; ++ks) {
;                 const bf16x8 af = *(const bf16x8*)(kdl + (buf * 16 + (l & 15)) * 64 + ks * 32 + (l >> 4) * 8);
; #pragma unroll
;                 for (int e = 0; e < 2; ++e) acc[e] = MFMA16(af, vfr[e][ks], acc[e]);
;             }
;             const int cidx = b * 64 + n;
; #pragma unroll
;             for (int e = 0; e < 2; ++e) {
;                 const int vv = (2 * w + e) * 16 + (l & 15);
;                 *(u32x2*)(ST + (((size_t)(cidx * 4 + hh)) * 256 + vv) * 128 + ksl * 16 + (l >> 4) * 4) = pk4(acc[e].x, acc[e].y, acc[e].z, acc[e].w);
;             }
;         }
	ds_read_b128 v[8:11], v29 offset:0
	ds_read_b128 v[12:15], v29 offset:16
	ds_read_b128 v[16:19], v29 offset:32
	ds_read_b128 v[20:23], v29 offset:48
	ds_read_b32 v24, v31 offset:0
	global_load_dwordx2 v[48:49], v230, s[26:27]
	global_load_dword v50, v231, s[58:59]
	s_add_u32 s26, s26, 0x1000
	s_addc_u32 s27, s27, 0
	s_add_u32 s58, s58, 0x10000
	s_addc_u32 s59, s59, 0
	global_load_dwordx4 v[178:181], v232, s[34:35]
	global_load_dwordx4 v[182:185], v233, s[34:35]
	global_load_dwordx4 v[186:189], v232, s[34:35] offset:1024
	global_load_dwordx4 v[190:193], v233, s[34:35] offset:1024
	s_add_u32 s34, s34, 0x8000
	s_addc_u32 s35, s35, 0
	s_waitcnt lgkmcnt(0)
	v_pk_fma_f32 v[64:65], v[8:9], v[86:87], v[118:119] op_sel:[0,0,0] op_sel_hi:[0,1,1]
	v_pk_mul_f32 v[66:67], v[16:17], v[102:103] op_sel:[0,0] op_sel_hi:[0,1]
	v_pk_fma_f32 v[64:65], v[8:9], v[88:89], v[64:65] op_sel:[1,0,0] op_sel_hi:[1,1,1]
	v_pk_fma_f32 v[66:67], v[16:17], v[104:105], v[66:67] op_sel:[1,0,0] op_sel_hi:[1,1,1]
	v_pk_fma_f32 v[64:65], v[10:11], v[90:91], v[64:65] op_sel:[0,0,0] op_sel_hi:[0,1,1]
	v_pk_fma_f32 v[66:67], v[18:19], v[106:107], v[66:67] op_sel:[0,0,0] op_sel_hi:[0,1,1]
	v_pk_fma_f32 v[64:65], v[10:11], v[92:93], v[64:65] op_sel:[1,0,0] op_sel_hi:[1,1,1]
	v_pk_fma_f32 v[66:67], v[18:19], v[108:109], v[66:67] op_sel:[1,0,0] op_sel_hi:[1,1,1]
	v_pk_fma_f32 v[64:65], v[12:13], v[94:95], v[64:65] op_sel:[0,0,0] op_sel_hi:[0,1,1]
	v_pk_fma_f32 v[66:67], v[20:21], v[110:111], v[66:67] op_sel:[0,0,0] op_sel_hi:[0,1,1]
	v_pk_fma_f32 v[64:65], v[12:13], v[96:97], v[64:65] op_sel:[1,0,0] op_sel_hi:[1,1,1]
	v_pk_fma_f32 v[66:67], v[20:21], v[112:113], v[66:67] op_sel:[1,0,0] op_sel_hi:[1,1,1]
	v_pk_fma_f32 v[64:65], v[14:15], v[98:99], v[64:65] op_sel:[0,0,0] op_sel_hi:[0,1,1]
	v_pk_fma_f32 v[66:67], v[22:23], v[114:115], v[66:67] op_sel:[0,0,0] op_sel_hi:[0,1,1]
	v_pk_fma_f32 v[64:65], v[14:15], v[100:101], v[64:65] op_sel:[1,0,0] op_sel_hi:[1,1,1]
	v_pk_fma_f32 v[66:67], v[22:23], v[116:117], v[66:67] op_sel:[1,0,0] op_sel_hi:[1,1,1]
	v_lshlrev_b32_e32 v148, 16, v24
	v_pk_add_f32 v[64:65], v[64:65], v[66:67]
	v_and_b32_e32 v149, 0xffff0000, v24
	v_mul_f32_e64 v68, |v64|, v220
	v_mul_f32_e64 v69, |v65|, v220
	v_exp_f32_e32 v68, v68
	v_exp_f32_e32 v69, v69
	v_min_f32_e32 v70, 0, v64
	v_min_f32_e32 v71, 0, v65
	v_pk_add_f32 v[68:69], v[68:69], v[222:223]
	s_nop 0
	v_log_f32_e32 v138, v68
	v_log_f32_e32 v139, v69
	s_nop 0
	v_pk_mul_f32 v[140:141], v[138:139], v[224:225]
	s_nop 0
	v_pk_fma_f32 v[142:143], v[138:139], v[224:225], v[140:141] neg_lo:[0,0,1] neg_hi:[0,0,1]
	s_nop 0
	v_pk_fma_f32 v[142:143], v[138:139], v[226:227], v[142:143]
	s_nop 0
	v_pk_fma_f32 v[142:143], v[138:139], v[224:225], v[142:143]
	s_nop 0
	v_pk_add_f32 v[144:145], v[70:71], v[142:143] neg_lo:[0,1] neg_hi:[0,1]
	s_nop 0
	v_pk_mul_f32 v[144:145], v[144:145], v[214:215]
	s_nop 1
	v_add_f32_dpp v144, v144, v144 row_shr:1 row_mask:0xf bank_mask:0xf
	v_add_f32_dpp v145, v145, v145 row_shr:1 row_mask:0xf bank_mask:0xf
	s_nop 0
	v_add_f32_dpp v144, v144, v144 row_shr:2 row_mask:0xf bank_mask:0xf
	v_add_f32_dpp v145, v145, v145 row_shr:2 row_mask:0xf bank_mask:0xf
	s_nop 0
	v_add_f32_dpp v144, v144, v144 row_shr:4 row_mask:0xf bank_mask:0xf
	v_add_f32_dpp v145, v145, v145 row_shr:4 row_mask:0xf bank_mask:0xf
	s_nop 0
	v_add_f32_dpp v144, v144, v144 row_shr:8 row_mask:0xf bank_mask:0xf
	v_add_f32_dpp v145, v145, v145 row_shr:8 row_mask:0xf bank_mask:0xf
	s_nop 0
	v_add_f32_dpp v144, v144, v144 row_bcast:15 row_mask:0xa bank_mask:0xf
	v_add_f32_dpp v145, v145, v145 row_bcast:15 row_mask:0xa bank_mask:0xf
	s_nop 0
	v_add_f32_dpp v144, v144, v144 row_bcast:31 row_mask:0xc bank_mask:0xf
	v_add_f32_dpp v145, v145, v145 row_bcast:31 row_mask:0xc bank_mask:0xf
	s_nop 0
	v_readlane_b32 s98, v144, 63
	v_readlane_b32 s99, v145, 63
	s_nop 1
	v_pk_add_f32 v[146:147], s[98:99], v[144:145] neg_lo:[0,1] neg_hi:[0,1]
	v_mul_f32_e64 v152, s98, v228
	v_mul_f32_e64 v153, s99, v228
	v_pk_mul_f32 v[146:147], v[146:147], v[228:229]
	v_exp_f32_e32 v152, v152
	v_exp_f32_e32 v153, v153
	v_exp_f32_e32 v146, v146
	v_exp_f32_e32 v147, v147
	s_nop 0
	v_pk_mul_f32 v[146:147], v[146:147], v[148:149]
	s_nop 0
	v_cvt_pk_bf16_f32 v150, v146, v147
	s_nop 0
	ds_write_b16 v172, v150 offset:0
	ds_write_b16_d16_hi v172, v150 offset:128
	s_and_saveexec_b64 s[20:21], vcc
	ds_write_b64 v163, v[152:153] offset:4096
	s_mov_b64 exec, s[20:21]
	s_waitcnt vmcnt(22)
	ds_write_b64 v28, v[52:53] offset:5120
	ds_write_b32 v30, v54 offset:2080
	s_waitcnt lgkmcnt(0)
	s_barrier
; DI bf16_t f2bf(float x) { return (bf16_t)(pk2(x, 0.f) & 0xffffu); }
;     ...
;         for (int n = 0; n < 64; ++n) {
;             const int buf = n & 1;
;             f32x4 a4[4]; bf16x8 vfr[2][2];
; #pragma unroll
;             for (int q = 0; q < 4; ++q) a4[q] = a4n[q];
;             const unsigned kraw = krawn;
; #pragma unroll
;             for (int e = 0; e < 2; ++e)
; #pragma unroll
;                 for (int ks = 0; ks < 2; ++ks) vfr[e][ks] = vfrn[e][ks];
;             if (n + 1 < 64) ldchunk(n + 1);
;             float cum[2];
; #pragma unroll
;             for (int e = 0; e < 2; ++e) {
;                 float z = bb[e];
; #pragma unroll
;                 for (int q = 0; q < 4; ++q) { z += a4[q].x * wa[e][4 * q] + a4[q].y * wa[e][4 * q + 1] + a4[q].z * wa[e][4 * q + 2] + a4[q].w * wa[e][4 * q + 3]; }
;                 cum[e] = (fminf(z, 0.f) - __logf(1.f + __expf(-fabsf(z)))) * (1.f / 16.f);
;             }
; #pragma unroll
;             for (int o = 1; o < 64; o <<= 1) {
;                 const float t0 = __shfl_up(cum[0], o), t1 = __shfl_up(cum[1], o);
;                 if (l >= o) { cum[0] += t0; cum[1] += t1; }
;             }
;             const float tot0 = __shfl(cum[0], 63), tot1 = __shfl(cum[1], 63);
;             kdl[(buf * 16 + 2 * w) * 64 + l] = f2bf(bf2f(kraw & 0xffffu) * __expf(tot0 - cum[0]));
;             kdl[(buf * 16 + 2 * w + 1) * 64 + l] = f2bf(bf2f(kraw >> 16) * __expf(tot1 - cum[1]));
;             if (l == 0) { decl[buf * 16 + 2 * w] = __expf(tot0); decl[buf * 16 + 2 * w + 1] = __expf(tot1); }
;             __syncthreads();
;             const f32x4 d4 = *(const f32x4*)(decl + buf * 16 + (l >> 4) * 4);
; #pragma unroll
;             for (int e = 0; e < 2; ++e) acc[e] = acc[e] * d4;
; #pragma unroll
;             for (int ks = 0; ks < 2; ++ks) {
;                 const bf16x8 af = *(const bf16x8*)(kdl + (buf * 16 + (l & 15)) * 64 + ks * 32 + (l >> 4) * 8);
; #pragma unroll
;                 for (int e = 0; e < 2; ++e) acc[e] = MFMA16(af, vfr[e][ks], acc[e]);
;             }
;             const int cidx = b * 64 + n;
; #pragma unroll
;             for (int e = 0; e < 2; ++e) {
;                 const int vv = (2 * w + e) * 16 + (l & 15);
;                 *(u32x2*)(ST + (((size_t)(cidx * 4 + hh)) * 256 + vv) * 128 + ksl * 16 + (l >> 4) * 4) = pk4(acc[e].x, acc[e].y, acc[e].z, acc[e].w);
;             }
;         }
	ds_read_b128 v[8:11], v29 offset:5120
	ds_read_b128 v[12:15], v29 offset:5136
	ds_read_b128 v[16:19], v29 offset:5152
	ds_read_b128 v[20:23], v29 offset:5168
	ds_read_b32 v24, v31 offset:2080
	global_load_dwordx2 v[52:53], v230, s[26:27]
	global_load_dword v54, v231, s[58:59]
	s_add_u32 s26, s26, 0x1000
	s_addc_u32 s27, s27, 0
	s_add_u32 s58, s58, 0x10000
	s_addc_u32 s59, s59, 0
	global_load_dwordx4 v[194:197], v232, s[34:35]
	global_load_dwordx4 v[198:201], v233, s[34:35]
	global_load_dwordx4 v[202:205], v232, s[34:35] offset:1024
	global_load_dwordx4 v[206:209], v233, s[34:35] offset:1024
	s_add_u32 s34, s34, 0x8000
	s_addc_u32 s35, s35, 0
	ds_read_b128 v[154:157], v75 offset:0
	ds_read_b128 v[240:243], v164 offset:4096
	ds_read_b128 v[236:239], v75 offset:64
	s_waitcnt lgkmcnt(3)
	v_pk_fma_f32 v[64:65], v[8:9], v[86:87], v[118:119] op_sel:[0,0,0] op_sel_hi:[0,1,1]
	v_pk_mul_f32 v[66:67], v[16:17], v[102:103] op_sel:[0,0] op_sel_hi:[0,1]
	v_pk_fma_f32 v[64:65], v[8:9], v[88:89], v[64:65] op_sel:[1,0,0] op_sel_hi:[1,1,1]
	v_pk_fma_f32 v[66:67], v[16:17], v[104:105], v[66:67] op_sel:[1,0,0] op_sel_hi:[1,1,1]
	v_pk_fma_f32 v[64:65], v[10:11], v[90:91], v[64:65] op_sel:[0,0,0] op_sel_hi:[0,1,1]
	v_pk_fma_f32 v[66:67], v[18:19], v[106:107], v[66:67] op_sel:[0,0,0] op_sel_hi:[0,1,1]
	v_pk_fma_f32 v[64:65], v[10:11], v[92:93], v[64:65] op_sel:[1,0,0] op_sel_hi:[1,1,1]
	v_pk_fma_f32 v[66:67], v[18:19], v[108:109], v[66:67] op_sel:[1,0,0] op_sel_hi:[1,1,1]
	v_pk_fma_f32 v[64:65], v[12:13], v[94:95], v[64:65] op_sel:[0,0,0] op_sel_hi:[0,1,1]
	v_pk_fma_f32 v[66:67], v[20:21], v[110:111], v[66:67] op_sel:[0,0,0] op_sel_hi:[0,1,1]
	v_pk_fma_f32 v[64:65], v[12:13], v[96:97], v[64:65] op_sel:[1,0,0] op_sel_hi:[1,1,1]
	v_pk_fma_f32 v[66:67], v[20:21], v[112:113], v[66:67] op_sel:[1,0,0] op_sel_hi:[1,1,1]
	v_pk_fma_f32 v[64:65], v[14:15], v[98:99], v[64:65] op_sel:[0,0,0] op_sel_hi:[0,1,1]
	v_pk_fma_f32 v[66:67], v[22:23], v[114:115], v[66:67] op_sel:[0,0,0] op_sel_hi:[0,1,1]
	v_pk_fma_f32 v[64:65], v[14:15], v[100:101], v[64:65] op_sel:[1,0,0] op_sel_hi:[1,1,1]
	v_pk_fma_f32 v[66:67], v[22:23], v[116:117], v[66:67] op_sel:[1,0,0] op_sel_hi:[1,1,1]
	v_lshlrev_b32_e32 v148, 16, v24
	v_pk_add_f32 v[64:65], v[64:65], v[66:67]
	v_and_b32_e32 v149, 0xffff0000, v24
	s_waitcnt lgkmcnt(0)
	v_pk_mul_f32 v[0:1], v[0:1], v[240:241]
	v_pk_mul_f32 v[2:3], v[2:3], v[242:243]
	v_pk_mul_f32 v[4:5], v[4:5], v[240:241]
	v_pk_mul_f32 v[6:7], v[6:7], v[242:243]
	s_waitcnt vmcnt(16)
	s_nop 0
	v_mfma_f32_16x16x32_bf16 v[0:3], v[154:157], v[32:35], v[0:3]
	v_mfma_f32_16x16x32_bf16 v[4:7], v[154:157], v[40:43], v[4:7]
	v_mfma_f32_16x16x32_bf16 v[0:3], v[236:239], v[36:39], v[0:3]
	v_mfma_f32_16x16x32_bf16 v[4:7], v[236:239], v[44:47], v[4:7]
	v_mul_f32_e64 v68, |v64|, v220
	v_mul_f32_e64 v69, |v65|, v220
	v_exp_f32_e32 v68, v68
	v_exp_f32_e32 v69, v69
	v_min_f32_e32 v70, 0, v64
	v_min_f32_e32 v71, 0, v65
	v_pk_add_f32 v[68:69], v[68:69], v[222:223]
	s_nop 0
	v_log_f32_e32 v138, v68
	v_log_f32_e32 v139, v69
	s_nop 0
	v_pk_mul_f32 v[140:141], v[138:139], v[224:225]
	s_nop 0
	v_pk_fma_f32 v[142:143], v[138:139], v[224:225], v[140:141] neg_lo:[0,0,1] neg_hi:[0,0,1]
	s_nop 0
	v_pk_fma_f32 v[142:143], v[138:139], v[226:227], v[142:143]
	s_nop 0
	v_pk_fma_f32 v[142:143], v[138:139], v[224:225], v[142:143]
	s_nop 0
	v_pk_add_f32 v[144:145], v[70:71], v[142:143] neg_lo:[0,1] neg_hi:[0,1]
	s_nop 0
	v_pk_mul_f32 v[144:145], v[144:145], v[214:215]
	v_cvt_pk_bf16_f32 v244, v0, v1
	v_cvt_pk_bf16_f32 v245, v2, v3
	v_cvt_pk_bf16_f32 v246, v4, v5
	v_cvt_pk_bf16_f32 v247, v6, v7
	global_store_dwordx2 v234, v[244:245], s[100:101]
	global_store_dwordx2 v235, v[246:247], s[100:101]
	s_add_u32 s100, s100, 0x40000
	s_addc_u32 s101, s101, 0
	v_add_f32_dpp v144, v144, v144 row_shr:1 row_mask:0xf bank_mask:0xf
	v_add_f32_dpp v145, v145, v145 row_shr:1 row_mask:0xf bank_mask:0xf
	s_nop 0
	v_add_f32_dpp v144, v144, v144 row_shr:2 row_mask:0xf bank_mask:0xf
	v_add_f32_dpp v145, v145, v145 row_shr:2 row_mask:0xf bank_mask:0xf
	s_nop 0
	v_add_f32_dpp v144, v144, v144 row_shr:4 row_mask:0xf bank_mask:0xf
	v_add_f32_dpp v145, v145, v145 row_shr:4 row_mask:0xf bank_mask:0xf
	s_nop 0
	v_add_f32_dpp v144, v144, v144 row_shr:8 row_mask:0xf bank_mask:0xf
	v_add_f32_dpp v145, v145, v145 row_shr:8 row_mask:0xf bank_mask:0xf
	s_nop 0
	v_add_f32_dpp v144, v144, v144 row_bcast:15 row_mask:0xa bank_mask:0xf
	v_add_f32_dpp v145, v145, v145 row_bcast:15 row_mask:0xa bank_mask:0xf
	s_nop 0
	v_add_f32_dpp v144, v144, v144 row_bcast:31 row_mask:0xc bank_mask:0xf
	v_add_f32_dpp v145, v145, v145 row_bcast:31 row_mask:0xc bank_mask:0xf
	s_nop 0
	v_readlane_b32 s98, v144, 63
	v_readlane_b32 s99, v145, 63
	s_nop 1
	v_pk_add_f32 v[146:147], s[98:99], v[144:145] neg_lo:[0,1] neg_hi:[0,1]
	v_mul_f32_e64 v152, s98, v228
	v_mul_f32_e64 v153, s99, v228
	v_pk_mul_f32 v[146:147], v[146:147], v[228:229]
	v_exp_f32_e32 v152, v152
	v_exp_f32_e32 v153, v153
	v_exp_f32_e32 v146, v146
	v_exp_f32_e32 v147, v147
	s_nop 0
	v_pk_mul_f32 v[146:147], v[146:147], v[148:149]
	s_nop 0
	v_cvt_pk_bf16_f32 v150, v146, v147
	s_nop 0
	ds_write_b16 v172, v150 offset:2048
	ds_write_b16_d16_hi v172, v150 offset:2176
	s_and_saveexec_b64 s[20:21], vcc
	ds_write_b64 v163, v[152:153] offset:4160
	s_mov_b64 exec, s[20:21]
	s_waitcnt vmcnt(22)
	ds_write_b64 v28, v[56:57] offset:0
	ds_write_b32 v30, v58 offset:0
	s_waitcnt lgkmcnt(0)
	s_barrier
; DI bf16_t f2bf(float x) { return (bf16_t)(pk2(x, 0.f) & 0xffffu); }
;     ...
;         for (int n = 0; n < 64; ++n) {
;             const int buf = n & 1;
;             f32x4 a4[4]; bf16x8 vfr[2][2];
; #pragma unroll
;             for (int q = 0; q < 4; ++q) a4[q] = a4n[q];
;             const unsigned kraw = krawn;
; #pragma unroll
;             for (int e = 0; e < 2; ++e)
; #pragma unroll
;                 for (int ks = 0; ks < 2; ++ks) vfr[e][ks] = vfrn[e][ks];
;             if (n + 1 < 64) ldchunk(n + 1);
;             float cum[2];
; #pragma unroll
;             for (int e = 0; e < 2; ++e) {
;                 float z = bb[e];
; #pragma unroll
;                 for (int q = 0; q < 4; ++q) { z += a4[q].x * wa[e][4 * q] + a4[q].y * wa[e][4 * q + 1] + a4[q].z * wa[e][4 * q + 2] + a4[q].w * wa[e][4 * q + 3]; }
;                 cum[e] = (fminf(z, 0.f) - __logf(1.f + __expf(-fabsf(z)))) * (1.f / 16.f);
;             }
; #pragma unroll
;             for (int o = 1; o < 64; o <<= 1) {
;                 const float t0 = __shfl_up(cum[0], o), t1 = __shfl_up(cum[1], o);
;                 if (l >= o) { cum[0] += t0; cum[1] += t1; }
;             }
;             const float tot0 = __shfl(cum[0], 63), tot1 = __shfl(cum[1], 63);
;             kdl[(buf * 16 + 2 * w) * 64 + l] = f2bf(bf2f(kraw & 0xffffu) * __expf(tot0 - cum[0]));
;             kdl[(buf * 16 + 2 * w + 1) * 64 + l] = f2bf(bf2f(kraw >> 16) * __expf(tot1 - cum[1]));
;             if (l == 0) { decl[buf * 16 + 2 * w] = __expf(tot0); decl[buf * 16 + 2 * w + 1] = __expf(tot1); }
;             __syncthreads();
;             const f32x4 d4 = *(const f32x4*)(decl + buf * 16 + (l >> 4) * 4);
; #pragma unroll
;             for (int e = 0; e < 2; ++e) acc[e] = acc[e] * d4;
; #pragma unroll
;             for (int ks = 0; ks < 2; ++ks) {
;                 const bf16x8 af = *(const bf16x8*)(kdl + (buf * 16 + (l & 15)) * 64 + ks * 32 + (l >> 4) * 8);
; #pragma unroll
;                 for (int e = 0; e < 2; ++e) acc[e] = MFMA16(af, vfr[e][ks], acc[e]);
;             }
;             const int cidx = b * 64 + n;
; #pragma unroll
;             for (int e = 0; e < 2; ++e) {
;                 const int vv = (2 * w + e) * 16 + (l & 15);
;                 *(u32x2*)(ST + (((size_t)(cidx * 4 + hh)) * 256 + vv) * 128 + ksl * 16 + (l >> 4) * 4) = pk4(acc[e].x, acc[e].y, acc[e].z, acc[e].w);
;             }
;         }
	ds_read_b128 v[8:11], v29 offset:0
	ds_read_b128 v[12:15], v29 offset:16
	ds_read_b128 v[16:19], v29 offset:32
	ds_read_b128 v[20:23], v29 offset:48
	ds_read_b32 v24, v31 offset:0
	global_load_dwordx2 v[56:57], v230, s[26:27]
	global_load_dword v58, v231, s[58:59]
	s_add_u32 s26, s26, 0x1000
	s_addc_u32 s27, s27, 0
	s_add_u32 s58, s58, 0x10000
	s_addc_u32 s59, s59, 0
	global_load_dwordx4 v[32:35], v232, s[34:35]
	global_load_dwordx4 v[36:39], v233, s[34:35]
	global_load_dwordx4 v[40:43], v232, s[34:35] offset:1024
	global_load_dwordx4 v[44:47], v233, s[34:35] offset:1024
	s_add_u32 s34, s34, 0x8000
	s_addc_u32 s35, s35, 0
	ds_read_b128 v[154:157], v75 offset:2048
	ds_read_b128 v[240:243], v164 offset:4160
	ds_read_b128 v[236:239], v75 offset:2112
	s_waitcnt lgkmcnt(3)
	v_pk_fma_f32 v[64:65], v[8:9], v[86:87], v[118:119] op_sel:[0,0,0] op_sel_hi:[0,1,1]
	v_pk_mul_f32 v[66:67], v[16:17], v[102:103] op_sel:[0,0] op_sel_hi:[0,1]
	v_pk_fma_f32 v[64:65], v[8:9], v[88:89], v[64:65] op_sel:[1,0,0] op_sel_hi:[1,1,1]
	v_pk_fma_f32 v[66:67], v[16:17], v[104:105], v[66:67] op_sel:[1,0,0] op_sel_hi:[1,1,1]
	v_pk_fma_f32 v[64:65], v[10:11], v[90:91], v[64:65] op_sel:[0,0,0] op_sel_hi:[0,1,1]
	v_pk_fma_f32 v[66:67], v[18:19], v[106:107], v[66:67] op_sel:[0,0,0] op_sel_hi:[0,1,1]
	v_pk_fma_f32 v[64:65], v[10:11], v[92:93], v[64:65] op_sel:[1,0,0] op_sel_hi:[1,1,1]
	v_pk_fma_f32 v[66:67], v[18:19], v[108:109], v[66:67] op_sel:[1,0,0] op_sel_hi:[1,1,1]
	v_pk_fma_f32 v[64:65], v[12:13], v[94:95], v[64:65] op_sel:[0,0,0] op_sel_hi:[0,1,1]
	v_pk_fma_f32 v[66:67], v[20:21], v[110:111], v[66:67] op_sel:[0,0,0] op_sel_hi:[0,1,1]
	v_pk_fma_f32 v[64:65], v[12:13], v[96:97], v[64:65] op_sel:[1,0,0] op_sel_hi:[1,1,1]
	v_pk_fma_f32 v[66:67], v[20:21], v[112:113], v[66:67] op_sel:[1,0,0] op_sel_hi:[1,1,1]
	v_pk_fma_f32 v[64:65], v[14:15], v[98:99], v[64:65] op_sel:[0,0,0] op_sel_hi:[0,1,1]
	v_pk_fma_f32 v[66:67], v[22:23], v[114:115], v[66:67] op_sel:[0,0,0] op_sel_hi:[0,1,1]
	v_pk_fma_f32 v[64:65], v[14:15], v[100:101], v[64:65] op_sel:[1,0,0] op_sel_hi:[1,1,1]
	v_pk_fma_f32 v[66:67], v[22:23], v[116:117], v[66:67] op_sel:[1,0,0] op_sel_hi:[1,1,1]
	v_lshlrev_b32_e32 v148, 16, v24
	v_pk_add_f32 v[64:65], v[64:65], v[66:67]
	v_and_b32_e32 v149, 0xffff0000, v24
	s_waitcnt lgkmcnt(0)
	v_pk_mul_f32 v[0:1], v[0:1], v[240:241]
	v_pk_mul_f32 v[2:3], v[2:3], v[242:243]
	v_pk_mul_f32 v[4:5], v[4:5], v[240:241]
	v_pk_mul_f32 v[6:7], v[6:7], v[242:243]
	s_waitcnt vmcnt(14)
	s_nop 0
	v_mfma_f32_16x16x32_bf16 v[0:3], v[154:157], v[178:181], v[0:3]
	v_mfma_f32_16x16x32_bf16 v[4:7], v[154:157], v[186:189], v[4:7]
	v_mfma_f32_16x16x32_bf16 v[0:3], v[236:239], v[182:185], v[0:3]
	v_mfma_f32_16x16x32_bf16 v[4:7], v[236:239], v[190:193], v[4:7]
	v_mul_f32_e64 v68, |v64|, v220
	v_mul_f32_e64 v69, |v65|, v220
	v_exp_f32_e32 v68, v68
	v_exp_f32_e32 v69, v69
	v_min_f32_e32 v70, 0, v64
	v_min_f32_e32 v71, 0, v65
	v_pk_add_f32 v[68:69], v[68:69], v[222:223]
	s_nop 0
	v_log_f32_e32 v138, v68
	v_log_f32_e32 v139, v69
	s_nop 0
	v_pk_mul_f32 v[140:141], v[138:139], v[224:225]
	s_nop 0
	v_pk_fma_f32 v[142:143], v[138:139], v[224:225], v[140:141] neg_lo:[0,0,1] neg_hi:[0,0,1]
	s_nop 0
	v_pk_fma_f32 v[142:143], v[138:139], v[226:227], v[142:143]
	s_nop 0
	v_pk_fma_f32 v[142:143], v[138:139], v[224:225], v[142:143]
	s_nop 0
	v_pk_add_f32 v[144:145], v[70:71], v[142:143] neg_lo:[0,1] neg_hi:[0,1]
	s_nop 0
	v_pk_mul_f32 v[144:145], v[144:145], v[214:215]
	v_cvt_pk_bf16_f32 v244, v0, v1
	v_cvt_pk_bf16_f32 v245, v2, v3
	v_cvt_pk_bf16_f32 v246, v4, v5
	v_cvt_pk_bf16_f32 v247, v6, v7
	global_store_dwordx2 v234, v[244:245], s[100:101]
	global_store_dwordx2 v235, v[246:247], s[100:101]
	s_add_u32 s100, s100, 0x40000
	s_addc_u32 s101, s101, 0
	v_add_f32_dpp v144, v144, v144 row_shr:1 row_mask:0xf bank_mask:0xf
	v_add_f32_dpp v145, v145, v145 row_shr:1 row_mask:0xf bank_mask:0xf
	s_nop 0
	v_add_f32_dpp v144, v144, v144 row_shr:2 row_mask:0xf bank_mask:0xf
	v_add_f32_dpp v145, v145, v145 row_shr:2 row_mask:0xf bank_mask:0xf
	s_nop 0
	v_add_f32_dpp v144, v144, v144 row_shr:4 row_mask:0xf bank_mask:0xf
	v_add_f32_dpp v145, v145, v145 row_shr:4 row_mask:0xf bank_mask:0xf
	s_nop 0
	v_add_f32_dpp v144, v144, v144 row_shr:8 row_mask:0xf bank_mask:0xf
	v_add_f32_dpp v145, v145, v145 row_shr:8 row_mask:0xf bank_mask:0xf
	s_nop 0
	v_add_f32_dpp v144, v144, v144 row_bcast:15 row_mask:0xa bank_mask:0xf
	v_add_f32_dpp v145, v145, v145 row_bcast:15 row_mask:0xa bank_mask:0xf
	s_nop 0
	v_add_f32_dpp v144, v144, v144 row_bcast:31 row_mask:0xc bank_mask:0xf
	v_add_f32_dpp v145, v145, v145 row_bcast:31 row_mask:0xc bank_mask:0xf
	s_nop 0
	v_readlane_b32 s98, v144, 63
	v_readlane_b32 s99, v145, 63
	s_nop 1
	v_pk_add_f32 v[146:147], s[98:99], v[144:145] neg_lo:[0,1] neg_hi:[0,1]
	v_mul_f32_e64 v152, s98, v228
	v_mul_f32_e64 v153, s99, v228
	v_pk_mul_f32 v[146:147], v[146:147], v[228:229]
	v_exp_f32_e32 v152, v152
	v_exp_f32_e32 v153, v153
	v_exp_f32_e32 v146, v146
	v_exp_f32_e32 v147, v147
	s_nop 0
	v_pk_mul_f32 v[146:147], v[146:147], v[148:149]
	s_nop 0
	v_cvt_pk_bf16_f32 v150, v146, v147
	s_nop 0
	ds_write_b16 v172, v150 offset:0
	ds_write_b16_d16_hi v172, v150 offset:128
	s_and_saveexec_b64 s[20:21], vcc
	ds_write_b64 v163, v[152:153] offset:4096
	s_mov_b64 exec, s[20:21]
	s_waitcnt vmcnt(20)
	ds_write_b64 v28, v[48:49] offset:5120
	ds_write_b32 v30, v50 offset:2080
	s_waitcnt lgkmcnt(0)
	s_barrier
; DI float bf2f(unsigned x) { return __uint_as_float(x << 16); }
;     ...
;         auto ldchunk = [&](int n) {
;             const int tok = b * 4096 + n * 64 + l;
; #pragma unroll
;             for (int q = 0; q < 4; ++q) a4n[q] = *(const f32x4*)(GA + (size_t)tok * 16 + 4 * q);
;             krawn = *(const unsigned*)(GK + (size_t)tok * 512 + kc0);
; #pragma unroll
;             for (int e = 0; e < 2; ++e)
; #pragma unroll
;                 for (int ks = 0; ks < 2; ++ks)
;                     vfrn[e][ks] = *(const bf16x8*)(GVT + ((size_t)(b * 1024 + hh * 256 + (2 * w + e) * 16 + (l & 15))) * 4096 + n * 64 + ks * 32 + (l >> 4) * 8);
;         };
;         ldchunk(0);
;         for (int n = 0; n < 64; ++n) {
;             const int buf = n & 1;
;             f32x4 a4[4]; bf16x8 vfr[2][2];
; #pragma unroll
;             for (int q = 0; q < 4; ++q) a4[q] = a4n[q];
;             const unsigned kraw = krawn;
; #pragma unroll
;             for (int e = 0; e < 2; ++e)
; #pragma unroll
;                 for (int ks = 0; ks < 2; ++ks) vfr[e][ks] = vfrn[e][ks];
;             if (n + 1 < 64) ldchunk(n + 1);
;             float cum[2];
; #pragma unroll
;             for (int e = 0; e < 2; ++e) {
;                 float z = bb[e];
; #pragma unroll
;                 for (int q = 0; q < 4; ++q) { z += a4[q].x * wa[e][4 * q] + a4[q].y * wa[e][4 * q + 1] + a4[q].z * wa[e][4 * q + 2] + a4[q].w * wa[e][4 * q + 3]; }
;                 cum[e] = (fminf(z, 0.f) - __logf(1.f + __expf(-fabsf(z)))) * (1.f / 16.f);
;             }
; #pragma unroll
;             for (int o = 1; o < 64; o <<= 1) {
;                 const float t0 = __shfl_up(cum[0], o), t1 = __shfl_up(cum[1], o);
;                 if (l >= o) { cum[0] += t0; cum[1] += t1; }
;             }
;             const float tot0 = __shfl(cum[0], 63), tot1 = __shfl(cum[1], 63);
;             kdl[(buf * 16 + 2 * w) * 64 + l] = f2bf(bf2f(kraw & 0xffffu) * __expf(tot0 - cum[0]));
;             kdl[(buf * 16 + 2 * w + 1) * 64 + l] = f2bf(bf2f(kraw >> 16) * __expf(tot1 - cum[1]));
;             if (l == 0) { decl[buf * 16 + 2 * w] = __expf(tot0); decl[buf * 16 + 2 * w + 1] = __expf(tot1); }
;             __syncthreads();
;             const f32x4 d4 = *(const f32x4*)(decl + buf * 16 + (l >> 4) * 4);
; #pragma unroll
;             for (int e = 0; e < 2; ++e) acc[e] = acc[e] * d4;
; #pragma unroll
;             for (int ks = 0; ks < 2; ++ks) {
	ds_read_b128 v[8:11], v29 offset:5120
	ds_read_b128 v[12:15], v29 offset:5136
	ds_read_b128 v[16:19], v29 offset:5152
	ds_read_b128 v[20:23], v29 offset:5168
	ds_read_b32 v24, v31 offset:2080
	global_load_dwordx2 v[48:49], v230, s[26:27]
	global_load_dword v50, v231, s[58:59]
	s_add_u32 s26, s26, 0x1000
	s_addc_u32 s27, s27, 0
	s_add_u32 s58, s58, 0x10000
	s_addc_u32 s59, s59, 0
	global_load_dwordx4 v[178:181], v232, s[34:35]
	global_load_dwordx4 v[182:185], v233, s[34:35]
	global_load_dwordx4 v[186:189], v232, s[34:35] offset:1024
	global_load_dwordx4 v[190:193], v233, s[34:35] offset:1024
	s_add_u32 s34, s34, 0x8000
	s_addc_u32 s35, s35, 0
	ds_read_b128 v[154:157], v75 offset:0
	ds_read_b128 v[240:243], v164 offset:4096
	ds_read_b128 v[236:239], v75 offset:64
	s_waitcnt lgkmcnt(3)
	v_pk_fma_f32 v[64:65], v[8:9], v[86:87], v[118:119] op_sel:[0,0,0] op_sel_hi:[0,1,1]
	v_pk_mul_f32 v[66:67], v[16:17], v[102:103] op_sel:[0,0] op_sel_hi:[0,1]
	v_pk_fma_f32 v[64:65], v[8:9], v[88:89], v[64:65] op_sel:[1,0,0] op_sel_hi:[1,1,1]
	v_pk_fma_f32 v[66:67], v[16:17], v[104:105], v[66:67] op_sel:[1,0,0] op_sel_hi:[1,1,1]
	v_pk_fma_f32 v[64:65], v[10:11], v[90:91], v[64:65] op_sel:[0,0,0] op_sel_hi:[0,1,1]
	v_pk_fma_f32 v[66:67], v[18:19], v[106:107], v[66:67] op_sel:[0,0,0] op_sel_hi:[0,1,1]
	v_pk_fma_f32 v[64:65], v[10:11], v[92:93], v[64:65] op_sel:[1,0,0] op_sel_hi:[1,1,1]
	v_pk_fma_f32 v[66:67], v[18:19], v[108:109], v[66:67] op_sel:[1,0,0] op_sel_hi:[1,1,1]
	v_pk_fma_f32 v[64:65], v[12:13], v[94:95], v[64:65] op_sel:[0,0,0] op_sel_hi:[0,1,1]
	v_pk_fma_f32 v[66:67], v[20:21], v[110:111], v[66:67] op_sel:[0,0,0] op_sel_hi:[0,1,1]
	v_pk_fma_f32 v[64:65], v[12:13], v[96:97], v[64:65] op_sel:[1,0,0] op_sel_hi:[1,1,1]
	v_pk_fma_f32 v[66:67], v[20:21], v[112:113], v[66:67] op_sel:[1,0,0] op_sel_hi:[1,1,1]
	v_pk_fma_f32 v[64:65], v[14:15], v[98:99], v[64:65] op_sel:[0,0,0] op_sel_hi:[0,1,1]
	v_pk_fma_f32 v[66:67], v[22:23], v[114:115], v[66:67] op_sel:[0,0,0] op_sel_hi:[0,1,1]
	v_pk_fma_f32 v[64:65], v[14:15], v[100:101], v[64:65] op_sel:[1,0,0] op_sel_hi:[1,1,1]
	v_pk_fma_f32 v[66:67], v[22:23], v[116:117], v[66:67] op_sel:[1,0,0] op_sel_hi:[1,1,1]
	v_lshlrev_b32_e32 v148, 16, v24
	v_pk_add_f32 v[64:65], v[64:65], v[66:67]
	v_and_b32_e32 v149, 0xffff0000, v24
	s_waitcnt lgkmcnt(0)
	v_pk_mul_f32 v[0:1], v[0:1], v[240:241]
	v_pk_mul_f32 v[2:3], v[2:3], v[242:243]
	v_pk_mul_f32 v[4:5], v[4:5], v[240:241]
	v_pk_mul_f32 v[6:7], v[6:7], v[242:243]
	s_waitcnt vmcnt(16)
	s_nop 0
	v_mfma_f32_16x16x32_bf16 v[0:3], v[154:157], v[194:197], v[0:3]
	v_mfma_f32_16x16x32_bf16 v[4:7], v[154:157], v[202:205], v[4:7]
	v_mfma_f32_16x16x32_bf16 v[0:3], v[236:239], v[198:201], v[0:3]
	v_mfma_f32_16x16x32_bf16 v[4:7], v[236:239], v[206:209], v[4:7]
	v_mul_f32_e64 v68, |v64|, v220
	v_mul_f32_e64 v69, |v65|, v220
	v_exp_f32_e32 v68, v68
	v_exp_f32_e32 v69, v69
	v_min_f32_e32 v70, 0, v64
	v_min_f32_e32 v71, 0, v65
	v_pk_add_f32 v[68:69], v[68:69], v[222:223]
	s_nop 0
	v_log_f32_e32 v138, v68
	v_log_f32_e32 v139, v69
	s_nop 0
	v_pk_mul_f32 v[140:141], v[138:139], v[224:225]
	s_nop 0
	v_pk_fma_f32 v[142:143], v[138:139], v[224:225], v[140:141] neg_lo:[0,0,1] neg_hi:[0,0,1]
	s_nop 0
	v_pk_fma_f32 v[142:143], v[138:139], v[226:227], v[142:143]
	s_nop 0
	v_pk_fma_f32 v[142:143], v[138:139], v[224:225], v[142:143]
	s_nop 0
	v_pk_add_f32 v[144:145], v[70:71], v[142:143] neg_lo:[0,1] neg_hi:[0,1]
	s_nop 0
	v_pk_mul_f32 v[144:145], v[144:145], v[214:215]
	v_cvt_pk_bf16_f32 v244, v0, v1
	v_cvt_pk_bf16_f32 v245, v2, v3
	v_cvt_pk_bf16_f32 v246, v4, v5
	v_cvt_pk_bf16_f32 v247, v6, v7
	global_store_dwordx2 v234, v[244:245], s[100:101]
	global_store_dwordx2 v235, v[246:247], s[100:101]
	s_add_u32 s100, s100, 0x40000
	s_addc_u32 s101, s101, 0
	v_add_f32_dpp v144, v144, v144 row_shr:1 row_mask:0xf bank_mask:0xf
	v_add_f32_dpp v145, v145, v145 row_shr:1 row_mask:0xf bank_mask:0xf
	s_nop 0
	v_add_f32_dpp v144, v144, v144 row_shr:2 row_mask:0xf bank_mask:0xf
	v_add_f32_dpp v145, v145, v145 row_shr:2 row_mask:0xf bank_mask:0xf
	s_nop 0
	v_add_f32_dpp v144, v144, v144 row_shr:4 row_mask:0xf bank_mask:0xf
	v_add_f32_dpp v145, v145, v145 row_shr:4 row_mask:0xf bank_mask:0xf
	s_nop 0
	v_add_f32_dpp v144, v144, v144 row_shr:8 row_mask:0xf bank_mask:0xf
	v_add_f32_dpp v145, v145, v145 row_shr:8 row_mask:0xf bank_mask:0xf
	s_nop 0
	v_add_f32_dpp v144, v144, v144 row_bcast:15 row_mask:0xa bank_mask:0xf
	v_add_f32_dpp v145, v145, v145 row_bcast:15 row_mask:0xa bank_mask:0xf
	s_nop 0
	v_add_f32_dpp v144, v144, v144 row_bcast:31 row_mask:0xc bank_mask:0xf
	v_add_f32_dpp v145, v145, v145 row_bcast:31 row_mask:0xc bank_mask:0xf
	s_nop 0
	v_readlane_b32 s98, v144, 63
	v_readlane_b32 s99, v145, 63
	s_nop 1
	v_pk_add_f32 v[146:147], s[98:99], v[144:145] neg_lo:[0,1] neg_hi:[0,1]
	v_mul_f32_e64 v152, s98, v228
	v_mul_f32_e64 v153, s99, v228
	v_pk_mul_f32 v[146:147], v[146:147], v[228:229]
	v_exp_f32_e32 v152, v152
	v_exp_f32_e32 v153, v153
	v_exp_f32_e32 v146, v146
	v_exp_f32_e32 v147, v147
	s_nop 0
	v_pk_mul_f32 v[146:147], v[146:147], v[148:149]
	s_nop 0
	v_cvt_pk_bf16_f32 v150, v146, v147
	s_nop 0
	ds_write_b16 v172, v150 offset:2048
	ds_write_b16_d16_hi v172, v150 offset:2176
	s_and_saveexec_b64 s[20:21], vcc
	ds_write_b64 v163, v[152:153] offset:4160
	s_mov_b64 exec, s[20:21]
	s_waitcnt vmcnt(22)
	ds_write_b64 v28, v[52:53] offset:0
	ds_write_b32 v30, v54 offset:0
	s_waitcnt lgkmcnt(0)
	s_barrier
; DI float bf2f(unsigned x) { return __uint_as_float(x << 16); }
;     ...
;         auto ldchunk = [&](int n) {
;             const int tok = b * 4096 + n * 64 + l;
; #pragma unroll
;             for (int q = 0; q < 4; ++q) a4n[q] = *(const f32x4*)(GA + (size_t)tok * 16 + 4 * q);
;             krawn = *(const unsigned*)(GK + (size_t)tok * 512 + kc0);
; #pragma unroll
;             for (int e = 0; e < 2; ++e)
; #pragma unroll
;                 for (int ks = 0; ks < 2; ++ks)
;                     vfrn[e][ks] = *(const bf16x8*)(GVT + ((size_t)(b * 1024 + hh * 256 + (2 * w + e) * 16 + (l & 15))) * 4096 + n * 64 + ks * 32 + (l >> 4) * 8);
;         };
;         ldchunk(0);
;         for (int n = 0; n < 64; ++n) {
;             const int buf = n & 1;
;             f32x4 a4[4]; bf16x8 vfr[2][2];
; #pragma unroll
;             for (int q = 0; q < 4; ++q) a4[q] = a4n[q];
;             const unsigned kraw = krawn;
; #pragma unroll
;             for (int e = 0; e < 2; ++e)
; #pragma unroll
;                 for (int ks = 0; ks < 2; ++ks) vfr[e][ks] = vfrn[e][ks];
;             if (n + 1 < 64) ldchunk(n + 1);
;             float cum[2];
; #pragma unroll
;             for (int e = 0; e < 2; ++e) {
;                 float z = bb[e];
; #pragma unroll
;                 for (int q = 0; q < 4; ++q) { z += a4[q].x * wa[e][4 * q] + a4[q].y * wa[e][4 * q + 1] + a4[q].z * wa[e][4 * q + 2] + a4[q].w * wa[e][4 * q + 3]; }
;                 cum[e] = (fminf(z, 0.f) - __logf(1.f + __expf(-fabsf(z)))) * (1.f / 16.f);
;             }
; #pragma unroll
;             for (int o = 1; o < 64; o <<= 1) {
;                 const float t0 = __shfl_up(cum[0], o), t1 = __shfl_up(cum[1], o);
;                 if (l >= o) { cum[0] += t0; cum[1] += t1; }
;             }
;             const float tot0 = __shfl(cum[0], 63), tot1 = __shfl(cum[1], 63);
;             kdl[(buf * 16 + 2 * w) * 64 + l] = f2bf(bf2f(kraw & 0xffffu) * __expf(tot0 - cum[0]));
;             kdl[(buf * 16 + 2 * w + 1) * 64 + l] = f2bf(bf2f(kraw >> 16) * __expf(tot1 - cum[1]));
;             if (l == 0) { decl[buf * 16 + 2 * w] = __expf(tot0); decl[buf * 16 + 2 * w + 1] = __expf(tot1); }
;             __syncthreads();
;             const f32x4 d4 = *(const f32x4*)(decl + buf * 16 + (l >> 4) * 4);
; #pragma unroll
;             for (int e = 0; e < 2; ++e) acc[e] = acc[e] * d4;
; #pragma unroll
;             for (int ks = 0; ks < 2; ++ks) {
	ds_read_b128 v[8:11], v29 offset:0
	ds_read_b128 v[12:15], v29 offset:16
	ds_read_b128 v[16:19], v29 offset:32
	ds_read_b128 v[20:23], v29 offset:48
	ds_read_b32 v24, v31 offset:0
	global_load_dwordx2 v[52:53], v230, s[26:27]
	global_load_dword v54, v231, s[58:59]
	s_add_u32 s26, s26, 0x1000
	s_addc_u32 s27, s27, 0
	s_add_u32 s58, s58, 0x10000
	s_addc_u32 s59, s59, 0
	global_load_dwordx4 v[194:197], v232, s[34:35]
	global_load_dwordx4 v[198:201], v233, s[34:35]
	global_load_dwordx4 v[202:205], v232, s[34:35] offset:1024
	global_load_dwordx4 v[206:209], v233, s[34:35] offset:1024
	s_add_u32 s34, s34, 0x8000
	s_addc_u32 s35, s35, 0
	ds_read_b128 v[154:157], v75 offset:2048
	ds_read_b128 v[240:243], v164 offset:4160
	ds_read_b128 v[236:239], v75 offset:2112
	s_waitcnt lgkmcnt(3)
	v_pk_fma_f32 v[64:65], v[8:9], v[86:87], v[118:119] op_sel:[0,0,0] op_sel_hi:[0,1,1]
	v_pk_mul_f32 v[66:67], v[16:17], v[102:103] op_sel:[0,0] op_sel_hi:[0,1]
	v_pk_fma_f32 v[64:65], v[8:9], v[88:89], v[64:65] op_sel:[1,0,0] op_sel_hi:[1,1,1]
	v_pk_fma_f32 v[66:67], v[16:17], v[104:105], v[66:67] op_sel:[1,0,0] op_sel_hi:[1,1,1]
	v_pk_fma_f32 v[64:65], v[10:11], v[90:91], v[64:65] op_sel:[0,0,0] op_sel_hi:[0,1,1]
	v_pk_fma_f32 v[66:67], v[18:19], v[106:107], v[66:67] op_sel:[0,0,0] op_sel_hi:[0,1,1]
	v_pk_fma_f32 v[64:65], v[10:11], v[92:93], v[64:65] op_sel:[1,0,0] op_sel_hi:[1,1,1]
	v_pk_fma_f32 v[66:67], v[18:19], v[108:109], v[66:67] op_sel:[1,0,0] op_sel_hi:[1,1,1]
	v_pk_fma_f32 v[64:65], v[12:13], v[94:95], v[64:65] op_sel:[0,0,0] op_sel_hi:[0,1,1]
	v_pk_fma_f32 v[66:67], v[20:21], v[110:111], v[66:67] op_sel:[0,0,0] op_sel_hi:[0,1,1]
	v_pk_fma_f32 v[64:65], v[12:13], v[96:97], v[64:65] op_sel:[1,0,0] op_sel_hi:[1,1,1]
	v_pk_fma_f32 v[66:67], v[20:21], v[112:113], v[66:67] op_sel:[1,0,0] op_sel_hi:[1,1,1]
	v_pk_fma_f32 v[64:65], v[14:15], v[98:99], v[64:65] op_sel:[0,0,0] op_sel_hi:[0,1,1]
	v_pk_fma_f32 v[66:67], v[22:23], v[114:115], v[66:67] op_sel:[0,0,0] op_sel_hi:[0,1,1]
	v_pk_fma_f32 v[64:65], v[14:15], v[100:101], v[64:65] op_sel:[1,0,0] op_sel_hi:[1,1,1]
	v_pk_fma_f32 v[66:67], v[22:23], v[116:117], v[66:67] op_sel:[1,0,0] op_sel_hi:[1,1,1]
	v_lshlrev_b32_e32 v148, 16, v24
	v_pk_add_f32 v[64:65], v[64:65], v[66:67]
	v_and_b32_e32 v149, 0xffff0000, v24
	s_waitcnt lgkmcnt(0)
	v_pk_mul_f32 v[0:1], v[0:1], v[240:241]
	v_pk_mul_f32 v[2:3], v[2:3], v[242:243]
	v_pk_mul_f32 v[4:5], v[4:5], v[240:241]
	v_pk_mul_f32 v[6:7], v[6:7], v[242:243]
	s_waitcnt vmcnt(16)
	s_nop 0
	v_mfma_f32_16x16x32_bf16 v[0:3], v[154:157], v[32:35], v[0:3]
	v_mfma_f32_16x16x32_bf16 v[4:7], v[154:157], v[40:43], v[4:7]
	v_mfma_f32_16x16x32_bf16 v[0:3], v[236:239], v[36:39], v[0:3]
	v_mfma_f32_16x16x32_bf16 v[4:7], v[236:239], v[44:47], v[4:7]
	v_mul_f32_e64 v68, |v64|, v220
	v_mul_f32_e64 v69, |v65|, v220
	v_exp_f32_e32 v68, v68
	v_exp_f32_e32 v69, v69
	v_min_f32_e32 v70, 0, v64
	v_min_f32_e32 v71, 0, v65
	v_pk_add_f32 v[68:69], v[68:69], v[222:223]
	s_nop 0
	v_log_f32_e32 v138, v68
	v_log_f32_e32 v139, v69
	s_nop 0
	v_pk_mul_f32 v[140:141], v[138:139], v[224:225]
	s_nop 0
	v_pk_fma_f32 v[142:143], v[138:139], v[224:225], v[140:141] neg_lo:[0,0,1] neg_hi:[0,0,1]
	s_nop 0
	v_pk_fma_f32 v[142:143], v[138:139], v[226:227], v[142:143]
	s_nop 0
	v_pk_fma_f32 v[142:143], v[138:139], v[224:225], v[142:143]
	s_nop 0
	v_pk_add_f32 v[144:145], v[70:71], v[142:143] neg_lo:[0,1] neg_hi:[0,1]
	s_nop 0
	v_pk_mul_f32 v[144:145], v[144:145], v[214:215]
	v_cvt_pk_bf16_f32 v244, v0, v1
	v_cvt_pk_bf16_f32 v245, v2, v3
	v_cvt_pk_bf16_f32 v246, v4, v5
	v_cvt_pk_bf16_f32 v247, v6, v7
	global_store_dwordx2 v234, v[244:245], s[100:101]
	global_store_dwordx2 v235, v[246:247], s[100:101]
	s_add_u32 s100, s100, 0x40000
	s_addc_u32 s101, s101, 0
	v_add_f32_dpp v144, v144, v144 row_shr:1 row_mask:0xf bank_mask:0xf
	v_add_f32_dpp v145, v145, v145 row_shr:1 row_mask:0xf bank_mask:0xf
	s_nop 0
	v_add_f32_dpp v144, v144, v144 row_shr:2 row_mask:0xf bank_mask:0xf
	v_add_f32_dpp v145, v145, v145 row_shr:2 row_mask:0xf bank_mask:0xf
	s_nop 0
	v_add_f32_dpp v144, v144, v144 row_shr:4 row_mask:0xf bank_mask:0xf
	v_add_f32_dpp v145, v145, v145 row_shr:4 row_mask:0xf bank_mask:0xf
	s_nop 0
	v_add_f32_dpp v144, v144, v144 row_shr:8 row_mask:0xf bank_mask:0xf
	v_add_f32_dpp v145, v145, v145 row_shr:8 row_mask:0xf bank_mask:0xf
	s_nop 0
	v_add_f32_dpp v144, v144, v144 row_bcast:15 row_mask:0xa bank_mask:0xf
	v_add_f32_dpp v145, v145, v145 row_bcast:15 row_mask:0xa bank_mask:0xf
	s_nop 0
	v_add_f32_dpp v144, v144, v144 row_bcast:31 row_mask:0xc bank_mask:0xf
	v_add_f32_dpp v145, v145, v145 row_bcast:31 row_mask:0xc bank_mask:0xf
	s_nop 0
	v_readlane_b32 s98, v144, 63
	v_readlane_b32 s99, v145, 63
	s_nop 1
	v_pk_add_f32 v[146:147], s[98:99], v[144:145] neg_lo:[0,1] neg_hi:[0,1]
	v_mul_f32_e64 v152, s98, v228
	v_mul_f32_e64 v153, s99, v228
	v_pk_mul_f32 v[146:147], v[146:147], v[228:229]
	v_exp_f32_e32 v152, v152
	v_exp_f32_e32 v153, v153
	v_exp_f32_e32 v146, v146
	v_exp_f32_e32 v147, v147
	s_nop 0
	v_pk_mul_f32 v[146:147], v[146:147], v[148:149]
	s_nop 0
	v_cvt_pk_bf16_f32 v150, v146, v147
	s_nop 0
	ds_write_b16 v172, v150 offset:0
	ds_write_b16_d16_hi v172, v150 offset:128
	s_and_saveexec_b64 s[20:21], vcc
	ds_write_b64 v163, v[152:153] offset:4096
	s_mov_b64 exec, s[20:21]
	s_waitcnt vmcnt(22)
	ds_write_b64 v28, v[56:57] offset:5120
	ds_write_b32 v30, v58 offset:2080
	s_waitcnt lgkmcnt(0)
	s_barrier
; DI float bf2f(unsigned x) { return __uint_as_float(x << 16); }
;     ...
;         auto ldchunk = [&](int n) {
;             const int tok = b * 4096 + n * 64 + l;
; #pragma unroll
;             for (int q = 0; q < 4; ++q) a4n[q] = *(const f32x4*)(GA + (size_t)tok * 16 + 4 * q);
;             krawn = *(const unsigned*)(GK + (size_t)tok * 512 + kc0);
; #pragma unroll
;             for (int e = 0; e < 2; ++e)
; #pragma unroll
;                 for (int ks = 0; ks < 2; ++ks)
;                     vfrn[e][ks] = *(const bf16x8*)(GVT + ((size_t)(b * 1024 + hh * 256 + (2 * w + e) * 16 + (l & 15))) * 4096 + n * 64 + ks * 32 + (l >> 4) * 8);
;         };
;         ldchunk(0);
;         for (int n = 0; n < 64; ++n) {
;             const int buf = n & 1;
;             f32x4 a4[4]; bf16x8 vfr[2][2];
; #pragma unroll
;             for (int q = 0; q < 4; ++q) a4[q] = a4n[q];
;             const unsigned kraw = krawn;
; #pragma unroll
;             for (int e = 0; e < 2; ++e)
; #pragma unroll
;                 for (int ks = 0; ks < 2; ++ks) vfr[e][ks] = vfrn[e][ks];
;             if (n + 1 < 64) ldchunk(n + 1);
;             float cum[2];
; #pragma unroll
;             for (int e = 0; e < 2; ++e) {
;                 float z = bb[e];
; #pragma unroll
;                 for (int q = 0; q < 4; ++q) { z += a4[q].x * wa[e][4 * q] + a4[q].y * wa[e][4 * q + 1] + a4[q].z * wa[e][4 * q + 2] + a4[q].w * wa[e][4 * q + 3]; }
;                 cum[e] = (fminf(z, 0.f) - __logf(1.f + __expf(-fabsf(z)))) * (1.f / 16.f);
;             }
; #pragma unroll
;             for (int o = 1; o < 64; o <<= 1) {
;                 const float t0 = __shfl_up(cum[0], o), t1 = __shfl_up(cum[1], o);
;                 if (l >= o) { cum[0] += t0; cum[1] += t1; }
;             }
;             const float tot0 = __shfl(cum[0], 63), tot1 = __shfl(cum[1], 63);
;             kdl[(buf * 16 + 2 * w) * 64 + l] = f2bf(bf2f(kraw & 0xffffu) * __expf(tot0 - cum[0]));
;             kdl[(buf * 16 + 2 * w + 1) * 64 + l] = f2bf(bf2f(kraw >> 16) * __expf(tot1 - cum[1]));
;             if (l == 0) { decl[buf * 16 + 2 * w] = __expf(tot0); decl[buf * 16 + 2 * w + 1] = __expf(tot1); }
;             __syncthreads();
;             const f32x4 d4 = *(const f32x4*)(decl + buf * 16 + (l >> 4) * 4);
; #pragma unroll
;             for (int e = 0; e < 2; ++e) acc[e] = acc[e] * d4;
; #pragma unroll
;             for (int ks = 0; ks < 2; ++ks) {
	ds_read_b128 v[8:11], v29 offset:5120
	ds_read_b128 v[12:15], v29 offset:5136
	ds_read_b128 v[16:19], v29 offset:5152
	ds_read_b128 v[20:23], v29 offset:5168
	ds_read_b32 v24, v31 offset:2080
	global_load_dwordx2 v[56:57], v230, s[26:27]
	global_load_dword v58, v231, s[58:59]
	s_add_u32 s26, s26, 0x1000
	s_addc_u32 s27, s27, 0
	s_add_u32 s58, s58, 0x10000
	s_addc_u32 s59, s59, 0
	global_load_dwordx4 v[32:35], v232, s[34:35]
	global_load_dwordx4 v[36:39], v233, s[34:35]
	global_load_dwordx4 v[40:43], v232, s[34:35] offset:1024
	global_load_dwordx4 v[44:47], v233, s[34:35] offset:1024
	s_add_u32 s34, s34, 0x8000
	s_addc_u32 s35, s35, 0
	ds_read_b128 v[154:157], v75 offset:0
	ds_read_b128 v[240:243], v164 offset:4096
	ds_read_b128 v[236:239], v75 offset:64
	s_waitcnt lgkmcnt(3)
	v_pk_fma_f32 v[64:65], v[8:9], v[86:87], v[118:119] op_sel:[0,0,0] op_sel_hi:[0,1,1]
	v_pk_mul_f32 v[66:67], v[16:17], v[102:103] op_sel:[0,0] op_sel_hi:[0,1]
	v_pk_fma_f32 v[64:65], v[8:9], v[88:89], v[64:65] op_sel:[1,0,0] op_sel_hi:[1,1,1]
	v_pk_fma_f32 v[66:67], v[16:17], v[104:105], v[66:67] op_sel:[1,0,0] op_sel_hi:[1,1,1]
	v_pk_fma_f32 v[64:65], v[10:11], v[90:91], v[64:65] op_sel:[0,0,0] op_sel_hi:[0,1,1]
	v_pk_fma_f32 v[66:67], v[18:19], v[106:107], v[66:67] op_sel:[0,0,0] op_sel_hi:[0,1,1]
	v_pk_fma_f32 v[64:65], v[10:11], v[92:93], v[64:65] op_sel:[1,0,0] op_sel_hi:[1,1,1]
	v_pk_fma_f32 v[66:67], v[18:19], v[108:109], v[66:67] op_sel:[1,0,0] op_sel_hi:[1,1,1]
	v_pk_fma_f32 v[64:65], v[12:13], v[94:95], v[64:65] op_sel:[0,0,0] op_sel_hi:[0,1,1]
	v_pk_fma_f32 v[66:67], v[20:21], v[110:111], v[66:67] op_sel:[0,0,0] op_sel_hi:[0,1,1]
	v_pk_fma_f32 v[64:65], v[12:13], v[96:97], v[64:65] op_sel:[1,0,0] op_sel_hi:[1,1,1]
	v_pk_fma_f32 v[66:67], v[20:21], v[112:113], v[66:67] op_sel:[1,0,0] op_sel_hi:[1,1,1]
	v_pk_fma_f32 v[64:65], v[14:15], v[98:99], v[64:65] op_sel:[0,0,0] op_sel_hi:[0,1,1]
	v_pk_fma_f32 v[66:67], v[22:23], v[114:115], v[66:67] op_sel:[0,0,0] op_sel_hi:[0,1,1]
	v_pk_fma_f32 v[64:65], v[14:15], v[100:101], v[64:65] op_sel:[1,0,0] op_sel_hi:[1,1,1]
	v_pk_fma_f32 v[66:67], v[22:23], v[116:117], v[66:67] op_sel:[1,0,0] op_sel_hi:[1,1,1]
	v_lshlrev_b32_e32 v148, 16, v24
	v_pk_add_f32 v[64:65], v[64:65], v[66:67]
	v_and_b32_e32 v149, 0xffff0000, v24
	s_waitcnt lgkmcnt(0)
	v_pk_mul_f32 v[0:1], v[0:1], v[240:241]
	v_pk_mul_f32 v[2:3], v[2:3], v[242:243]
	v_pk_mul_f32 v[4:5], v[4:5], v[240:241]
	v_pk_mul_f32 v[6:7], v[6:7], v[242:243]
	s_waitcnt vmcnt(16)
	s_nop 0
	v_mfma_f32_16x16x32_bf16 v[0:3], v[154:157], v[178:181], v[0:3]
	v_mfma_f32_16x16x32_bf16 v[4:7], v[154:157], v[186:189], v[4:7]
	v_mfma_f32_16x16x32_bf16 v[0:3], v[236:239], v[182:185], v[0:3]
	v_mfma_f32_16x16x32_bf16 v[4:7], v[236:239], v[190:193], v[4:7]
	v_mul_f32_e64 v68, |v64|, v220
	v_mul_f32_e64 v69, |v65|, v220
	v_exp_f32_e32 v68, v68
	v_exp_f32_e32 v69, v69
	v_min_f32_e32 v70, 0, v64
	v_min_f32_e32 v71, 0, v65
	v_pk_add_f32 v[68:69], v[68:69], v[222:223]
	s_nop 0
	v_log_f32_e32 v138, v68
	v_log_f32_e32 v139, v69
	s_nop 0
	v_pk_mul_f32 v[140:141], v[138:139], v[224:225]
	s_nop 0
	v_pk_fma_f32 v[142:143], v[138:139], v[224:225], v[140:141] neg_lo:[0,0,1] neg_hi:[0,0,1]
	s_nop 0
	v_pk_fma_f32 v[142:143], v[138:139], v[226:227], v[142:143]
	s_nop 0
	v_pk_fma_f32 v[142:143], v[138:139], v[224:225], v[142:143]
	s_nop 0
	v_pk_add_f32 v[144:145], v[70:71], v[142:143] neg_lo:[0,1] neg_hi:[0,1]
	s_nop 0
	v_pk_mul_f32 v[144:145], v[144:145], v[214:215]
	v_cvt_pk_bf16_f32 v244, v0, v1
	v_cvt_pk_bf16_f32 v245, v2, v3
	v_cvt_pk_bf16_f32 v246, v4, v5
	v_cvt_pk_bf16_f32 v247, v6, v7
	global_store_dwordx2 v234, v[244:245], s[100:101]
	global_store_dwordx2 v235, v[246:247], s[100:101]
	s_add_u32 s100, s100, 0x40000
	s_addc_u32 s101, s101, 0
	v_add_f32_dpp v144, v144, v144 row_shr:1 row_mask:0xf bank_mask:0xf
	v_add_f32_dpp v145, v145, v145 row_shr:1 row_mask:0xf bank_mask:0xf
	s_nop 0
	v_add_f32_dpp v144, v144, v144 row_shr:2 row_mask:0xf bank_mask:0xf
	v_add_f32_dpp v145, v145, v145 row_shr:2 row_mask:0xf bank_mask:0xf
	s_nop 0
	v_add_f32_dpp v144, v144, v144 row_shr:4 row_mask:0xf bank_mask:0xf
	v_add_f32_dpp v145, v145, v145 row_shr:4 row_mask:0xf bank_mask:0xf
	s_nop 0
	v_add_f32_dpp v144, v144, v144 row_shr:8 row_mask:0xf bank_mask:0xf
	v_add_f32_dpp v145, v145, v145 row_shr:8 row_mask:0xf bank_mask:0xf
	s_nop 0
	v_add_f32_dpp v144, v144, v144 row_bcast:15 row_mask:0xa bank_mask:0xf
	v_add_f32_dpp v145, v145, v145 row_bcast:15 row_mask:0xa bank_mask:0xf
	s_nop 0
	v_add_f32_dpp v144, v144, v144 row_bcast:31 row_mask:0xc bank_mask:0xf
	v_add_f32_dpp v145, v145, v145 row_bcast:31 row_mask:0xc bank_mask:0xf
	s_nop 0
	v_readlane_b32 s98, v144, 63
	v_readlane_b32 s99, v145, 63
	s_nop 1
	v_pk_add_f32 v[146:147], s[98:99], v[144:145] neg_lo:[0,1] neg_hi:[0,1]
	v_mul_f32_e64 v152, s98, v228
	v_mul_f32_e64 v153, s99, v228
	v_pk_mul_f32 v[146:147], v[146:147], v[228:229]
	v_exp_f32_e32 v152, v152
	v_exp_f32_e32 v153, v153
	v_exp_f32_e32 v146, v146
	v_exp_f32_e32 v147, v147
	s_nop 0
	v_pk_mul_f32 v[146:147], v[146:147], v[148:149]
	s_nop 0
	v_cvt_pk_bf16_f32 v150, v146, v147
	s_nop 0
	ds_write_b16 v172, v150 offset:2048
	ds_write_b16_d16_hi v172, v150 offset:2176
	s_and_saveexec_b64 s[20:21], vcc
	ds_write_b64 v163, v[152:153] offset:4160
	s_mov_b64 exec, s[20:21]
	s_waitcnt vmcnt(22)
	ds_write_b64 v28, v[48:49] offset:0
	ds_write_b32 v30, v50 offset:0
	s_waitcnt lgkmcnt(0)
	s_barrier
	ds_read_b128 v[8:11], v29 offset:0
	ds_read_b128 v[12:15], v29 offset:16
	ds_read_b128 v[16:19], v29 offset:32
	ds_read_b128 v[20:23], v29 offset:48
	ds_read_b32 v24, v31 offset:0
	s_mov_b32 s28, 9
; DI float bf2f(unsigned x) { return __uint_as_float(x << 16); }
;     ...
;         auto ldchunk = [&](int n) {
;             const int tok = b * 4096 + n * 64 + l;
; #pragma unroll
;             for (int q = 0; q < 4; ++q) a4n[q] = *(const f32x4*)(GA + (size_t)tok * 16 + 4 * q);
;             krawn = *(const unsigned*)(GK + (size_t)tok * 512 + kc0);
; #pragma unroll
;             for (int e = 0; e < 2; ++e)
; #pragma unroll
;                 for (int ks = 0; ks < 2; ++ks)
;                     vfrn[e][ks] = *(const bf16x8*)(GVT + ((size_t)(b * 1024 + hh * 256 + (2 * w + e) * 16 + (l & 15))) * 4096 + n * 64 + ks * 32 + (l >> 4) * 8);
;         };
;         ldchunk(0);
;         for (int n = 0; n < 64; ++n) {
;             const int buf = n & 1;
;             f32x4 a4[4]; bf16x8 vfr[2][2];
; #pragma unroll
;             for (int q = 0; q < 4; ++q) a4[q] = a4n[q];
;             const unsigned kraw = krawn;
; #pragma unroll
;             for (int e = 0; e < 2; ++e)
; #pragma unroll
;                 for (int ks = 0; ks < 2; ++ks) vfr[e][ks] = vfrn[e][ks];
;             if (n + 1 < 64) ldchunk(n + 1);
;             float cum[2];
; #pragma unroll
;             for (int e = 0; e < 2; ++e) {
;                 float z = bb[e];
; #pragma unroll
;                 for (int q = 0; q < 4; ++q) { z += a4[q].x * wa[e][4 * q] + a4[q].y * wa[e][4 * q + 1] + a4[q].z * wa[e][4 * q + 2] + a4[q].w * wa[e][4 * q + 3]; }
;                 cum[e] = (fminf(z, 0.f) - __logf(1.f + __expf(-fabsf(z)))) * (1.f / 16.f);
;             }
; #pragma unroll
;             for (int o = 1; o < 64; o <<= 1) {
;                 const float t0 = __shfl_up(cum[0], o), t1 = __shfl_up(cum[1], o);
;                 if (l >= o) { cum[0] += t0; cum[1] += t1; }
;             }
;             const float tot0 = __shfl(cum[0], 63), tot1 = __shfl(cum[1], 63);
;             kdl[(buf * 16 + 2 * w) * 64 + l] = f2bf(bf2f(kraw & 0xffffu) * __expf(tot0 - cum[0]));
;             kdl[(buf * 16 + 2 * w + 1) * 64 + l] = f2bf(bf2f(kraw >> 16) * __expf(tot1 - cum[1]));
;             if (l == 0) { decl[buf * 16 + 2 * w] = __expf(tot0); decl[buf * 16 + 2 * w + 1] = __expf(tot1); }
;             __syncthreads();
;             const f32x4 d4 = *(const f32x4*)(decl + buf * 16 + (l >> 4) * 4);
; #pragma unroll
;             for (int e = 0; e < 2; ++e) acc[e] = acc[e] * d4;
; #pragma unroll
;             for (int ks = 0; ks < 2; ++ks) {
.Lgscan_loop:
	global_load_dwordx2 v[48:49], v230, s[26:27]
	global_load_dword v50, v231, s[58:59]
	s_add_u32 s26, s26, 0x1000
	s_addc_u32 s27, s27, 0
	s_add_u32 s58, s58, 0x10000
	s_addc_u32 s59, s59, 0
	global_load_dwordx4 v[178:181], v232, s[34:35]
	global_load_dwordx4 v[182:185], v233, s[34:35]
	global_load_dwordx4 v[186:189], v232, s[34:35] offset:1024
	global_load_dwordx4 v[190:193], v233, s[34:35] offset:1024
	s_add_u32 s34, s34, 0x8000
	s_addc_u32 s35, s35, 0
	ds_read_b128 v[154:157], v75 offset:2048
	ds_read_b128 v[240:243], v164 offset:4160
	ds_read_b128 v[236:239], v75 offset:2112
	s_waitcnt lgkmcnt(3)
	v_pk_fma_f32 v[64:65], v[8:9], v[86:87], v[118:119] op_sel:[0,0,0] op_sel_hi:[0,1,1]
	v_pk_mul_f32 v[66:67], v[16:17], v[102:103] op_sel:[0,0] op_sel_hi:[0,1]
	v_pk_fma_f32 v[64:65], v[8:9], v[88:89], v[64:65] op_sel:[1,0,0] op_sel_hi:[1,1,1]
	v_pk_fma_f32 v[66:67], v[16:17], v[104:105], v[66:67] op_sel:[1,0,0] op_sel_hi:[1,1,1]
	v_pk_fma_f32 v[64:65], v[10:11], v[90:91], v[64:65] op_sel:[0,0,0] op_sel_hi:[0,1,1]
	v_pk_fma_f32 v[66:67], v[18:19], v[106:107], v[66:67] op_sel:[0,0,0] op_sel_hi:[0,1,1]
	v_pk_fma_f32 v[64:65], v[10:11], v[92:93], v[64:65] op_sel:[1,0,0] op_sel_hi:[1,1,1]
	v_pk_fma_f32 v[66:67], v[18:19], v[108:109], v[66:67] op_sel:[1,0,0] op_sel_hi:[1,1,1]
	v_pk_fma_f32 v[64:65], v[12:13], v[94:95], v[64:65] op_sel:[0,0,0] op_sel_hi:[0,1,1]
	v_pk_fma_f32 v[66:67], v[20:21], v[110:111], v[66:67] op_sel:[0,0,0] op_sel_hi:[0,1,1]
	v_pk_fma_f32 v[64:65], v[12:13], v[96:97], v[64:65] op_sel:[1,0,0] op_sel_hi:[1,1,1]
	v_pk_fma_f32 v[66:67], v[20:21], v[112:113], v[66:67] op_sel:[1,0,0] op_sel_hi:[1,1,1]
	v_pk_fma_f32 v[64:65], v[14:15], v[98:99], v[64:65] op_sel:[0,0,0] op_sel_hi:[0,1,1]
	v_pk_fma_f32 v[66:67], v[22:23], v[114:115], v[66:67] op_sel:[0,0,0] op_sel_hi:[0,1,1]
	v_pk_fma_f32 v[64:65], v[14:15], v[100:101], v[64:65] op_sel:[1,0,0] op_sel_hi:[1,1,1]
	v_pk_fma_f32 v[66:67], v[22:23], v[116:117], v[66:67] op_sel:[1,0,0] op_sel_hi:[1,1,1]
	v_lshlrev_b32_e32 v148, 16, v24
	v_pk_add_f32 v[64:65], v[64:65], v[66:67]
	v_and_b32_e32 v149, 0xffff0000, v24
	s_waitcnt lgkmcnt(0)
	v_pk_mul_f32 v[0:1], v[0:1], v[240:241]
	v_pk_mul_f32 v[2:3], v[2:3], v[242:243]
	v_pk_mul_f32 v[4:5], v[4:5], v[240:241]
	v_pk_mul_f32 v[6:7], v[6:7], v[242:243]
	s_waitcnt vmcnt(16)
	s_nop 0
	v_mfma_f32_16x16x32_bf16 v[0:3], v[154:157], v[194:197], v[0:3]
	v_mfma_f32_16x16x32_bf16 v[4:7], v[154:157], v[202:205], v[4:7]
	v_mfma_f32_16x16x32_bf16 v[0:3], v[236:239], v[198:201], v[0:3]
	v_mfma_f32_16x16x32_bf16 v[4:7], v[236:239], v[206:209], v[4:7]
	v_mul_f32_e64 v68, |v64|, v220
	v_mul_f32_e64 v69, |v65|, v220
	v_exp_f32_e32 v68, v68
	v_exp_f32_e32 v69, v69
	v_min_f32_e32 v70, 0, v64
	v_min_f32_e32 v71, 0, v65
	v_pk_add_f32 v[68:69], v[68:69], v[222:223]
	s_nop 0
	v_log_f32_e32 v138, v68
	v_log_f32_e32 v139, v69
	s_nop 0
	v_pk_mul_f32 v[140:141], v[138:139], v[224:225]
	s_nop 0
	v_pk_fma_f32 v[142:143], v[138:139], v[224:225], v[140:141] neg_lo:[0,0,1] neg_hi:[0,0,1]
	s_nop 0
	v_pk_fma_f32 v[142:143], v[138:139], v[226:227], v[142:143]
	s_nop 0
	v_pk_fma_f32 v[142:143], v[138:139], v[224:225], v[142:143]
	s_nop 0
	v_pk_add_f32 v[144:145], v[70:71], v[142:143] neg_lo:[0,1] neg_hi:[0,1]
	s_nop 0
	v_pk_mul_f32 v[144:145], v[144:145], v[214:215]
	v_cvt_pk_bf16_f32 v244, v0, v1
	v_cvt_pk_bf16_f32 v245, v2, v3
	v_cvt_pk_bf16_f32 v246, v4, v5
	v_cvt_pk_bf16_f32 v247, v6, v7
	global_store_dwordx2 v234, v[244:245], s[100:101]
	global_store_dwordx2 v235, v[246:247], s[100:101]
	s_add_u32 s100, s100, 0x40000
	s_addc_u32 s101, s101, 0
	v_add_f32_dpp v144, v144, v144 row_shr:1 row_mask:0xf bank_mask:0xf
	v_add_f32_dpp v145, v145, v145 row_shr:1 row_mask:0xf bank_mask:0xf
	s_nop 0
	v_add_f32_dpp v144, v144, v144 row_shr:2 row_mask:0xf bank_mask:0xf
	v_add_f32_dpp v145, v145, v145 row_shr:2 row_mask:0xf bank_mask:0xf
	s_nop 0
	v_add_f32_dpp v144, v144, v144 row_shr:4 row_mask:0xf bank_mask:0xf
	v_add_f32_dpp v145, v145, v145 row_shr:4 row_mask:0xf bank_mask:0xf
	s_nop 0
	v_add_f32_dpp v144, v144, v144 row_shr:8 row_mask:0xf bank_mask:0xf
	v_add_f32_dpp v145, v145, v145 row_shr:8 row_mask:0xf bank_mask:0xf
	s_nop 0
	v_add_f32_dpp v144, v144, v144 row_bcast:15 row_mask:0xa bank_mask:0xf
	v_add_f32_dpp v145, v145, v145 row_bcast:15 row_mask:0xa bank_mask:0xf
	s_nop 0
	v_add_f32_dpp v144, v144, v144 row_bcast:31 row_mask:0xc bank_mask:0xf
	v_add_f32_dpp v145, v145, v145 row_bcast:31 row_mask:0xc bank_mask:0xf
	s_nop 0
	v_readlane_b32 s98, v144, 63
	v_readlane_b32 s99, v145, 63
	s_nop 1
	v_pk_add_f32 v[146:147], s[98:99], v[144:145] neg_lo:[0,1] neg_hi:[0,1]
	v_mul_f32_e64 v152, s98, v228
	v_mul_f32_e64 v153, s99, v228
	v_pk_mul_f32 v[146:147], v[146:147], v[228:229]
	v_exp_f32_e32 v152, v152
	v_exp_f32_e32 v153, v153
	v_exp_f32_e32 v146, v146
	v_exp_f32_e32 v147, v147
	s_nop 0
	v_pk_mul_f32 v[146:147], v[146:147], v[148:149]
	s_nop 0
	v_cvt_pk_bf16_f32 v150, v146, v147
	s_nop 0
	ds_write_b16 v172, v150 offset:0
	ds_write_b16_d16_hi v172, v150 offset:128
	s_and_saveexec_b64 s[20:21], vcc
	ds_write_b64 v163, v[152:153] offset:4096
	s_mov_b64 exec, s[20:21]
	s_waitcnt vmcnt(22)
	ds_write_b64 v28, v[52:53] offset:5120
	ds_write_b32 v30, v54 offset:2080
	s_waitcnt lgkmcnt(0)
	s_barrier
; DI float bf2f(unsigned x) { return __uint_as_float(x << 16); }
;     ...
;         auto ldchunk = [&](int n) {
;             const int tok = b * 4096 + n * 64 + l;
; #pragma unroll
;             for (int q = 0; q < 4; ++q) a4n[q] = *(const f32x4*)(GA + (size_t)tok * 16 + 4 * q);
;             krawn = *(const unsigned*)(GK + (size_t)tok * 512 + kc0);
; #pragma unroll
;             for (int e = 0; e < 2; ++e)
; #pragma unroll
;                 for (int ks = 0; ks < 2; ++ks)
;                     vfrn[e][ks] = *(const bf16x8*)(GVT + ((size_t)(b * 1024 + hh * 256 + (2 * w + e) * 16 + (l & 15))) * 4096 + n * 64 + ks * 32 + (l >> 4) * 8);
;         };
;         ldchunk(0);
;         for (int n = 0; n < 64; ++n) {
;             const int buf = n & 1;
;             f32x4 a4[4]; bf16x8 vfr[2][2];
; #pragma unroll
;             for (int q = 0; q < 4; ++q) a4[q] = a4n[q];
;             const unsigned kraw = krawn;
; #pragma unroll
;             for (int e = 0; e < 2; ++e)
; #pragma unroll
;                 for (int ks = 0; ks < 2; ++ks) vfr[e][ks] = vfrn[e][ks];
;             if (n + 1 < 64) ldchunk(n + 1);
;             float cum[2];
; #pragma unroll
;             for (int e = 0; e < 2; ++e) {
;                 float z = bb[e];
; #pragma unroll
;                 for (int q = 0; q < 4; ++q) { z += a4[q].x * wa[e][4 * q] + a4[q].y * wa[e][4 * q + 1] + a4[q].z * wa[e][4 * q + 2] + a4[q].w * wa[e][4 * q + 3]; }
;                 cum[e] = (fminf(z, 0.f) - __logf(1.f + __expf(-fabsf(z)))) * (1.f / 16.f);
;             }
; #pragma unroll
;             for (int o = 1; o < 64; o <<= 1) {
;                 const float t0 = __shfl_up(cum[0], o), t1 = __shfl_up(cum[1], o);
;                 if (l >= o) { cum[0] += t0; cum[1] += t1; }
;             }
;             const float tot0 = __shfl(cum[0], 63), tot1 = __shfl(cum[1], 63);
;             kdl[(buf * 16 + 2 * w) * 64 + l] = f2bf(bf2f(kraw & 0xffffu) * __expf(tot0 - cum[0]));
;             kdl[(buf * 16 + 2 * w + 1) * 64 + l] = f2bf(bf2f(kraw >> 16) * __expf(tot1 - cum[1]));
;             if (l == 0) { decl[buf * 16 + 2 * w] = __expf(tot0); decl[buf * 16 + 2 * w + 1] = __expf(tot1); }
;             __syncthreads();
;             const f32x4 d4 = *(const f32x4*)(decl + buf * 16 + (l >> 4) * 4);
; #pragma unroll
;             for (int e = 0; e < 2; ++e) acc[e] = acc[e] * d4;
; #pragma unroll
;             for (int ks = 0; ks < 2; ++ks) {
	ds_read_b128 v[8:11], v29 offset:5120
	ds_read_b128 v[12:15], v29 offset:5136
	ds_read_b128 v[16:19], v29 offset:5152
	ds_read_b128 v[20:23], v29 offset:5168
	ds_read_b32 v24, v31 offset:2080
	global_load_dwordx2 v[52:53], v230, s[26:27]
	global_load_dword v54, v231, s[58:59]
	s_add_u32 s26, s26, 0x1000
	s_addc_u32 s27, s27, 0
	s_add_u32 s58, s58, 0x10000
	s_addc_u32 s59, s59, 0
	global_load_dwordx4 v[194:197], v232, s[34:35]
	global_load_dwordx4 v[198:201], v233, s[34:35]
	global_load_dwordx4 v[202:205], v232, s[34:35] offset:1024
	global_load_dwordx4 v[206:209], v233, s[34:35] offset:1024
	s_add_u32 s34, s34, 0x8000
	s_addc_u32 s35, s35, 0
	ds_read_b128 v[154:157], v75 offset:0
	ds_read_b128 v[240:243], v164 offset:4096
	ds_read_b128 v[236:239], v75 offset:64
	s_waitcnt lgkmcnt(3)
	v_pk_fma_f32 v[64:65], v[8:9], v[86:87], v[118:119] op_sel:[0,0,0] op_sel_hi:[0,1,1]
	v_pk_mul_f32 v[66:67], v[16:17], v[102:103] op_sel:[0,0] op_sel_hi:[0,1]
	v_pk_fma_f32 v[64:65], v[8:9], v[88:89], v[64:65] op_sel:[1,0,0] op_sel_hi:[1,1,1]
	v_pk_fma_f32 v[66:67], v[16:17], v[104:105], v[66:67] op_sel:[1,0,0] op_sel_hi:[1,1,1]
	v_pk_fma_f32 v[64:65], v[10:11], v[90:91], v[64:65] op_sel:[0,0,0] op_sel_hi:[0,1,1]
	v_pk_fma_f32 v[66:67], v[18:19], v[106:107], v[66:67] op_sel:[0,0,0] op_sel_hi:[0,1,1]
	v_pk_fma_f32 v[64:65], v[10:11], v[92:93], v[64:65] op_sel:[1,0,0] op_sel_hi:[1,1,1]
	v_pk_fma_f32 v[66:67], v[18:19], v[108:109], v[66:67] op_sel:[1,0,0] op_sel_hi:[1,1,1]
	v_pk_fma_f32 v[64:65], v[12:13], v[94:95], v[64:65] op_sel:[0,0,0] op_sel_hi:[0,1,1]
	v_pk_fma_f32 v[66:67], v[20:21], v[110:111], v[66:67] op_sel:[0,0,0] op_sel_hi:[0,1,1]
	v_pk_fma_f32 v[64:65], v[12:13], v[96:97], v[64:65] op_sel:[1,0,0] op_sel_hi:[1,1,1]
	v_pk_fma_f32 v[66:67], v[20:21], v[112:113], v[66:67] op_sel:[1,0,0] op_sel_hi:[1,1,1]
	v_pk_fma_f32 v[64:65], v[14:15], v[98:99], v[64:65] op_sel:[0,0,0] op_sel_hi:[0,1,1]
	v_pk_fma_f32 v[66:67], v[22:23], v[114:115], v[66:67] op_sel:[0,0,0] op_sel_hi:[0,1,1]
	v_pk_fma_f32 v[64:65], v[14:15], v[100:101], v[64:65] op_sel:[1,0,0] op_sel_hi:[1,1,1]
	v_pk_fma_f32 v[66:67], v[22:23], v[116:117], v[66:67] op_sel:[1,0,0] op_sel_hi:[1,1,1]
	v_lshlrev_b32_e32 v148, 16, v24
	v_pk_add_f32 v[64:65], v[64:65], v[66:67]
	v_and_b32_e32 v149, 0xffff0000, v24
	s_waitcnt lgkmcnt(0)
	v_pk_mul_f32 v[0:1], v[0:1], v[240:241]
	v_pk_mul_f32 v[2:3], v[2:3], v[242:243]
	v_pk_mul_f32 v[4:5], v[4:5], v[240:241]
	v_pk_mul_f32 v[6:7], v[6:7], v[242:243]
	s_waitcnt vmcnt(16)
	s_nop 0
	v_mfma_f32_16x16x32_bf16 v[0:3], v[154:157], v[32:35], v[0:3]
	v_mfma_f32_16x16x32_bf16 v[4:7], v[154:157], v[40:43], v[4:7]
	v_mfma_f32_16x16x32_bf16 v[0:3], v[236:239], v[36:39], v[0:3]
	v_mfma_f32_16x16x32_bf16 v[4:7], v[236:239], v[44:47], v[4:7]
	v_mul_f32_e64 v68, |v64|, v220
	v_mul_f32_e64 v69, |v65|, v220
	v_exp_f32_e32 v68, v68
	v_exp_f32_e32 v69, v69
	v_min_f32_e32 v70, 0, v64
	v_min_f32_e32 v71, 0, v65
	v_pk_add_f32 v[68:69], v[68:69], v[222:223]
	s_nop 0
	v_log_f32_e32 v138, v68
	v_log_f32_e32 v139, v69
	s_nop 0
	v_pk_mul_f32 v[140:141], v[138:139], v[224:225]
	s_nop 0
	v_pk_fma_f32 v[142:143], v[138:139], v[224:225], v[140:141] neg_lo:[0,0,1] neg_hi:[0,0,1]
	s_nop 0
	v_pk_fma_f32 v[142:143], v[138:139], v[226:227], v[142:143]
	s_nop 0
	v_pk_fma_f32 v[142:143], v[138:139], v[224:225], v[142:143]
	s_nop 0
	v_pk_add_f32 v[144:145], v[70:71], v[142:143] neg_lo:[0,1] neg_hi:[0,1]
	s_nop 0
	v_pk_mul_f32 v[144:145], v[144:145], v[214:215]
	v_cvt_pk_bf16_f32 v244, v0, v1
	v_cvt_pk_bf16_f32 v245, v2, v3
	v_cvt_pk_bf16_f32 v246, v4, v5
	v_cvt_pk_bf16_f32 v247, v6, v7
	global_store_dwordx2 v234, v[244:245], s[100:101]
	global_store_dwordx2 v235, v[246:247], s[100:101]
	s_add_u32 s100, s100, 0x40000
	s_addc_u32 s101, s101, 0
	v_add_f32_dpp v144, v144, v144 row_shr:1 row_mask:0xf bank_mask:0xf
	v_add_f32_dpp v145, v145, v145 row_shr:1 row_mask:0xf bank_mask:0xf
	s_nop 0
	v_add_f32_dpp v144, v144, v144 row_shr:2 row_mask:0xf bank_mask:0xf
	v_add_f32_dpp v145, v145, v145 row_shr:2 row_mask:0xf bank_mask:0xf
	s_nop 0
	v_add_f32_dpp v144, v144, v144 row_shr:4 row_mask:0xf bank_mask:0xf
	v_add_f32_dpp v145, v145, v145 row_shr:4 row_mask:0xf bank_mask:0xf
	s_nop 0
	v_add_f32_dpp v144, v144, v144 row_shr:8 row_mask:0xf bank_mask:0xf
	v_add_f32_dpp v145, v145, v145 row_shr:8 row_mask:0xf bank_mask:0xf
	s_nop 0
	v_add_f32_dpp v144, v144, v144 row_bcast:15 row_mask:0xa bank_mask:0xf
	v_add_f32_dpp v145, v145, v145 row_bcast:15 row_mask:0xa bank_mask:0xf
	s_nop 0
	v_add_f32_dpp v144, v144, v144 row_bcast:31 row_mask:0xc bank_mask:0xf
	v_add_f32_dpp v145, v145, v145 row_bcast:31 row_mask:0xc bank_mask:0xf
	s_nop 0
	v_readlane_b32 s98, v144, 63
	v_readlane_b32 s99, v145, 63
	s_nop 1
	v_pk_add_f32 v[146:147], s[98:99], v[144:145] neg_lo:[0,1] neg_hi:[0,1]
	v_mul_f32_e64 v152, s98, v228
	v_mul_f32_e64 v153, s99, v228
	v_pk_mul_f32 v[146:147], v[146:147], v[228:229]
	v_exp_f32_e32 v152, v152
	v_exp_f32_e32 v153, v153
	v_exp_f32_e32 v146, v146
	v_exp_f32_e32 v147, v147
	s_nop 0
	v_pk_mul_f32 v[146:147], v[146:147], v[148:149]
	s_nop 0
	v_cvt_pk_bf16_f32 v150, v146, v147
	s_nop 0
	ds_write_b16 v172, v150 offset:2048
	ds_write_b16_d16_hi v172, v150 offset:2176
	s_and_saveexec_b64 s[20:21], vcc
	ds_write_b64 v163, v[152:153] offset:4160
	s_mov_b64 exec, s[20:21]
	s_waitcnt vmcnt(22)
	ds_write_b64 v28, v[56:57] offset:0
	ds_write_b32 v30, v58 offset:0
	s_waitcnt lgkmcnt(0)
	s_barrier
; DI float bf2f(unsigned x) { return __uint_as_float(x << 16); }
;     ...
;         auto ldchunk = [&](int n) {
;             const int tok = b * 4096 + n * 64 + l;
; #pragma unroll
;             for (int q = 0; q < 4; ++q) a4n[q] = *(const f32x4*)(GA + (size_t)tok * 16 + 4 * q);
;             krawn = *(const unsigned*)(GK + (size_t)tok * 512 + kc0);
; #pragma unroll
;             for (int e = 0; e < 2; ++e)
; #pragma unroll
;                 for (int ks = 0; ks < 2; ++ks)
;                     vfrn[e][ks] = *(const bf16x8*)(GVT + ((size_t)(b * 1024 + hh * 256 + (2 * w + e) * 16 + (l & 15))) * 4096 + n * 64 + ks * 32 + (l >> 4) * 8);
;         };
;         ldchunk(0);
;         for (int n = 0; n < 64; ++n) {
;             const int buf = n & 1;
;             f32x4 a4[4]; bf16x8 vfr[2][2];
; #pragma unroll
;             for (int q = 0; q < 4; ++q) a4[q] = a4n[q];
;             const unsigned kraw = krawn;
; #pragma unroll
;             for (int e = 0; e < 2; ++e)
; #pragma unroll
;                 for (int ks = 0; ks < 2; ++ks) vfr[e][ks] = vfrn[e][ks];
;             if (n + 1 < 64) ldchunk(n + 1);
;             float cum[2];
; #pragma unroll
;             for (int e = 0; e < 2; ++e) {
;                 float z = bb[e];
; #pragma unroll
;                 for (int q = 0; q < 4; ++q) { z += a4[q].x * wa[e][4 * q] + a4[q].y * wa[e][4 * q + 1] + a4[q].z * wa[e][4 * q + 2] + a4[q].w * wa[e][4 * q + 3]; }
;                 cum[e] = (fminf(z, 0.f) - __logf(1.f + __expf(-fabsf(z)))) * (1.f / 16.f);
;             }
; #pragma unroll
;             for (int o = 1; o < 64; o <<= 1) {
;                 const float t0 = __shfl_up(cum[0], o), t1 = __shfl_up(cum[1], o);
;                 if (l >= o) { cum[0] += t0; cum[1] += t1; }
;             }
;             const float tot0 = __shfl(cum[0], 63), tot1 = __shfl(cum[1], 63);
;             kdl[(buf * 16 + 2 * w) * 64 + l] = f2bf(bf2f(kraw & 0xffffu) * __expf(tot0 - cum[0]));
;             kdl[(buf * 16 + 2 * w + 1) * 64 + l] = f2bf(bf2f(kraw >> 16) * __expf(tot1 - cum[1]));
;             if (l == 0) { decl[buf * 16 + 2 * w] = __expf(tot0); decl[buf * 16 + 2 * w + 1] = __expf(tot1); }
;             __syncthreads();
;             const f32x4 d4 = *(const f32x4*)(decl + buf * 16 + (l >> 4) * 4);
; #pragma unroll
;             for (int e = 0; e < 2; ++e) acc[e] = acc[e] * d4;
; #pragma unroll
;             for (int ks = 0; ks < 2; ++ks) {
	ds_read_b128 v[8:11], v29 offset:0
	ds_read_b128 v[12:15], v29 offset:16
	ds_read_b128 v[16:19], v29 offset:32
	ds_read_b128 v[20:23], v29 offset:48
	ds_read_b32 v24, v31 offset:0
	global_load_dwordx2 v[56:57], v230, s[26:27]
	global_load_dword v58, v231, s[58:59]
	s_add_u32 s26, s26, 0x1000
	s_addc_u32 s27, s27, 0
	s_add_u32 s58, s58, 0x10000
	s_addc_u32 s59, s59, 0
	global_load_dwordx4 v[32:35], v232, s[34:35]
	global_load_dwordx4 v[36:39], v233, s[34:35]
	global_load_dwordx4 v[40:43], v232, s[34:35] offset:1024
	global_load_dwordx4 v[44:47], v233, s[34:35] offset:1024
	s_add_u32 s34, s34, 0x8000
	s_addc_u32 s35, s35, 0
	ds_read_b128 v[154:157], v75 offset:2048
	ds_read_b128 v[240:243], v164 offset:4160
	ds_read_b128 v[236:239], v75 offset:2112
	s_waitcnt lgkmcnt(3)
	v_pk_fma_f32 v[64:65], v[8:9], v[86:87], v[118:119] op_sel:[0,0,0] op_sel_hi:[0,1,1]
	v_pk_mul_f32 v[66:67], v[16:17], v[102:103] op_sel:[0,0] op_sel_hi:[0,1]
	v_pk_fma_f32 v[64:65], v[8:9], v[88:89], v[64:65] op_sel:[1,0,0] op_sel_hi:[1,1,1]
	v_pk_fma_f32 v[66:67], v[16:17], v[104:105], v[66:67] op_sel:[1,0,0] op_sel_hi:[1,1,1]
	v_pk_fma_f32 v[64:65], v[10:11], v[90:91], v[64:65] op_sel:[0,0,0] op_sel_hi:[0,1,1]
	v_pk_fma_f32 v[66:67], v[18:19], v[106:107], v[66:67] op_sel:[0,0,0] op_sel_hi:[0,1,1]
	v_pk_fma_f32 v[64:65], v[10:11], v[92:93], v[64:65] op_sel:[1,0,0] op_sel_hi:[1,1,1]
	v_pk_fma_f32 v[66:67], v[18:19], v[108:109], v[66:67] op_sel:[1,0,0] op_sel_hi:[1,1,1]
	v_pk_fma_f32 v[64:65], v[12:13], v[94:95], v[64:65] op_sel:[0,0,0] op_sel_hi:[0,1,1]
	v_pk_fma_f32 v[66:67], v[20:21], v[110:111], v[66:67] op_sel:[0,0,0] op_sel_hi:[0,1,1]
	v_pk_fma_f32 v[64:65], v[12:13], v[96:97], v[64:65] op_sel:[1,0,0] op_sel_hi:[1,1,1]
	v_pk_fma_f32 v[66:67], v[20:21], v[112:113], v[66:67] op_sel:[1,0,0] op_sel_hi:[1,1,1]
	v_pk_fma_f32 v[64:65], v[14:15], v[98:99], v[64:65] op_sel:[0,0,0] op_sel_hi:[0,1,1]
	v_pk_fma_f32 v[66:67], v[22:23], v[114:115], v[66:67] op_sel:[0,0,0] op_sel_hi:[0,1,1]
	v_pk_fma_f32 v[64:65], v[14:15], v[100:101], v[64:65] op_sel:[1,0,0] op_sel_hi:[1,1,1]
	v_pk_fma_f32 v[66:67], v[22:23], v[116:117], v[66:67] op_sel:[1,0,0] op_sel_hi:[1,1,1]
	v_lshlrev_b32_e32 v148, 16, v24
	v_pk_add_f32 v[64:65], v[64:65], v[66:67]
	v_and_b32_e32 v149, 0xffff0000, v24
	s_waitcnt lgkmcnt(0)
	v_pk_mul_f32 v[0:1], v[0:1], v[240:241]
	v_pk_mul_f32 v[2:3], v[2:3], v[242:243]
	v_pk_mul_f32 v[4:5], v[4:5], v[240:241]
	v_pk_mul_f32 v[6:7], v[6:7], v[242:243]
	s_waitcnt vmcnt(16)
	s_nop 0
	v_mfma_f32_16x16x32_bf16 v[0:3], v[154:157], v[178:181], v[0:3]
	v_mfma_f32_16x16x32_bf16 v[4:7], v[154:157], v[186:189], v[4:7]
	v_mfma_f32_16x16x32_bf16 v[0:3], v[236:239], v[182:185], v[0:3]
	v_mfma_f32_16x16x32_bf16 v[4:7], v[236:239], v[190:193], v[4:7]
	v_mul_f32_e64 v68, |v64|, v220
	v_mul_f32_e64 v69, |v65|, v220
	v_exp_f32_e32 v68, v68
	v_exp_f32_e32 v69, v69
	v_min_f32_e32 v70, 0, v64
	v_min_f32_e32 v71, 0, v65
	v_pk_add_f32 v[68:69], v[68:69], v[222:223]
	s_nop 0
	v_log_f32_e32 v138, v68
	v_log_f32_e32 v139, v69
	s_nop 0
	v_pk_mul_f32 v[140:141], v[138:139], v[224:225]
	s_nop 0
	v_pk_fma_f32 v[142:143], v[138:139], v[224:225], v[140:141] neg_lo:[0,0,1] neg_hi:[0,0,1]
	s_nop 0
	v_pk_fma_f32 v[142:143], v[138:139], v[226:227], v[142:143]
	s_nop 0
	v_pk_fma_f32 v[142:143], v[138:139], v[224:225], v[142:143]
	s_nop 0
	v_pk_add_f32 v[144:145], v[70:71], v[142:143] neg_lo:[0,1] neg_hi:[0,1]
	s_nop 0
	v_pk_mul_f32 v[144:145], v[144:145], v[214:215]
	v_cvt_pk_bf16_f32 v244, v0, v1
	v_cvt_pk_bf16_f32 v245, v2, v3
	v_cvt_pk_bf16_f32 v246, v4, v5
	v_cvt_pk_bf16_f32 v247, v6, v7
	global_store_dwordx2 v234, v[244:245], s[100:101]
	global_store_dwordx2 v235, v[246:247], s[100:101]
	s_add_u32 s100, s100, 0x40000
	s_addc_u32 s101, s101, 0
	v_add_f32_dpp v144, v144, v144 row_shr:1 row_mask:0xf bank_mask:0xf
	v_add_f32_dpp v145, v145, v145 row_shr:1 row_mask:0xf bank_mask:0xf
	s_nop 0
	v_add_f32_dpp v144, v144, v144 row_shr:2 row_mask:0xf bank_mask:0xf
	v_add_f32_dpp v145, v145, v145 row_shr:2 row_mask:0xf bank_mask:0xf
	s_nop 0
	v_add_f32_dpp v144, v144, v144 row_shr:4 row_mask:0xf bank_mask:0xf
	v_add_f32_dpp v145, v145, v145 row_shr:4 row_mask:0xf bank_mask:0xf
	s_nop 0
	v_add_f32_dpp v144, v144, v144 row_shr:8 row_mask:0xf bank_mask:0xf
	v_add_f32_dpp v145, v145, v145 row_shr:8 row_mask:0xf bank_mask:0xf
	s_nop 0
	v_add_f32_dpp v144, v144, v144 row_bcast:15 row_mask:0xa bank_mask:0xf
	v_add_f32_dpp v145, v145, v145 row_bcast:15 row_mask:0xa bank_mask:0xf
	s_nop 0
	v_add_f32_dpp v144, v144, v144 row_bcast:31 row_mask:0xc bank_mask:0xf
	v_add_f32_dpp v145, v145, v145 row_bcast:31 row_mask:0xc bank_mask:0xf
	s_nop 0
	v_readlane_b32 s98, v144, 63
	v_readlane_b32 s99, v145, 63
	s_nop 1
	v_pk_add_f32 v[146:147], s[98:99], v[144:145] neg_lo:[0,1] neg_hi:[0,1]
	v_mul_f32_e64 v152, s98, v228
	v_mul_f32_e64 v153, s99, v228
	v_pk_mul_f32 v[146:147], v[146:147], v[228:229]
	v_exp_f32_e32 v152, v152
	v_exp_f32_e32 v153, v153
	v_exp_f32_e32 v146, v146
	v_exp_f32_e32 v147, v147
	s_nop 0
	v_pk_mul_f32 v[146:147], v[146:147], v[148:149]
	s_nop 0
	v_cvt_pk_bf16_f32 v150, v146, v147
	s_nop 0
	ds_write_b16 v172, v150 offset:0
	ds_write_b16_d16_hi v172, v150 offset:128
	s_and_saveexec_b64 s[20:21], vcc
	ds_write_b64 v163, v[152:153] offset:4096
	s_mov_b64 exec, s[20:21]
	s_waitcnt vmcnt(22)
	ds_write_b64 v28, v[48:49] offset:5120
	ds_write_b32 v30, v50 offset:2080
	s_waitcnt lgkmcnt(0)
	s_barrier
; DI float bf2f(unsigned x) { return __uint_as_float(x << 16); }
;     ...
;         auto ldchunk = [&](int n) {
;             const int tok = b * 4096 + n * 64 + l;
; #pragma unroll
;             for (int q = 0; q < 4; ++q) a4n[q] = *(const f32x4*)(GA + (size_t)tok * 16 + 4 * q);
;             krawn = *(const unsigned*)(GK + (size_t)tok * 512 + kc0);
; #pragma unroll
;             for (int e = 0; e < 2; ++e)
; #pragma unroll
;                 for (int ks = 0; ks < 2; ++ks)
;                     vfrn[e][ks] = *(const bf16x8*)(GVT + ((size_t)(b * 1024 + hh * 256 + (2 * w + e) * 16 + (l & 15))) * 4096 + n * 64 + ks * 32 + (l >> 4) * 8);
;         };
;         ldchunk(0);
;         for (int n = 0; n < 64; ++n) {
;             const int buf = n & 1;
;             f32x4 a4[4]; bf16x8 vfr[2][2];
; #pragma unroll
;             for (int q = 0; q < 4; ++q) a4[q] = a4n[q];
;             const unsigned kraw = krawn;
; #pragma unroll
;             for (int e = 0; e < 2; ++e)
; #pragma unroll
;                 for (int ks = 0; ks < 2; ++ks) vfr[e][ks] = vfrn[e][ks];
;             if (n + 1 < 64) ldchunk(n + 1);
;             float cum[2];
; #pragma unroll
;             for (int e = 0; e < 2; ++e) {
;                 float z = bb[e];
; #pragma unroll
;                 for (int q = 0; q < 4; ++q) { z += a4[q].x * wa[e][4 * q] + a4[q].y * wa[e][4 * q + 1] + a4[q].z * wa[e][4 * q + 2] + a4[q].w * wa[e][4 * q + 3]; }
;                 cum[e] = (fminf(z, 0.f) - __logf(1.f + __expf(-fabsf(z)))) * (1.f / 16.f);
;             }
; #pragma unroll
;             for (int o = 1; o < 64; o <<= 1) {
;                 const float t0 = __shfl_up(cum[0], o), t1 = __shfl_up(cum[1], o);
;                 if (l >= o) { cum[0] += t0; cum[1] += t1; }
;             }
;             const float tot0 = __shfl(cum[0], 63), tot1 = __shfl(cum[1], 63);
;             kdl[(buf * 16 + 2 * w) * 64 + l] = f2bf(bf2f(kraw & 0xffffu) * __expf(tot0 - cum[0]));
;             kdl[(buf * 16 + 2 * w + 1) * 64 + l] = f2bf(bf2f(kraw >> 16) * __expf(tot1 - cum[1]));
;             if (l == 0) { decl[buf * 16 + 2 * w] = __expf(tot0); decl[buf * 16 + 2 * w + 1] = __expf(tot1); }
;             __syncthreads();
;             const f32x4 d4 = *(const f32x4*)(decl + buf * 16 + (l >> 4) * 4);
; #pragma unroll
;             for (int e = 0; e < 2; ++e) acc[e] = acc[e] * d4;
; #pragma unroll
;             for (int ks = 0; ks < 2; ++ks) {
	ds_read_b128 v[8:11], v29 offset:5120
	ds_read_b128 v[12:15], v29 offset:5136
	ds_read_b128 v[16:19], v29 offset:5152
	ds_read_b128 v[20:23], v29 offset:5168
	ds_read_b32 v24, v31 offset:2080
	global_load_dwordx2 v[48:49], v230, s[26:27]
	global_load_dword v50, v231, s[58:59]
	s_add_u32 s26, s26, 0x1000
	s_addc_u32 s27, s27, 0
	s_add_u32 s58, s58, 0x10000
	s_addc_u32 s59, s59, 0
	global_load_dwordx4 v[178:181], v232, s[34:35]
	global_load_dwordx4 v[182:185], v233, s[34:35]
	global_load_dwordx4 v[186:189], v232, s[34:35] offset:1024
	global_load_dwordx4 v[190:193], v233, s[34:35] offset:1024
	s_add_u32 s34, s34, 0x8000
	s_addc_u32 s35, s35, 0
	ds_read_b128 v[154:157], v75 offset:0
	ds_read_b128 v[240:243], v164 offset:4096
	ds_read_b128 v[236:239], v75 offset:64
	s_waitcnt lgkmcnt(3)
	v_pk_fma_f32 v[64:65], v[8:9], v[86:87], v[118:119] op_sel:[0,0,0] op_sel_hi:[0,1,1]
	v_pk_mul_f32 v[66:67], v[16:17], v[102:103] op_sel:[0,0] op_sel_hi:[0,1]
	v_pk_fma_f32 v[64:65], v[8:9], v[88:89], v[64:65] op_sel:[1,0,0] op_sel_hi:[1,1,1]
	v_pk_fma_f32 v[66:67], v[16:17], v[104:105], v[66:67] op_sel:[1,0,0] op_sel_hi:[1,1,1]
	v_pk_fma_f32 v[64:65], v[10:11], v[90:91], v[64:65] op_sel:[0,0,0] op_sel_hi:[0,1,1]
	v_pk_fma_f32 v[66:67], v[18:19], v[106:107], v[66:67] op_sel:[0,0,0] op_sel_hi:[0,1,1]
	v_pk_fma_f32 v[64:65], v[10:11], v[92:93], v[64:65] op_sel:[1,0,0] op_sel_hi:[1,1,1]
	v_pk_fma_f32 v[66:67], v[18:19], v[108:109], v[66:67] op_sel:[1,0,0] op_sel_hi:[1,1,1]
	v_pk_fma_f32 v[64:65], v[12:13], v[94:95], v[64:65] op_sel:[0,0,0] op_sel_hi:[0,1,1]
	v_pk_fma_f32 v[66:67], v[20:21], v[110:111], v[66:67] op_sel:[0,0,0] op_sel_hi:[0,1,1]
	v_pk_fma_f32 v[64:65], v[12:13], v[96:97], v[64:65] op_sel:[1,0,0] op_sel_hi:[1,1,1]
	v_pk_fma_f32 v[66:67], v[20:21], v[112:113], v[66:67] op_sel:[1,0,0] op_sel_hi:[1,1,1]
	v_pk_fma_f32 v[64:65], v[14:15], v[98:99], v[64:65] op_sel:[0,0,0] op_sel_hi:[0,1,1]
	v_pk_fma_f32 v[66:67], v[22:23], v[114:115], v[66:67] op_sel:[0,0,0] op_sel_hi:[0,1,1]
	v_pk_fma_f32 v[64:65], v[14:15], v[100:101], v[64:65] op_sel:[1,0,0] op_sel_hi:[1,1,1]
	v_pk_fma_f32 v[66:67], v[22:23], v[116:117], v[66:67] op_sel:[1,0,0] op_sel_hi:[1,1,1]
	v_lshlrev_b32_e32 v148, 16, v24
	v_pk_add_f32 v[64:65], v[64:65], v[66:67]
	v_and_b32_e32 v149, 0xffff0000, v24
	s_waitcnt lgkmcnt(0)
	v_pk_mul_f32 v[0:1], v[0:1], v[240:241]
	v_pk_mul_f32 v[2:3], v[2:3], v[242:243]
	v_pk_mul_f32 v[4:5], v[4:5], v[240:241]
	v_pk_mul_f32 v[6:7], v[6:7], v[242:243]
	s_waitcnt vmcnt(16)
	s_nop 0
	v_mfma_f32_16x16x32_bf16 v[0:3], v[154:157], v[194:197], v[0:3]
	v_mfma_f32_16x16x32_bf16 v[4:7], v[154:157], v[202:205], v[4:7]
	v_mfma_f32_16x16x32_bf16 v[0:3], v[236:239], v[198:201], v[0:3]
	v_mfma_f32_16x16x32_bf16 v[4:7], v[236:239], v[206:209], v[4:7]
	v_mul_f32_e64 v68, |v64|, v220
	v_mul_f32_e64 v69, |v65|, v220
	v_exp_f32_e32 v68, v68
	v_exp_f32_e32 v69, v69
	v_min_f32_e32 v70, 0, v64
	v_min_f32_e32 v71, 0, v65
	v_pk_add_f32 v[68:69], v[68:69], v[222:223]
	s_nop 0
	v_log_f32_e32 v138, v68
	v_log_f32_e32 v139, v69
	s_nop 0
	v_pk_mul_f32 v[140:141], v[138:139], v[224:225]
	s_nop 0
	v_pk_fma_f32 v[142:143], v[138:139], v[224:225], v[140:141] neg_lo:[0,0,1] neg_hi:[0,0,1]
	s_nop 0
	v_pk_fma_f32 v[142:143], v[138:139], v[226:227], v[142:143]
	s_nop 0
	v_pk_fma_f32 v[142:143], v[138:139], v[224:225], v[142:143]
	s_nop 0
	v_pk_add_f32 v[144:145], v[70:71], v[142:143] neg_lo:[0,1] neg_hi:[0,1]
	s_nop 0
	v_pk_mul_f32 v[144:145], v[144:145], v[214:215]
	v_cvt_pk_bf16_f32 v244, v0, v1
	v_cvt_pk_bf16_f32 v245, v2, v3
	v_cvt_pk_bf16_f32 v246, v4, v5
	v_cvt_pk_bf16_f32 v247, v6, v7
	global_store_dwordx2 v234, v[244:245], s[100:101]
	global_store_dwordx2 v235, v[246:247], s[100:101]
	s_add_u32 s100, s100, 0x40000
	s_addc_u32 s101, s101, 0
	v_add_f32_dpp v144, v144, v144 row_shr:1 row_mask:0xf bank_mask:0xf
	v_add_f32_dpp v145, v145, v145 row_shr:1 row_mask:0xf bank_mask:0xf
	s_nop 0
	v_add_f32_dpp v144, v144, v144 row_shr:2 row_mask:0xf bank_mask:0xf
	v_add_f32_dpp v145, v145, v145 row_shr:2 row_mask:0xf bank_mask:0xf
	s_nop 0
	v_add_f32_dpp v144, v144, v144 row_shr:4 row_mask:0xf bank_mask:0xf
	v_add_f32_dpp v145, v145, v145 row_shr:4 row_mask:0xf bank_mask:0xf
	s_nop 0
	v_add_f32_dpp v144, v144, v144 row_shr:8 row_mask:0xf bank_mask:0xf
	v_add_f32_dpp v145, v145, v145 row_shr:8 row_mask:0xf bank_mask:0xf
	s_nop 0
	v_add_f32_dpp v144, v144, v144 row_bcast:15 row_mask:0xa bank_mask:0xf
	v_add_f32_dpp v145, v145, v145 row_bcast:15 row_mask:0xa bank_mask:0xf
	s_nop 0
	v_add_f32_dpp v144, v144, v144 row_bcast:31 row_mask:0xc bank_mask:0xf
	v_add_f32_dpp v145, v145, v145 row_bcast:31 row_mask:0xc bank_mask:0xf
	s_nop 0
	v_readlane_b32 s98, v144, 63
	v_readlane_b32 s99, v145, 63
	s_nop 1
	v_pk_add_f32 v[146:147], s[98:99], v[144:145] neg_lo:[0,1] neg_hi:[0,1]
	v_mul_f32_e64 v152, s98, v228
	v_mul_f32_e64 v153, s99, v228
	v_pk_mul_f32 v[146:147], v[146:147], v[228:229]
	v_exp_f32_e32 v152, v152
	v_exp_f32_e32 v153, v153
	v_exp_f32_e32 v146, v146
	v_exp_f32_e32 v147, v147
	s_nop 0
	v_pk_mul_f32 v[146:147], v[146:147], v[148:149]
	s_nop 0
	v_cvt_pk_bf16_f32 v150, v146, v147
	s_nop 0
	ds_write_b16 v172, v150 offset:2048
	ds_write_b16_d16_hi v172, v150 offset:2176
	s_and_saveexec_b64 s[20:21], vcc
	ds_write_b64 v163, v[152:153] offset:4160
	s_mov_b64 exec, s[20:21]
	s_waitcnt vmcnt(22)
	ds_write_b64 v28, v[52:53] offset:0
	ds_write_b32 v30, v54 offset:0
	s_waitcnt lgkmcnt(0)
	s_barrier
; DI float bf2f(unsigned x) { return __uint_as_float(x << 16); }
;     ...
;         auto ldchunk = [&](int n) {
;             const int tok = b * 4096 + n * 64 + l;
; #pragma unroll
;             for (int q = 0; q < 4; ++q) a4n[q] = *(const f32x4*)(GA + (size_t)tok * 16 + 4 * q);
;             krawn = *(const unsigned*)(GK + (size_t)tok * 512 + kc0);
; #pragma unroll
;             for (int e = 0; e < 2; ++e)
; #pragma unroll
;                 for (int ks = 0; ks < 2; ++ks)
;                     vfrn[e][ks] = *(const bf16x8*)(GVT + ((size_t)(b * 1024 + hh * 256 + (2 * w + e) * 16 + (l & 15))) * 4096 + n * 64 + ks * 32 + (l >> 4) * 8);
;         };
;         ldchunk(0);
;         for (int n = 0; n < 64; ++n) {
;             const int buf = n & 1;
;             f32x4 a4[4]; bf16x8 vfr[2][2];
; #pragma unroll
;             for (int q = 0; q < 4; ++q) a4[q] = a4n[q];
;             const unsigned kraw = krawn;
; #pragma unroll
;             for (int e = 0; e < 2; ++e)
; #pragma unroll
;                 for (int ks = 0; ks < 2; ++ks) vfr[e][ks] = vfrn[e][ks];
;             if (n + 1 < 64) ldchunk(n + 1);
;             float cum[2];
; #pragma unroll
;             for (int e = 0; e < 2; ++e) {
;                 float z = bb[e];
; #pragma unroll
;                 for (int q = 0; q < 4; ++q) { z += a4[q].x * wa[e][4 * q] + a4[q].y * wa[e][4 * q + 1] + a4[q].z * wa[e][4 * q + 2] + a4[q].w * wa[e][4 * q + 3]; }
;                 cum[e] = (fminf(z, 0.f) - __logf(1.f + __expf(-fabsf(z)))) * (1.f / 16.f);
;             }
; #pragma unroll
;             for (int o = 1; o < 64; o <<= 1) {
;                 const float t0 = __shfl_up(cum[0], o), t1 = __shfl_up(cum[1], o);
;                 if (l >= o) { cum[0] += t0; cum[1] += t1; }
;             }
;             const float tot0 = __shfl(cum[0], 63), tot1 = __shfl(cum[1], 63);
;             kdl[(buf * 16 + 2 * w) * 64 + l] = f2bf(bf2f(kraw & 0xffffu) * __expf(tot0 - cum[0]));
;             kdl[(buf * 16 + 2 * w + 1) * 64 + l] = f2bf(bf2f(kraw >> 16) * __expf(tot1 - cum[1]));
;             if (l == 0) { decl[buf * 16 + 2 * w] = __expf(tot0); decl[buf * 16 + 2 * w + 1] = __expf(tot1); }
;             __syncthreads();
;             const f32x4 d4 = *(const f32x4*)(decl + buf * 16 + (l >> 4) * 4);
; #pragma unroll
;             for (int e = 0; e < 2; ++e) acc[e] = acc[e] * d4;
; #pragma unroll
;             for (int ks = 0; ks < 2; ++ks) {
	ds_read_b128 v[8:11], v29 offset:0
	ds_read_b128 v[12:15], v29 offset:16
	ds_read_b128 v[16:19], v29 offset:32
	ds_read_b128 v[20:23], v29 offset:48
	ds_read_b32 v24, v31 offset:0
	global_load_dwordx2 v[52:53], v230, s[26:27]
	global_load_dword v54, v231, s[58:59]
	s_add_u32 s26, s26, 0x1000
	s_addc_u32 s27, s27, 0
	s_add_u32 s58, s58, 0x10000
	s_addc_u32 s59, s59, 0
	global_load_dwordx4 v[194:197], v232, s[34:35]
	global_load_dwordx4 v[198:201], v233, s[34:35]
	global_load_dwordx4 v[202:205], v232, s[34:35] offset:1024
	global_load_dwordx4 v[206:209], v233, s[34:35] offset:1024
	s_add_u32 s34, s34, 0x8000
	s_addc_u32 s35, s35, 0
	ds_read_b128 v[154:157], v75 offset:2048
	ds_read_b128 v[240:243], v164 offset:4160
	ds_read_b128 v[236:239], v75 offset:2112
	s_waitcnt lgkmcnt(3)
	v_pk_fma_f32 v[64:65], v[8:9], v[86:87], v[118:119] op_sel:[0,0,0] op_sel_hi:[0,1,1]
	v_pk_mul_f32 v[66:67], v[16:17], v[102:103] op_sel:[0,0] op_sel_hi:[0,1]
	v_pk_fma_f32 v[64:65], v[8:9], v[88:89], v[64:65] op_sel:[1,0,0] op_sel_hi:[1,1,1]
	v_pk_fma_f32 v[66:67], v[16:17], v[104:105], v[66:67] op_sel:[1,0,0] op_sel_hi:[1,1,1]
	v_pk_fma_f32 v[64:65], v[10:11], v[90:91], v[64:65] op_sel:[0,0,0] op_sel_hi:[0,1,1]
	v_pk_fma_f32 v[66:67], v[18:19], v[106:107], v[66:67] op_sel:[0,0,0] op_sel_hi:[0,1,1]
	v_pk_fma_f32 v[64:65], v[10:11], v[92:93], v[64:65] op_sel:[1,0,0] op_sel_hi:[1,1,1]
	v_pk_fma_f32 v[66:67], v[18:19], v[108:109], v[66:67] op_sel:[1,0,0] op_sel_hi:[1,1,1]
	v_pk_fma_f32 v[64:65], v[12:13], v[94:95], v[64:65] op_sel:[0,0,0] op_sel_hi:[0,1,1]
	v_pk_fma_f32 v[66:67], v[20:21], v[110:111], v[66:67] op_sel:[0,0,0] op_sel_hi:[0,1,1]
	v_pk_fma_f32 v[64:65], v[12:13], v[96:97], v[64:65] op_sel:[1,0,0] op_sel_hi:[1,1,1]
	v_pk_fma_f32 v[66:67], v[20:21], v[112:113], v[66:67] op_sel:[1,0,0] op_sel_hi:[1,1,1]
	v_pk_fma_f32 v[64:65], v[14:15], v[98:99], v[64:65] op_sel:[0,0,0] op_sel_hi:[0,1,1]
	v_pk_fma_f32 v[66:67], v[22:23], v[114:115], v[66:67] op_sel:[0,0,0] op_sel_hi:[0,1,1]
	v_pk_fma_f32 v[64:65], v[14:15], v[100:101], v[64:65] op_sel:[1,0,0] op_sel_hi:[1,1,1]
	v_pk_fma_f32 v[66:67], v[22:23], v[116:117], v[66:67] op_sel:[1,0,0] op_sel_hi:[1,1,1]
	v_lshlrev_b32_e32 v148, 16, v24
	v_pk_add_f32 v[64:65], v[64:65], v[66:67]
	v_and_b32_e32 v149, 0xffff0000, v24
	s_waitcnt lgkmcnt(0)
	v_pk_mul_f32 v[0:1], v[0:1], v[240:241]
	v_pk_mul_f32 v[2:3], v[2:3], v[242:243]
	v_pk_mul_f32 v[4:5], v[4:5], v[240:241]
	v_pk_mul_f32 v[6:7], v[6:7], v[242:243]
	s_waitcnt vmcnt(16)
	s_nop 0
	v_mfma_f32_16x16x32_bf16 v[0:3], v[154:157], v[32:35], v[0:3]
	v_mfma_f32_16x16x32_bf16 v[4:7], v[154:157], v[40:43], v[4:7]
	v_mfma_f32_16x16x32_bf16 v[0:3], v[236:239], v[36:39], v[0:3]
	v_mfma_f32_16x16x32_bf16 v[4:7], v[236:239], v[44:47], v[4:7]
	v_mul_f32_e64 v68, |v64|, v220
	v_mul_f32_e64 v69, |v65|, v220
	v_exp_f32_e32 v68, v68
	v_exp_f32_e32 v69, v69
	v_min_f32_e32 v70, 0, v64
	v_min_f32_e32 v71, 0, v65
	v_pk_add_f32 v[68:69], v[68:69], v[222:223]
	s_nop 0
	v_log_f32_e32 v138, v68
	v_log_f32_e32 v139, v69
	s_nop 0
	v_pk_mul_f32 v[140:141], v[138:139], v[224:225]
	s_nop 0
	v_pk_fma_f32 v[142:143], v[138:139], v[224:225], v[140:141] neg_lo:[0,0,1] neg_hi:[0,0,1]
	s_nop 0
	v_pk_fma_f32 v[142:143], v[138:139], v[226:227], v[142:143]
	s_nop 0
	v_pk_fma_f32 v[142:143], v[138:139], v[224:225], v[142:143]
	s_nop 0
	v_pk_add_f32 v[144:145], v[70:71], v[142:143] neg_lo:[0,1] neg_hi:[0,1]
	s_nop 0
	v_pk_mul_f32 v[144:145], v[144:145], v[214:215]
	v_cvt_pk_bf16_f32 v244, v0, v1
	v_cvt_pk_bf16_f32 v245, v2, v3
	v_cvt_pk_bf16_f32 v246, v4, v5
	v_cvt_pk_bf16_f32 v247, v6, v7
	global_store_dwordx2 v234, v[244:245], s[100:101]
	global_store_dwordx2 v235, v[246:247], s[100:101]
	s_add_u32 s100, s100, 0x40000
	s_addc_u32 s101, s101, 0
	v_add_f32_dpp v144, v144, v144 row_shr:1 row_mask:0xf bank_mask:0xf
	v_add_f32_dpp v145, v145, v145 row_shr:1 row_mask:0xf bank_mask:0xf
	s_nop 0
	v_add_f32_dpp v144, v144, v144 row_shr:2 row_mask:0xf bank_mask:0xf
	v_add_f32_dpp v145, v145, v145 row_shr:2 row_mask:0xf bank_mask:0xf
	s_nop 0
	v_add_f32_dpp v144, v144, v144 row_shr:4 row_mask:0xf bank_mask:0xf
	v_add_f32_dpp v145, v145, v145 row_shr:4 row_mask:0xf bank_mask:0xf
	s_nop 0
	v_add_f32_dpp v144, v144, v144 row_shr:8 row_mask:0xf bank_mask:0xf
	v_add_f32_dpp v145, v145, v145 row_shr:8 row_mask:0xf bank_mask:0xf
	s_nop 0
	v_add_f32_dpp v144, v144, v144 row_bcast:15 row_mask:0xa bank_mask:0xf
	v_add_f32_dpp v145, v145, v145 row_bcast:15 row_mask:0xa bank_mask:0xf
	s_nop 0
	v_add_f32_dpp v144, v144, v144 row_bcast:31 row_mask:0xc bank_mask:0xf
	v_add_f32_dpp v145, v145, v145 row_bcast:31 row_mask:0xc bank_mask:0xf
	s_nop 0
	v_readlane_b32 s98, v144, 63
	v_readlane_b32 s99, v145, 63
	s_nop 1
	v_pk_add_f32 v[146:147], s[98:99], v[144:145] neg_lo:[0,1] neg_hi:[0,1]
	v_mul_f32_e64 v152, s98, v228
	v_mul_f32_e64 v153, s99, v228
	v_pk_mul_f32 v[146:147], v[146:147], v[228:229]
	v_exp_f32_e32 v152, v152
	v_exp_f32_e32 v153, v153
	v_exp_f32_e32 v146, v146
	v_exp_f32_e32 v147, v147
	s_nop 0
	v_pk_mul_f32 v[146:147], v[146:147], v[148:149]
	s_nop 0
	v_cvt_pk_bf16_f32 v150, v146, v147
	s_nop 0
	ds_write_b16 v172, v150 offset:0
	ds_write_b16_d16_hi v172, v150 offset:128
	s_and_saveexec_b64 s[20:21], vcc
	ds_write_b64 v163, v[152:153] offset:4096
	s_mov_b64 exec, s[20:21]
	s_waitcnt vmcnt(22)
	ds_write_b64 v28, v[56:57] offset:5120
	ds_write_b32 v30, v58 offset:2080
	s_waitcnt lgkmcnt(0)
	s_barrier
; DI float bf2f(unsigned x) { return __uint_as_float(x << 16); }
;     ...
;         auto ldchunk = [&](int n) {
;             const int tok = b * 4096 + n * 64 + l;
; #pragma unroll
;             for (int q = 0; q < 4; ++q) a4n[q] = *(const f32x4*)(GA + (size_t)tok * 16 + 4 * q);
;             krawn = *(const unsigned*)(GK + (size_t)tok * 512 + kc0);
; #pragma unroll
;             for (int e = 0; e < 2; ++e)
; #pragma unroll
;                 for (int ks = 0; ks < 2; ++ks)
;                     vfrn[e][ks] = *(const bf16x8*)(GVT + ((size_t)(b * 1024 + hh * 256 + (2 * w + e) * 16 + (l & 15))) * 4096 + n * 64 + ks * 32 + (l >> 4) * 8);
;         };
;         ldchunk(0);
;         for (int n = 0; n < 64; ++n) {
;             const int buf = n & 1;
;             f32x4 a4[4]; bf16x8 vfr[2][2];
; #pragma unroll
;             for (int q = 0; q < 4; ++q) a4[q] = a4n[q];
;             const unsigned kraw = krawn;
; #pragma unroll
;             for (int e = 0; e < 2; ++e)
; #pragma unroll
;                 for (int ks = 0; ks < 2; ++ks) vfr[e][ks] = vfrn[e][ks];
;             if (n + 1 < 64) ldchunk(n + 1);
;             float cum[2];
; #pragma unroll
;             for (int e = 0; e < 2; ++e) {
;                 float z = bb[e];
; #pragma unroll
;                 for (int q = 0; q < 4; ++q) { z += a4[q].x * wa[e][4 * q] + a4[q].y * wa[e][4 * q + 1] + a4[q].z * wa[e][4 * q + 2] + a4[q].w * wa[e][4 * q + 3]; }
;                 cum[e] = (fminf(z, 0.f) - __logf(1.f + __expf(-fabsf(z)))) * (1.f / 16.f);
;             }
; #pragma unroll
;             for (int o = 1; o < 64; o <<= 1) {
;                 const float t0 = __shfl_up(cum[0], o), t1 = __shfl_up(cum[1], o);
;                 if (l >= o) { cum[0] += t0; cum[1] += t1; }
;             }
;             const float tot0 = __shfl(cum[0], 63), tot1 = __shfl(cum[1], 63);
;             kdl[(buf * 16 + 2 * w) * 64 + l] = f2bf(bf2f(kraw & 0xffffu) * __expf(tot0 - cum[0]));
;             kdl[(buf * 16 + 2 * w + 1) * 64 + l] = f2bf(bf2f(kraw >> 16) * __expf(tot1 - cum[1]));
;             if (l == 0) { decl[buf * 16 + 2 * w] = __expf(tot0); decl[buf * 16 + 2 * w + 1] = __expf(tot1); }
;             __syncthreads();
;             const f32x4 d4 = *(const f32x4*)(decl + buf * 16 + (l >> 4) * 4);
; #pragma unroll
;             for (int e = 0; e < 2; ++e) acc[e] = acc[e] * d4;
; #pragma unroll
;             for (int ks = 0; ks < 2; ++ks) {
	ds_read_b128 v[8:11], v29 offset:5120
	ds_read_b128 v[12:15], v29 offset:5136
	ds_read_b128 v[16:19], v29 offset:5152
	ds_read_b128 v[20:23], v29 offset:5168
	ds_read_b32 v24, v31 offset:2080
	global_load_dwordx2 v[56:57], v230, s[26:27]
	global_load_dword v58, v231, s[58:59]
	s_add_u32 s26, s26, 0x1000
	s_addc_u32 s27, s27, 0
	s_add_u32 s58, s58, 0x10000
	s_addc_u32 s59, s59, 0
	global_load_dwordx4 v[32:35], v232, s[34:35]
	global_load_dwordx4 v[36:39], v233, s[34:35]
	global_load_dwordx4 v[40:43], v232, s[34:35] offset:1024
	global_load_dwordx4 v[44:47], v233, s[34:35] offset:1024
	s_add_u32 s34, s34, 0x8000
	s_addc_u32 s35, s35, 0
	ds_read_b128 v[154:157], v75 offset:0
	ds_read_b128 v[240:243], v164 offset:4096
	ds_read_b128 v[236:239], v75 offset:64
	s_waitcnt lgkmcnt(3)
	v_pk_fma_f32 v[64:65], v[8:9], v[86:87], v[118:119] op_sel:[0,0,0] op_sel_hi:[0,1,1]
	v_pk_mul_f32 v[66:67], v[16:17], v[102:103] op_sel:[0,0] op_sel_hi:[0,1]
	v_pk_fma_f32 v[64:65], v[8:9], v[88:89], v[64:65] op_sel:[1,0,0] op_sel_hi:[1,1,1]
	v_pk_fma_f32 v[66:67], v[16:17], v[104:105], v[66:67] op_sel:[1,0,0] op_sel_hi:[1,1,1]
	v_pk_fma_f32 v[64:65], v[10:11], v[90:91], v[64:65] op_sel:[0,0,0] op_sel_hi:[0,1,1]
	v_pk_fma_f32 v[66:67], v[18:19], v[106:107], v[66:67] op_sel:[0,0,0] op_sel_hi:[0,1,1]
	v_pk_fma_f32 v[64:65], v[10:11], v[92:93], v[64:65] op_sel:[1,0,0] op_sel_hi:[1,1,1]
	v_pk_fma_f32 v[66:67], v[18:19], v[108:109], v[66:67] op_sel:[1,0,0] op_sel_hi:[1,1,1]
	v_pk_fma_f32 v[64:65], v[12:13], v[94:95], v[64:65] op_sel:[0,0,0] op_sel_hi:[0,1,1]
	v_pk_fma_f32 v[66:67], v[20:21], v[110:111], v[66:67] op_sel:[0,0,0] op_sel_hi:[0,1,1]
	v_pk_fma_f32 v[64:65], v[12:13], v[96:97], v[64:65] op_sel:[1,0,0] op_sel_hi:[1,1,1]
	v_pk_fma_f32 v[66:67], v[20:21], v[112:113], v[66:67] op_sel:[1,0,0] op_sel_hi:[1,1,1]
	v_pk_fma_f32 v[64:65], v[14:15], v[98:99], v[64:65] op_sel:[0,0,0] op_sel_hi:[0,1,1]
	v_pk_fma_f32 v[66:67], v[22:23], v[114:115], v[66:67] op_sel:[0,0,0] op_sel_hi:[0,1,1]
	v_pk_fma_f32 v[64:65], v[14:15], v[100:101], v[64:65] op_sel:[1,0,0] op_sel_hi:[1,1,1]
	v_pk_fma_f32 v[66:67], v[22:23], v[116:117], v[66:67] op_sel:[1,0,0] op_sel_hi:[1,1,1]
	v_lshlrev_b32_e32 v148, 16, v24
	v_pk_add_f32 v[64:65], v[64:65], v[66:67]
	v_and_b32_e32 v149, 0xffff0000, v24
	s_waitcnt lgkmcnt(0)
	v_pk_mul_f32 v[0:1], v[0:1], v[240:241]
	v_pk_mul_f32 v[2:3], v[2:3], v[242:243]
	v_pk_mul_f32 v[4:5], v[4:5], v[240:241]
	v_pk_mul_f32 v[6:7], v[6:7], v[242:243]
	s_waitcnt vmcnt(16)
	s_nop 0
	v_mfma_f32_16x16x32_bf16 v[0:3], v[154:157], v[178:181], v[0:3]
	v_mfma_f32_16x16x32_bf16 v[4:7], v[154:157], v[186:189], v[4:7]
	v_mfma_f32_16x16x32_bf16 v[0:3], v[236:239], v[182:185], v[0:3]
	v_mfma_f32_16x16x32_bf16 v[4:7], v[236:239], v[190:193], v[4:7]
	v_mul_f32_e64 v68, |v64|, v220
	v_mul_f32_e64 v69, |v65|, v220
	v_exp_f32_e32 v68, v68
	v_exp_f32_e32 v69, v69
	v_min_f32_e32 v70, 0, v64
	v_min_f32_e32 v71, 0, v65
	v_pk_add_f32 v[68:69], v[68:69], v[222:223]
	s_nop 0
	v_log_f32_e32 v138, v68
	v_log_f32_e32 v139, v69
	s_nop 0
	v_pk_mul_f32 v[140:141], v[138:139], v[224:225]
	s_nop 0
	v_pk_fma_f32 v[142:143], v[138:139], v[224:225], v[140:141] neg_lo:[0,0,1] neg_hi:[0,0,1]
	s_nop 0
	v_pk_fma_f32 v[142:143], v[138:139], v[226:227], v[142:143]
	s_nop 0
	v_pk_fma_f32 v[142:143], v[138:139], v[224:225], v[142:143]
	s_nop 0
	v_pk_add_f32 v[144:145], v[70:71], v[142:143] neg_lo:[0,1] neg_hi:[0,1]
	s_nop 0
	v_pk_mul_f32 v[144:145], v[144:145], v[214:215]
	v_cvt_pk_bf16_f32 v244, v0, v1
	v_cvt_pk_bf16_f32 v245, v2, v3
	v_cvt_pk_bf16_f32 v246, v4, v5
	v_cvt_pk_bf16_f32 v247, v6, v7
	global_store_dwordx2 v234, v[244:245], s[100:101]
	global_store_dwordx2 v235, v[246:247], s[100:101]
	s_add_u32 s100, s100, 0x40000
	s_addc_u32 s101, s101, 0
	v_add_f32_dpp v144, v144, v144 row_shr:1 row_mask:0xf bank_mask:0xf
	v_add_f32_dpp v145, v145, v145 row_shr:1 row_mask:0xf bank_mask:0xf
	s_nop 0
	v_add_f32_dpp v144, v144, v144 row_shr:2 row_mask:0xf bank_mask:0xf
	v_add_f32_dpp v145, v145, v145 row_shr:2 row_mask:0xf bank_mask:0xf
	s_nop 0
	v_add_f32_dpp v144, v144, v144 row_shr:4 row_mask:0xf bank_mask:0xf
	v_add_f32_dpp v145, v145, v145 row_shr:4 row_mask:0xf bank_mask:0xf
	s_nop 0
	v_add_f32_dpp v144, v144, v144 row_shr:8 row_mask:0xf bank_mask:0xf
	v_add_f32_dpp v145, v145, v145 row_shr:8 row_mask:0xf bank_mask:0xf
	s_nop 0
	v_add_f32_dpp v144, v144, v144 row_bcast:15 row_mask:0xa bank_mask:0xf
	v_add_f32_dpp v145, v145, v145 row_bcast:15 row_mask:0xa bank_mask:0xf
	s_nop 0
	v_add_f32_dpp v144, v144, v144 row_bcast:31 row_mask:0xc bank_mask:0xf
	v_add_f32_dpp v145, v145, v145 row_bcast:31 row_mask:0xc bank_mask:0xf
	s_nop 0
	v_readlane_b32 s98, v144, 63
	v_readlane_b32 s99, v145, 63
	s_nop 1
	v_pk_add_f32 v[146:147], s[98:99], v[144:145] neg_lo:[0,1] neg_hi:[0,1]
	v_mul_f32_e64 v152, s98, v228
	v_mul_f32_e64 v153, s99, v228
	v_pk_mul_f32 v[146:147], v[146:147], v[228:229]
	v_exp_f32_e32 v152, v152
	v_exp_f32_e32 v153, v153
	v_exp_f32_e32 v146, v146
	v_exp_f32_e32 v147, v147
	s_nop 0
	v_pk_mul_f32 v[146:147], v[146:147], v[148:149]
	s_nop 0
	v_cvt_pk_bf16_f32 v150, v146, v147
	s_nop 0
	ds_write_b16 v172, v150 offset:2048
	ds_write_b16_d16_hi v172, v150 offset:2176
	s_and_saveexec_b64 s[20:21], vcc
	ds_write_b64 v163, v[152:153] offset:4160
	s_mov_b64 exec, s[20:21]
	s_waitcnt vmcnt(22)
	ds_write_b64 v28, v[48:49] offset:0
	ds_write_b32 v30, v50 offset:0
	s_waitcnt lgkmcnt(0)
	s_barrier
	ds_read_b128 v[8:11], v29 offset:0
	ds_read_b128 v[12:15], v29 offset:16
	ds_read_b128 v[16:19], v29 offset:32
	ds_read_b128 v[20:23], v29 offset:48
	ds_read_b32 v24, v31 offset:0
	s_sub_u32 s28, s28, 1
	s_cmp_lg_u32 s28, 0
	s_cbranch_scc1 .Lgscan_loop
; DI float bf2f(unsigned x) { return __uint_as_float(x << 16); }
;     ...
;         auto ldchunk = [&](int n) {
;             const int tok = b * 4096 + n * 64 + l;
; #pragma unroll
;             for (int q = 0; q < 4; ++q) a4n[q] = *(const f32x4*)(GA + (size_t)tok * 16 + 4 * q);
;             krawn = *(const unsigned*)(GK + (size_t)tok * 512 + kc0);
; #pragma unroll
;             for (int e = 0; e < 2; ++e)
; #pragma unroll
;                 for (int ks = 0; ks < 2; ++ks)
;                     vfrn[e][ks] = *(const bf16x8*)(GVT + ((size_t)(b * 1024 + hh * 256 + (2 * w + e) * 16 + (l & 15))) * 4096 + n * 64 + ks * 32 + (l >> 4) * 8);
;         };
;         ldchunk(0);
;         for (int n = 0; n < 64; ++n) {
;             const int buf = n & 1;
;             f32x4 a4[4]; bf16x8 vfr[2][2];
; #pragma unroll
;             for (int q = 0; q < 4; ++q) a4[q] = a4n[q];
;             const unsigned kraw = krawn;
; #pragma unroll
;             for (int e = 0; e < 2; ++e)
; #pragma unroll
;                 for (int ks = 0; ks < 2; ++ks) vfr[e][ks] = vfrn[e][ks];
;             if (n + 1 < 64) ldchunk(n + 1);
;             float cum[2];
; #pragma unroll
;             for (int e = 0; e < 2; ++e) {
;                 float z = bb[e];
; #pragma unroll
;                 for (int q = 0; q < 4; ++q) { z += a4[q].x * wa[e][4 * q] + a4[q].y * wa[e][4 * q + 1] + a4[q].z * wa[e][4 * q + 2] + a4[q].w * wa[e][4 * q + 3]; }
;                 cum[e] = (fminf(z, 0.f) - __logf(1.f + __expf(-fabsf(z)))) * (1.f / 16.f);
;             }
; #pragma unroll
;             for (int o = 1; o < 64; o <<= 1) {
;                 const float t0 = __shfl_up(cum[0], o), t1 = __shfl_up(cum[1], o);
;                 if (l >= o) { cum[0] += t0; cum[1] += t1; }
;             }
;             const float tot0 = __shfl(cum[0], 63), tot1 = __shfl(cum[1], 63);
;             kdl[(buf * 16 + 2 * w) * 64 + l] = f2bf(bf2f(kraw & 0xffffu) * __expf(tot0 - cum[0]));
;             kdl[(buf * 16 + 2 * w + 1) * 64 + l] = f2bf(bf2f(kraw >> 16) * __expf(tot1 - cum[1]));
;             if (l == 0) { decl[buf * 16 + 2 * w] = __expf(tot0); decl[buf * 16 + 2 * w + 1] = __expf(tot1); }
;             __syncthreads();
;             const f32x4 d4 = *(const f32x4*)(decl + buf * 16 + (l >> 4) * 4);
; #pragma unroll
;             for (int e = 0; e < 2; ++e) acc[e] = acc[e] * d4;
; #pragma unroll
;             for (int ks = 0; ks < 2; ++ks) {
	global_load_dwordx2 v[48:49], v230, s[26:27]
	global_load_dword v50, v231, s[58:59]
	s_add_u32 s26, s26, 0x1000
	s_addc_u32 s27, s27, 0
	s_add_u32 s58, s58, 0x10000
	s_addc_u32 s59, s59, 0
	global_load_dwordx4 v[178:181], v232, s[34:35]
	global_load_dwordx4 v[182:185], v233, s[34:35]
	global_load_dwordx4 v[186:189], v232, s[34:35] offset:1024
	global_load_dwordx4 v[190:193], v233, s[34:35] offset:1024
	s_add_u32 s34, s34, 0x8000
	s_addc_u32 s35, s35, 0
	ds_read_b128 v[154:157], v75 offset:2048
	ds_read_b128 v[240:243], v164 offset:4160
	ds_read_b128 v[236:239], v75 offset:2112
	s_waitcnt lgkmcnt(3)
	v_pk_fma_f32 v[64:65], v[8:9], v[86:87], v[118:119] op_sel:[0,0,0] op_sel_hi:[0,1,1]
	v_pk_mul_f32 v[66:67], v[16:17], v[102:103] op_sel:[0,0] op_sel_hi:[0,1]
	v_pk_fma_f32 v[64:65], v[8:9], v[88:89], v[64:65] op_sel:[1,0,0] op_sel_hi:[1,1,1]
	v_pk_fma_f32 v[66:67], v[16:17], v[104:105], v[66:67] op_sel:[1,0,0] op_sel_hi:[1,1,1]
	v_pk_fma_f32 v[64:65], v[10:11], v[90:91], v[64:65] op_sel:[0,0,0] op_sel_hi:[0,1,1]
	v_pk_fma_f32 v[66:67], v[18:19], v[106:107], v[66:67] op_sel:[0,0,0] op_sel_hi:[0,1,1]
	v_pk_fma_f32 v[64:65], v[10:11], v[92:93], v[64:65] op_sel:[1,0,0] op_sel_hi:[1,1,1]
	v_pk_fma_f32 v[66:67], v[18:19], v[108:109], v[66:67] op_sel:[1,0,0] op_sel_hi:[1,1,1]
	v_pk_fma_f32 v[64:65], v[12:13], v[94:95], v[64:65] op_sel:[0,0,0] op_sel_hi:[0,1,1]
	v_pk_fma_f32 v[66:67], v[20:21], v[110:111], v[66:67] op_sel:[0,0,0] op_sel_hi:[0,1,1]
	v_pk_fma_f32 v[64:65], v[12:13], v[96:97], v[64:65] op_sel:[1,0,0] op_sel_hi:[1,1,1]
	v_pk_fma_f32 v[66:67], v[20:21], v[112:113], v[66:67] op_sel:[1,0,0] op_sel_hi:[1,1,1]
	v_pk_fma_f32 v[64:65], v[14:15], v[98:99], v[64:65] op_sel:[0,0,0] op_sel_hi:[0,1,1]
	v_pk_fma_f32 v[66:67], v[22:23], v[114:115], v[66:67] op_sel:[0,0,0] op_sel_hi:[0,1,1]
	v_pk_fma_f32 v[64:65], v[14:15], v[100:101], v[64:65] op_sel:[1,0,0] op_sel_hi:[1,1,1]
	v_pk_fma_f32 v[66:67], v[22:23], v[116:117], v[66:67] op_sel:[1,0,0] op_sel_hi:[1,1,1]
	v_lshlrev_b32_e32 v148, 16, v24
	v_pk_add_f32 v[64:65], v[64:65], v[66:67]
	v_and_b32_e32 v149, 0xffff0000, v24
	s_waitcnt lgkmcnt(0)
	v_pk_mul_f32 v[0:1], v[0:1], v[240:241]
	v_pk_mul_f32 v[2:3], v[2:3], v[242:243]
	v_pk_mul_f32 v[4:5], v[4:5], v[240:241]
	v_pk_mul_f32 v[6:7], v[6:7], v[242:243]
	s_waitcnt vmcnt(16)
	s_nop 0
	v_mfma_f32_16x16x32_bf16 v[0:3], v[154:157], v[194:197], v[0:3]
	v_mfma_f32_16x16x32_bf16 v[4:7], v[154:157], v[202:205], v[4:7]
	v_mfma_f32_16x16x32_bf16 v[0:3], v[236:239], v[198:201], v[0:3]
	v_mfma_f32_16x16x32_bf16 v[4:7], v[236:239], v[206:209], v[4:7]
	v_mul_f32_e64 v68, |v64|, v220
	v_mul_f32_e64 v69, |v65|, v220
	v_exp_f32_e32 v68, v68
	v_exp_f32_e32 v69, v69
	v_min_f32_e32 v70, 0, v64
	v_min_f32_e32 v71, 0, v65
	v_pk_add_f32 v[68:69], v[68:69], v[222:223]
	s_nop 0
	v_log_f32_e32 v138, v68
	v_log_f32_e32 v139, v69
	s_nop 0
	v_pk_mul_f32 v[140:141], v[138:139], v[224:225]
	s_nop 0
	v_pk_fma_f32 v[142:143], v[138:139], v[224:225], v[140:141] neg_lo:[0,0,1] neg_hi:[0,0,1]
	s_nop 0
	v_pk_fma_f32 v[142:143], v[138:139], v[226:227], v[142:143]
	s_nop 0
	v_pk_fma_f32 v[142:143], v[138:139], v[224:225], v[142:143]
	s_nop 0
	v_pk_add_f32 v[144:145], v[70:71], v[142:143] neg_lo:[0,1] neg_hi:[0,1]
	s_nop 0
	v_pk_mul_f32 v[144:145], v[144:145], v[214:215]
	v_cvt_pk_bf16_f32 v244, v0, v1
	v_cvt_pk_bf16_f32 v245, v2, v3
	v_cvt_pk_bf16_f32 v246, v4, v5
	v_cvt_pk_bf16_f32 v247, v6, v7
	global_store_dwordx2 v234, v[244:245], s[100:101]
	global_store_dwordx2 v235, v[246:247], s[100:101]
	s_add_u32 s100, s100, 0x40000
	s_addc_u32 s101, s101, 0
	v_add_f32_dpp v144, v144, v144 row_shr:1 row_mask:0xf bank_mask:0xf
	v_add_f32_dpp v145, v145, v145 row_shr:1 row_mask:0xf bank_mask:0xf
	s_nop 0
	v_add_f32_dpp v144, v144, v144 row_shr:2 row_mask:0xf bank_mask:0xf
	v_add_f32_dpp v145, v145, v145 row_shr:2 row_mask:0xf bank_mask:0xf
	s_nop 0
	v_add_f32_dpp v144, v144, v144 row_shr:4 row_mask:0xf bank_mask:0xf
	v_add_f32_dpp v145, v145, v145 row_shr:4 row_mask:0xf bank_mask:0xf
	s_nop 0
	v_add_f32_dpp v144, v144, v144 row_shr:8 row_mask:0xf bank_mask:0xf
	v_add_f32_dpp v145, v145, v145 row_shr:8 row_mask:0xf bank_mask:0xf
	s_nop 0
	v_add_f32_dpp v144, v144, v144 row_bcast:15 row_mask:0xa bank_mask:0xf
	v_add_f32_dpp v145, v145, v145 row_bcast:15 row_mask:0xa bank_mask:0xf
	s_nop 0
	v_add_f32_dpp v144, v144, v144 row_bcast:31 row_mask:0xc bank_mask:0xf
	v_add_f32_dpp v145, v145, v145 row_bcast:31 row_mask:0xc bank_mask:0xf
	s_nop 0
	v_readlane_b32 s98, v144, 63
	v_readlane_b32 s99, v145, 63
	s_nop 1
	v_pk_add_f32 v[146:147], s[98:99], v[144:145] neg_lo:[0,1] neg_hi:[0,1]
	v_mul_f32_e64 v152, s98, v228
	v_mul_f32_e64 v153, s99, v228
	v_pk_mul_f32 v[146:147], v[146:147], v[228:229]
	v_exp_f32_e32 v152, v152
	v_exp_f32_e32 v153, v153
	v_exp_f32_e32 v146, v146
	v_exp_f32_e32 v147, v147
	s_nop 0
	v_pk_mul_f32 v[146:147], v[146:147], v[148:149]
	s_nop 0
	v_cvt_pk_bf16_f32 v150, v146, v147
	s_nop 0
	ds_write_b16 v172, v150 offset:0
	ds_write_b16_d16_hi v172, v150 offset:128
	s_and_saveexec_b64 s[20:21], vcc
	ds_write_b64 v163, v[152:153] offset:4096
	s_mov_b64 exec, s[20:21]
	s_waitcnt vmcnt(22)
	ds_write_b64 v28, v[52:53] offset:5120
	ds_write_b32 v30, v54 offset:2080
	s_waitcnt lgkmcnt(0)
	s_barrier
; DI float bf2f(unsigned x) { return __uint_as_float(x << 16); }
;     ...
;         auto ldchunk = [&](int n) {
;             const int tok = b * 4096 + n * 64 + l;
; #pragma unroll
;             for (int q = 0; q < 4; ++q) a4n[q] = *(const f32x4*)(GA + (size_t)tok * 16 + 4 * q);
;             krawn = *(const unsigned*)(GK + (size_t)tok * 512 + kc0);
; #pragma unroll
;             for (int e = 0; e < 2; ++e)
; #pragma unroll
;                 for (int ks = 0; ks < 2; ++ks)
;                     vfrn[e][ks] = *(const bf16x8*)(GVT + ((size_t)(b * 1024 + hh * 256 + (2 * w + e) * 16 + (l & 15))) * 4096 + n * 64 + ks * 32 + (l >> 4) * 8);
;         };
;         ldchunk(0);
;         for (int n = 0; n < 64; ++n) {
;             const int buf = n & 1;
;             f32x4 a4[4]; bf16x8 vfr[2][2];
; #pragma unroll
;             for (int q = 0; q < 4; ++q) a4[q] = a4n[q];
;             const unsigned kraw = krawn;
; #pragma unroll
;             for (int e = 0; e < 2; ++e)
; #pragma unroll
;                 for (int ks = 0; ks < 2; ++ks) vfr[e][ks] = vfrn[e][ks];
;             if (n + 1 < 64) ldchunk(n + 1);
;             float cum[2];
; #pragma unroll
;             for (int e = 0; e < 2; ++e) {
;                 float z = bb[e];
; #pragma unroll
;                 for (int q = 0; q < 4; ++q) { z += a4[q].x * wa[e][4 * q] + a4[q].y * wa[e][4 * q + 1] + a4[q].z * wa[e][4 * q + 2] + a4[q].w * wa[e][4 * q + 3]; }
;                 cum[e] = (fminf(z, 0.f) - __logf(1.f + __expf(-fabsf(z)))) * (1.f / 16.f);
;             }
; #pragma unroll
;             for (int o = 1; o < 64; o <<= 1) {
;                 const float t0 = __shfl_up(cum[0], o), t1 = __shfl_up(cum[1], o);
;                 if (l >= o) { cum[0] += t0; cum[1] += t1; }
;             }
;             const float tot0 = __shfl(cum[0], 63), tot1 = __shfl(cum[1], 63);
;             kdl[(buf * 16 + 2 * w) * 64 + l] = f2bf(bf2f(kraw & 0xffffu) * __expf(tot0 - cum[0]));
;             kdl[(buf * 16 + 2 * w + 1) * 64 + l] = f2bf(bf2f(kraw >> 16) * __expf(tot1 - cum[1]));
;             if (l == 0) { decl[buf * 16 + 2 * w] = __expf(tot0); decl[buf * 16 + 2 * w + 1] = __expf(tot1); }
;             __syncthreads();
;             const f32x4 d4 = *(const f32x4*)(decl + buf * 16 + (l >> 4) * 4);
; #pragma unroll
;             for (int e = 0; e < 2; ++e) acc[e] = acc[e] * d4;
; #pragma unroll
;             for (int ks = 0; ks < 2; ++ks) {
	ds_read_b128 v[8:11], v29 offset:5120
	ds_read_b128 v[12:15], v29 offset:5136
	ds_read_b128 v[16:19], v29 offset:5152
	ds_read_b128 v[20:23], v29 offset:5168
	ds_read_b32 v24, v31 offset:2080
	global_load_dwordx4 v[194:197], v232, s[34:35]
	global_load_dwordx4 v[198:201], v233, s[34:35]
	global_load_dwordx4 v[202:205], v232, s[34:35] offset:1024
	global_load_dwordx4 v[206:209], v233, s[34:35] offset:1024
	s_add_u32 s34, s34, 0x8000
	s_addc_u32 s35, s35, 0
	ds_read_b128 v[154:157], v75 offset:0
	ds_read_b128 v[240:243], v164 offset:4096
	ds_read_b128 v[236:239], v75 offset:64
	s_waitcnt lgkmcnt(3)
	v_pk_fma_f32 v[64:65], v[8:9], v[86:87], v[118:119] op_sel:[0,0,0] op_sel_hi:[0,1,1]
	v_pk_mul_f32 v[66:67], v[16:17], v[102:103] op_sel:[0,0] op_sel_hi:[0,1]
	v_pk_fma_f32 v[64:65], v[8:9], v[88:89], v[64:65] op_sel:[1,0,0] op_sel_hi:[1,1,1]
	v_pk_fma_f32 v[66:67], v[16:17], v[104:105], v[66:67] op_sel:[1,0,0] op_sel_hi:[1,1,1]
	v_pk_fma_f32 v[64:65], v[10:11], v[90:91], v[64:65] op_sel:[0,0,0] op_sel_hi:[0,1,1]
	v_pk_fma_f32 v[66:67], v[18:19], v[106:107], v[66:67] op_sel:[0,0,0] op_sel_hi:[0,1,1]
	v_pk_fma_f32 v[64:65], v[10:11], v[92:93], v[64:65] op_sel:[1,0,0] op_sel_hi:[1,1,1]
	v_pk_fma_f32 v[66:67], v[18:19], v[108:109], v[66:67] op_sel:[1,0,0] op_sel_hi:[1,1,1]
	v_pk_fma_f32 v[64:65], v[12:13], v[94:95], v[64:65] op_sel:[0,0,0] op_sel_hi:[0,1,1]
	v_pk_fma_f32 v[66:67], v[20:21], v[110:111], v[66:67] op_sel:[0,0,0] op_sel_hi:[0,1,1]
	v_pk_fma_f32 v[64:65], v[12:13], v[96:97], v[64:65] op_sel:[1,0,0] op_sel_hi:[1,1,1]
	v_pk_fma_f32 v[66:67], v[20:21], v[112:113], v[66:67] op_sel:[1,0,0] op_sel_hi:[1,1,1]
	v_pk_fma_f32 v[64:65], v[14:15], v[98:99], v[64:65] op_sel:[0,0,0] op_sel_hi:[0,1,1]
	v_pk_fma_f32 v[66:67], v[22:23], v[114:115], v[66:67] op_sel:[0,0,0] op_sel_hi:[0,1,1]
	v_pk_fma_f32 v[64:65], v[14:15], v[100:101], v[64:65] op_sel:[1,0,0] op_sel_hi:[1,1,1]
	v_pk_fma_f32 v[66:67], v[22:23], v[116:117], v[66:67] op_sel:[1,0,0] op_sel_hi:[1,1,1]
	v_lshlrev_b32_e32 v148, 16, v24
	v_pk_add_f32 v[64:65], v[64:65], v[66:67]
	v_and_b32_e32 v149, 0xffff0000, v24
	s_waitcnt lgkmcnt(0)
	v_pk_mul_f32 v[0:1], v[0:1], v[240:241]
	v_pk_mul_f32 v[2:3], v[2:3], v[242:243]
	v_pk_mul_f32 v[4:5], v[4:5], v[240:241]
	v_pk_mul_f32 v[6:7], v[6:7], v[242:243]
	s_waitcnt vmcnt(14)
	s_nop 0
	v_mfma_f32_16x16x32_bf16 v[0:3], v[154:157], v[32:35], v[0:3]
	v_mfma_f32_16x16x32_bf16 v[4:7], v[154:157], v[40:43], v[4:7]
	v_mfma_f32_16x16x32_bf16 v[0:3], v[236:239], v[36:39], v[0:3]
	v_mfma_f32_16x16x32_bf16 v[4:7], v[236:239], v[44:47], v[4:7]
	v_mul_f32_e64 v68, |v64|, v220
	v_mul_f32_e64 v69, |v65|, v220
	v_exp_f32_e32 v68, v68
	v_exp_f32_e32 v69, v69
	v_min_f32_e32 v70, 0, v64
	v_min_f32_e32 v71, 0, v65
	v_pk_add_f32 v[68:69], v[68:69], v[222:223]
	s_nop 0
	v_log_f32_e32 v138, v68
	v_log_f32_e32 v139, v69
	s_nop 0
	v_pk_mul_f32 v[140:141], v[138:139], v[224:225]
	s_nop 0
	v_pk_fma_f32 v[142:143], v[138:139], v[224:225], v[140:141] neg_lo:[0,0,1] neg_hi:[0,0,1]
	s_nop 0
	v_pk_fma_f32 v[142:143], v[138:139], v[226:227], v[142:143]
	s_nop 0
	v_pk_fma_f32 v[142:143], v[138:139], v[224:225], v[142:143]
	s_nop 0
	v_pk_add_f32 v[144:145], v[70:71], v[142:143] neg_lo:[0,1] neg_hi:[0,1]
	s_nop 0
	v_pk_mul_f32 v[144:145], v[144:145], v[214:215]
	v_cvt_pk_bf16_f32 v244, v0, v1
	v_cvt_pk_bf16_f32 v245, v2, v3
	v_cvt_pk_bf16_f32 v246, v4, v5
	v_cvt_pk_bf16_f32 v247, v6, v7
	global_store_dwordx2 v234, v[244:245], s[100:101]
	global_store_dwordx2 v235, v[246:247], s[100:101]
	s_add_u32 s100, s100, 0x40000
	s_addc_u32 s101, s101, 0
	v_add_f32_dpp v144, v144, v144 row_shr:1 row_mask:0xf bank_mask:0xf
	v_add_f32_dpp v145, v145, v145 row_shr:1 row_mask:0xf bank_mask:0xf
	s_nop 0
	v_add_f32_dpp v144, v144, v144 row_shr:2 row_mask:0xf bank_mask:0xf
	v_add_f32_dpp v145, v145, v145 row_shr:2 row_mask:0xf bank_mask:0xf
	s_nop 0
	v_add_f32_dpp v144, v144, v144 row_shr:4 row_mask:0xf bank_mask:0xf
	v_add_f32_dpp v145, v145, v145 row_shr:4 row_mask:0xf bank_mask:0xf
	s_nop 0
	v_add_f32_dpp v144, v144, v144 row_shr:8 row_mask:0xf bank_mask:0xf
	v_add_f32_dpp v145, v145, v145 row_shr:8 row_mask:0xf bank_mask:0xf
	s_nop 0
	v_add_f32_dpp v144, v144, v144 row_bcast:15 row_mask:0xa bank_mask:0xf
	v_add_f32_dpp v145, v145, v145 row_bcast:15 row_mask:0xa bank_mask:0xf
	s_nop 0
	v_add_f32_dpp v144, v144, v144 row_bcast:31 row_mask:0xc bank_mask:0xf
	v_add_f32_dpp v145, v145, v145 row_bcast:31 row_mask:0xc bank_mask:0xf
	s_nop 0
	v_readlane_b32 s98, v144, 63
	v_readlane_b32 s99, v145, 63
	s_nop 1
	v_pk_add_f32 v[146:147], s[98:99], v[144:145] neg_lo:[0,1] neg_hi:[0,1]
	v_mul_f32_e64 v152, s98, v228
	v_mul_f32_e64 v153, s99, v228
	v_pk_mul_f32 v[146:147], v[146:147], v[228:229]
	v_exp_f32_e32 v152, v152
	v_exp_f32_e32 v153, v153
	v_exp_f32_e32 v146, v146
	v_exp_f32_e32 v147, v147
	s_nop 0
	v_pk_mul_f32 v[146:147], v[146:147], v[148:149]
	s_nop 0
	v_cvt_pk_bf16_f32 v150, v146, v147
	s_nop 0
	ds_write_b16 v172, v150 offset:2048
	ds_write_b16_d16_hi v172, v150 offset:2176
	s_and_saveexec_b64 s[20:21], vcc
	ds_write_b64 v163, v[152:153] offset:4160
	s_mov_b64 exec, s[20:21]
	s_waitcnt vmcnt(20)
	ds_write_b64 v28, v[56:57] offset:0
	ds_write_b32 v30, v58 offset:0
	s_waitcnt lgkmcnt(0)
	s_barrier
; DI float bf2f(unsigned x) { return __uint_as_float(x << 16); }
;     ...
;         auto ldchunk = [&](int n) {
;             const int tok = b * 4096 + n * 64 + l;
; #pragma unroll
;             for (int q = 0; q < 4; ++q) a4n[q] = *(const f32x4*)(GA + (size_t)tok * 16 + 4 * q);
;             krawn = *(const unsigned*)(GK + (size_t)tok * 512 + kc0);
; #pragma unroll
;             for (int e = 0; e < 2; ++e)
; #pragma unroll
;                 for (int ks = 0; ks < 2; ++ks)
;                     vfrn[e][ks] = *(const bf16x8*)(GVT + ((size_t)(b * 1024 + hh * 256 + (2 * w + e) * 16 + (l & 15))) * 4096 + n * 64 + ks * 32 + (l >> 4) * 8);
;         };
;         ldchunk(0);
;         for (int n = 0; n < 64; ++n) {
;             const int buf = n & 1;
;             f32x4 a4[4]; bf16x8 vfr[2][2];
; #pragma unroll
;             for (int q = 0; q < 4; ++q) a4[q] = a4n[q];
;             const unsigned kraw = krawn;
; #pragma unroll
;             for (int e = 0; e < 2; ++e)
; #pragma unroll
;                 for (int ks = 0; ks < 2; ++ks) vfr[e][ks] = vfrn[e][ks];
;             if (n + 1 < 64) ldchunk(n + 1);
;             float cum[2];
; #pragma unroll
;             for (int e = 0; e < 2; ++e) {
;                 float z = bb[e];
; #pragma unroll
;                 for (int q = 0; q < 4; ++q) { z += a4[q].x * wa[e][4 * q] + a4[q].y * wa[e][4 * q + 1] + a4[q].z * wa[e][4 * q + 2] + a4[q].w * wa[e][4 * q + 3]; }
;                 cum[e] = (fminf(z, 0.f) - __logf(1.f + __expf(-fabsf(z)))) * (1.f / 16.f);
;             }
; #pragma unroll
;             for (int o = 1; o < 64; o <<= 1) {
;                 const float t0 = __shfl_up(cum[0], o), t1 = __shfl_up(cum[1], o);
;                 if (l >= o) { cum[0] += t0; cum[1] += t1; }
;             }
;             const float tot0 = __shfl(cum[0], 63), tot1 = __shfl(cum[1], 63);
;             kdl[(buf * 16 + 2 * w) * 64 + l] = f2bf(bf2f(kraw & 0xffffu) * __expf(tot0 - cum[0]));
;             kdl[(buf * 16 + 2 * w + 1) * 64 + l] = f2bf(bf2f(kraw >> 16) * __expf(tot1 - cum[1]));
;             if (l == 0) { decl[buf * 16 + 2 * w] = __expf(tot0); decl[buf * 16 + 2 * w + 1] = __expf(tot1); }
;             __syncthreads();
;             const f32x4 d4 = *(const f32x4*)(decl + buf * 16 + (l >> 4) * 4);
; #pragma unroll
;             for (int e = 0; e < 2; ++e) acc[e] = acc[e] * d4;
; #pragma unroll
;             for (int ks = 0; ks < 2; ++ks) {
	ds_read_b128 v[8:11], v29 offset:0
	ds_read_b128 v[12:15], v29 offset:16
	ds_read_b128 v[16:19], v29 offset:32
	ds_read_b128 v[20:23], v29 offset:48
	ds_read_b32 v24, v31 offset:0
	global_load_dwordx4 v[32:35], v232, s[34:35]
	global_load_dwordx4 v[36:39], v233, s[34:35]
	global_load_dwordx4 v[40:43], v232, s[34:35] offset:1024
	global_load_dwordx4 v[44:47], v233, s[34:35] offset:1024
	s_add_u32 s34, s34, 0x8000
	s_addc_u32 s35, s35, 0
	ds_read_b128 v[154:157], v75 offset:2048
	ds_read_b128 v[240:243], v164 offset:4160
	ds_read_b128 v[236:239], v75 offset:2112
	s_waitcnt lgkmcnt(3)
	v_pk_fma_f32 v[64:65], v[8:9], v[86:87], v[118:119] op_sel:[0,0,0] op_sel_hi:[0,1,1]
	v_pk_mul_f32 v[66:67], v[16:17], v[102:103] op_sel:[0,0] op_sel_hi:[0,1]
	v_pk_fma_f32 v[64:65], v[8:9], v[88:89], v[64:65] op_sel:[1,0,0] op_sel_hi:[1,1,1]
	v_pk_fma_f32 v[66:67], v[16:17], v[104:105], v[66:67] op_sel:[1,0,0] op_sel_hi:[1,1,1]
	v_pk_fma_f32 v[64:65], v[10:11], v[90:91], v[64:65] op_sel:[0,0,0] op_sel_hi:[0,1,1]
	v_pk_fma_f32 v[66:67], v[18:19], v[106:107], v[66:67] op_sel:[0,0,0] op_sel_hi:[0,1,1]
	v_pk_fma_f32 v[64:65], v[10:11], v[92:93], v[64:65] op_sel:[1,0,0] op_sel_hi:[1,1,1]
	v_pk_fma_f32 v[66:67], v[18:19], v[108:109], v[66:67] op_sel:[1,0,0] op_sel_hi:[1,1,1]
	v_pk_fma_f32 v[64:65], v[12:13], v[94:95], v[64:65] op_sel:[0,0,0] op_sel_hi:[0,1,1]
	v_pk_fma_f32 v[66:67], v[20:21], v[110:111], v[66:67] op_sel:[0,0,0] op_sel_hi:[0,1,1]
	v_pk_fma_f32 v[64:65], v[12:13], v[96:97], v[64:65] op_sel:[1,0,0] op_sel_hi:[1,1,1]
	v_pk_fma_f32 v[66:67], v[20:21], v[112:113], v[66:67] op_sel:[1,0,0] op_sel_hi:[1,1,1]
	v_pk_fma_f32 v[64:65], v[14:15], v[98:99], v[64:65] op_sel:[0,0,0] op_sel_hi:[0,1,1]
	v_pk_fma_f32 v[66:67], v[22:23], v[114:115], v[66:67] op_sel:[0,0,0] op_sel_hi:[0,1,1]
	v_pk_fma_f32 v[64:65], v[14:15], v[100:101], v[64:65] op_sel:[1,0,0] op_sel_hi:[1,1,1]
	v_pk_fma_f32 v[66:67], v[22:23], v[116:117], v[66:67] op_sel:[1,0,0] op_sel_hi:[1,1,1]
	v_lshlrev_b32_e32 v148, 16, v24
	v_pk_add_f32 v[64:65], v[64:65], v[66:67]
	v_and_b32_e32 v149, 0xffff0000, v24
	s_waitcnt lgkmcnt(0)
	v_pk_mul_f32 v[0:1], v[0:1], v[240:241]
	v_pk_mul_f32 v[2:3], v[2:3], v[242:243]
	v_pk_mul_f32 v[4:5], v[4:5], v[240:241]
	v_pk_mul_f32 v[6:7], v[6:7], v[242:243]
	s_waitcnt vmcnt(12)
	s_nop 0
	v_mfma_f32_16x16x32_bf16 v[0:3], v[154:157], v[178:181], v[0:3]
	v_mfma_f32_16x16x32_bf16 v[4:7], v[154:157], v[186:189], v[4:7]
	v_mfma_f32_16x16x32_bf16 v[0:3], v[236:239], v[182:185], v[0:3]
	v_mfma_f32_16x16x32_bf16 v[4:7], v[236:239], v[190:193], v[4:7]
	v_mul_f32_e64 v68, |v64|, v220
	v_mul_f32_e64 v69, |v65|, v220
	v_exp_f32_e32 v68, v68
	v_exp_f32_e32 v69, v69
	v_min_f32_e32 v70, 0, v64
	v_min_f32_e32 v71, 0, v65
	v_pk_add_f32 v[68:69], v[68:69], v[222:223]
	s_nop 0
	v_log_f32_e32 v138, v68
	v_log_f32_e32 v139, v69
	s_nop 0
	v_pk_mul_f32 v[140:141], v[138:139], v[224:225]
	s_nop 0
	v_pk_fma_f32 v[142:143], v[138:139], v[224:225], v[140:141] neg_lo:[0,0,1] neg_hi:[0,0,1]
	s_nop 0
	v_pk_fma_f32 v[142:143], v[138:139], v[226:227], v[142:143]
	s_nop 0
	v_pk_fma_f32 v[142:143], v[138:139], v[224:225], v[142:143]
	s_nop 0
	v_pk_add_f32 v[144:145], v[70:71], v[142:143] neg_lo:[0,1] neg_hi:[0,1]
	s_nop 0
	v_pk_mul_f32 v[144:145], v[144:145], v[214:215]
	v_cvt_pk_bf16_f32 v244, v0, v1
	v_cvt_pk_bf16_f32 v245, v2, v3
	v_cvt_pk_bf16_f32 v246, v4, v5
	v_cvt_pk_bf16_f32 v247, v6, v7
	global_store_dwordx2 v234, v[244:245], s[100:101]
	global_store_dwordx2 v235, v[246:247], s[100:101]
	s_add_u32 s100, s100, 0x40000
	s_addc_u32 s101, s101, 0
	v_add_f32_dpp v144, v144, v144 row_shr:1 row_mask:0xf bank_mask:0xf
	v_add_f32_dpp v145, v145, v145 row_shr:1 row_mask:0xf bank_mask:0xf
	s_nop 0
	v_add_f32_dpp v144, v144, v144 row_shr:2 row_mask:0xf bank_mask:0xf
	v_add_f32_dpp v145, v145, v145 row_shr:2 row_mask:0xf bank_mask:0xf
	s_nop 0
	v_add_f32_dpp v144, v144, v144 row_shr:4 row_mask:0xf bank_mask:0xf
	v_add_f32_dpp v145, v145, v145 row_shr:4 row_mask:0xf bank_mask:0xf
	s_nop 0
	v_add_f32_dpp v144, v144, v144 row_shr:8 row_mask:0xf bank_mask:0xf
	v_add_f32_dpp v145, v145, v145 row_shr:8 row_mask:0xf bank_mask:0xf
	s_nop 0
	v_add_f32_dpp v144, v144, v144 row_bcast:15 row_mask:0xa bank_mask:0xf
	v_add_f32_dpp v145, v145, v145 row_bcast:15 row_mask:0xa bank_mask:0xf
	s_nop 0
	v_add_f32_dpp v144, v144, v144 row_bcast:31 row_mask:0xc bank_mask:0xf
	v_add_f32_dpp v145, v145, v145 row_bcast:31 row_mask:0xc bank_mask:0xf
	s_nop 0
	v_readlane_b32 s98, v144, 63
	v_readlane_b32 s99, v145, 63
	s_nop 1
	v_pk_add_f32 v[146:147], s[98:99], v[144:145] neg_lo:[0,1] neg_hi:[0,1]
	v_mul_f32_e64 v152, s98, v228
	v_mul_f32_e64 v153, s99, v228
	v_pk_mul_f32 v[146:147], v[146:147], v[228:229]
	v_exp_f32_e32 v152, v152
	v_exp_f32_e32 v153, v153
	v_exp_f32_e32 v146, v146
	v_exp_f32_e32 v147, v147
	s_nop 0
	v_pk_mul_f32 v[146:147], v[146:147], v[148:149]
	s_nop 0
	v_cvt_pk_bf16_f32 v150, v146, v147
	s_nop 0
	ds_write_b16 v172, v150 offset:0
	ds_write_b16_d16_hi v172, v150 offset:128
	s_and_saveexec_b64 s[20:21], vcc
	ds_write_b64 v163, v[152:153] offset:4096
	s_mov_b64 exec, s[20:21]
	s_waitcnt vmcnt(18)
	ds_write_b64 v28, v[48:49] offset:5120
	ds_write_b32 v30, v50 offset:2080
	s_waitcnt lgkmcnt(0)
	s_barrier
; #define MFMA16(a, b, c) __builtin_amdgcn_mfma_f32_16x16x32_bf16((a), (b), (c), 0, 0, 0)
; DI bf16_t f2bf(float x) { return (bf16_t)(pk2(x, 0.f) & 0xffffu); }
; DI float bf2f(unsigned x) { return __uint_as_float(x << 16); }
; DI u32x2 pk4(float a, float b, float c, float d) { u32x2 r; r.x = pk2(a, b); r.y = pk2(c, d); return r; }
;     ...
;             for (int e = 0; e < 2; ++e) {
;                 float z = bb[e];
; #pragma unroll
;                 for (int q = 0; q < 4; ++q) { z += a4[q].x * wa[e][4 * q] + a4[q].y * wa[e][4 * q + 1] + a4[q].z * wa[e][4 * q + 2] + a4[q].w * wa[e][4 * q + 3]; }
;                 cum[e] = (fminf(z, 0.f) - __logf(1.f + __expf(-fabsf(z)))) * (1.f / 16.f);
;             }
; #pragma unroll
;             for (int o = 1; o < 64; o <<= 1) {
;                 const float t0 = __shfl_up(cum[0], o), t1 = __shfl_up(cum[1], o);
;                 if (l >= o) { cum[0] += t0; cum[1] += t1; }
;             }
;             const float tot0 = __shfl(cum[0], 63), tot1 = __shfl(cum[1], 63);
;             kdl[(buf * 16 + 2 * w) * 64 + l] = f2bf(bf2f(kraw & 0xffffu) * __expf(tot0 - cum[0]));
;             kdl[(buf * 16 + 2 * w + 1) * 64 + l] = f2bf(bf2f(kraw >> 16) * __expf(tot1 - cum[1]));
;             if (l == 0) { decl[buf * 16 + 2 * w] = __expf(tot0); decl[buf * 16 + 2 * w + 1] = __expf(tot1); }
;             __syncthreads();
;             const f32x4 d4 = *(const f32x4*)(decl + buf * 16 + (l >> 4) * 4);
; #pragma unroll
;             for (int e = 0; e < 2; ++e) acc[e] = acc[e] * d4;
; #pragma unroll
;             for (int ks = 0; ks < 2; ++ks) {
;                 const bf16x8 af = *(const bf16x8*)(kdl + (buf * 16 + (l & 15)) * 64 + ks * 32 + (l >> 4) * 8);
; #pragma unroll
;                 for (int e = 0; e < 2; ++e) acc[e] = MFMA16(af, vfr[e][ks], acc[e]);
;             }
;             const int cidx = b * 64 + n;
; #pragma unroll
;             for (int e = 0; e < 2; ++e) {
;                 const int vv = (2 * w + e) * 16 + (l & 15);
;                 *(u32x2*)(ST + (((size_t)(cidx * 4 + hh)) * 256 + vv) * 128 + ksl * 16 + (l >> 4) * 4) = pk4(acc[e].x, acc[e].y, acc[e].z, acc[e].w);
;             }
;         }
;     }
	ds_read_b128 v[8:11], v29 offset:5120
	ds_read_b128 v[12:15], v29 offset:5136
	ds_read_b128 v[16:19], v29 offset:5152
	ds_read_b128 v[20:23], v29 offset:5168
	ds_read_b32 v24, v31 offset:2080
	ds_read_b128 v[154:157], v75 offset:0
	ds_read_b128 v[240:243], v164 offset:4096
	ds_read_b128 v[236:239], v75 offset:64
	s_waitcnt lgkmcnt(3)
	v_pk_fma_f32 v[64:65], v[8:9], v[86:87], v[118:119] op_sel:[0,0,0] op_sel_hi:[0,1,1]
	v_pk_mul_f32 v[66:67], v[16:17], v[102:103] op_sel:[0,0] op_sel_hi:[0,1]
	v_pk_fma_f32 v[64:65], v[8:9], v[88:89], v[64:65] op_sel:[1,0,0] op_sel_hi:[1,1,1]
	v_pk_fma_f32 v[66:67], v[16:17], v[104:105], v[66:67] op_sel:[1,0,0] op_sel_hi:[1,1,1]
	v_pk_fma_f32 v[64:65], v[10:11], v[90:91], v[64:65] op_sel:[0,0,0] op_sel_hi:[0,1,1]
	v_pk_fma_f32 v[66:67], v[18:19], v[106:107], v[66:67] op_sel:[0,0,0] op_sel_hi:[0,1,1]
	v_pk_fma_f32 v[64:65], v[10:11], v[92:93], v[64:65] op_sel:[1,0,0] op_sel_hi:[1,1,1]
	v_pk_fma_f32 v[66:67], v[18:19], v[108:109], v[66:67] op_sel:[1,0,0] op_sel_hi:[1,1,1]
	v_pk_fma_f32 v[64:65], v[12:13], v[94:95], v[64:65] op_sel:[0,0,0] op_sel_hi:[0,1,1]
	v_pk_fma_f32 v[66:67], v[20:21], v[110:111], v[66:67] op_sel:[0,0,0] op_sel_hi:[0,1,1]
	v_pk_fma_f32 v[64:65], v[12:13], v[96:97], v[64:65] op_sel:[1,0,0] op_sel_hi:[1,1,1]
	v_pk_fma_f32 v[66:67], v[20:21], v[112:113], v[66:67] op_sel:[1,0,0] op_sel_hi:[1,1,1]
	v_pk_fma_f32 v[64:65], v[14:15], v[98:99], v[64:65] op_sel:[0,0,0] op_sel_hi:[0,1,1]
	v_pk_fma_f32 v[66:67], v[22:23], v[114:115], v[66:67] op_sel:[0,0,0] op_sel_hi:[0,1,1]
	v_pk_fma_f32 v[64:65], v[14:15], v[100:101], v[64:65] op_sel:[1,0,0] op_sel_hi:[1,1,1]
	v_pk_fma_f32 v[66:67], v[22:23], v[116:117], v[66:67] op_sel:[1,0,0] op_sel_hi:[1,1,1]
	v_lshlrev_b32_e32 v148, 16, v24
	v_pk_add_f32 v[64:65], v[64:65], v[66:67]
	v_and_b32_e32 v149, 0xffff0000, v24
	s_waitcnt lgkmcnt(0)
	v_pk_mul_f32 v[0:1], v[0:1], v[240:241]
	v_pk_mul_f32 v[2:3], v[2:3], v[242:243]
	v_pk_mul_f32 v[4:5], v[4:5], v[240:241]
	v_pk_mul_f32 v[6:7], v[6:7], v[242:243]
	s_waitcnt vmcnt(8)
	s_nop 0
	v_mfma_f32_16x16x32_bf16 v[0:3], v[154:157], v[194:197], v[0:3]
	v_mfma_f32_16x16x32_bf16 v[4:7], v[154:157], v[202:205], v[4:7]
	v_mfma_f32_16x16x32_bf16 v[0:3], v[236:239], v[198:201], v[0:3]
	v_mfma_f32_16x16x32_bf16 v[4:7], v[236:239], v[206:209], v[4:7]
	v_mul_f32_e64 v68, |v64|, v220
	v_mul_f32_e64 v69, |v65|, v220
	v_exp_f32_e32 v68, v68
	v_exp_f32_e32 v69, v69
	v_min_f32_e32 v70, 0, v64
	v_min_f32_e32 v71, 0, v65
	v_pk_add_f32 v[68:69], v[68:69], v[222:223]
	s_nop 0
	v_log_f32_e32 v138, v68
	v_log_f32_e32 v139, v69
	s_nop 0
	v_pk_mul_f32 v[140:141], v[138:139], v[224:225]
	s_nop 0
	v_pk_fma_f32 v[142:143], v[138:139], v[224:225], v[140:141] neg_lo:[0,0,1] neg_hi:[0,0,1]
	s_nop 0
	v_pk_fma_f32 v[142:143], v[138:139], v[226:227], v[142:143]
	s_nop 0
	v_pk_fma_f32 v[142:143], v[138:139], v[224:225], v[142:143]
	s_nop 0
	v_pk_add_f32 v[144:145], v[70:71], v[142:143] neg_lo:[0,1] neg_hi:[0,1]
	s_nop 0
	v_pk_mul_f32 v[144:145], v[144:145], v[214:215]
	v_cvt_pk_bf16_f32 v244, v0, v1
	v_cvt_pk_bf16_f32 v245, v2, v3
	v_cvt_pk_bf16_f32 v246, v4, v5
	v_cvt_pk_bf16_f32 v247, v6, v7
	global_store_dwordx2 v234, v[244:245], s[100:101]
	global_store_dwordx2 v235, v[246:247], s[100:101]
	s_add_u32 s100, s100, 0x40000
	s_addc_u32 s101, s101, 0
	v_add_f32_dpp v144, v144, v144 row_shr:1 row_mask:0xf bank_mask:0xf
	v_add_f32_dpp v145, v145, v145 row_shr:1 row_mask:0xf bank_mask:0xf
	s_nop 0
	v_add_f32_dpp v144, v144, v144 row_shr:2 row_mask:0xf bank_mask:0xf
	v_add_f32_dpp v145, v145, v145 row_shr:2 row_mask:0xf bank_mask:0xf
	s_nop 0
	v_add_f32_dpp v144, v144, v144 row_shr:4 row_mask:0xf bank_mask:0xf
	v_add_f32_dpp v145, v145, v145 row_shr:4 row_mask:0xf bank_mask:0xf
	s_nop 0
	v_add_f32_dpp v144, v144, v144 row_shr:8 row_mask:0xf bank_mask:0xf
	v_add_f32_dpp v145, v145, v145 row_shr:8 row_mask:0xf bank_mask:0xf
	s_nop 0
	v_add_f32_dpp v144, v144, v144 row_bcast:15 row_mask:0xa bank_mask:0xf
	v_add_f32_dpp v145, v145, v145 row_bcast:15 row_mask:0xa bank_mask:0xf
	s_nop 0
	v_add_f32_dpp v144, v144, v144 row_bcast:31 row_mask:0xc bank_mask:0xf
	v_add_f32_dpp v145, v145, v145 row_bcast:31 row_mask:0xc bank_mask:0xf
	s_nop 0
	v_readlane_b32 s98, v144, 63
	v_readlane_b32 s99, v145, 63
	s_nop 1
	v_pk_add_f32 v[146:147], s[98:99], v[144:145] neg_lo:[0,1] neg_hi:[0,1]
	v_mul_f32_e64 v152, s98, v228
	v_mul_f32_e64 v153, s99, v228
	v_pk_mul_f32 v[146:147], v[146:147], v[228:229]
	v_exp_f32_e32 v152, v152
	v_exp_f32_e32 v153, v153
	v_exp_f32_e32 v146, v146
	v_exp_f32_e32 v147, v147
	s_nop 0
	v_pk_mul_f32 v[146:147], v[146:147], v[148:149]
	s_nop 0
	v_cvt_pk_bf16_f32 v150, v146, v147
	s_nop 0
	ds_write_b16 v172, v150 offset:2048
	ds_write_b16_d16_hi v172, v150 offset:2176
	s_and_saveexec_b64 s[20:21], vcc
	ds_write_b64 v163, v[152:153] offset:4160
	s_mov_b64 exec, s[20:21]
	s_waitcnt lgkmcnt(0)
	s_barrier
	ds_read_b128 v[154:157], v75 offset:2048
	ds_read_b128 v[240:243], v164 offset:4160
	ds_read_b128 v[236:239], v75 offset:2112
	s_waitcnt lgkmcnt(0)
	v_pk_mul_f32 v[0:1], v[0:1], v[240:241]
	v_pk_mul_f32 v[2:3], v[2:3], v[242:243]
	v_pk_mul_f32 v[4:5], v[4:5], v[240:241]
	v_pk_mul_f32 v[6:7], v[6:7], v[242:243]
	s_waitcnt vmcnt(4)
	s_nop 0
	v_mfma_f32_16x16x32_bf16 v[0:3], v[154:157], v[32:35], v[0:3]
	v_mfma_f32_16x16x32_bf16 v[4:7], v[154:157], v[40:43], v[4:7]
	v_mfma_f32_16x16x32_bf16 v[0:3], v[236:239], v[36:39], v[0:3]
	v_mfma_f32_16x16x32_bf16 v[4:7], v[236:239], v[44:47], v[4:7]
	s_nop 7
	s_nop 1
	v_cvt_pk_bf16_f32 v244, v0, v1
	v_cvt_pk_bf16_f32 v245, v2, v3
	v_cvt_pk_bf16_f32 v246, v4, v5
	v_cvt_pk_bf16_f32 v247, v6, v7
	global_store_dwordx2 v234, v[244:245], s[100:101]
	global_store_dwordx2 v235, v[246:247], s[100:101]
	s_add_u32 s100, s100, 0x40000
	s_addc_u32 s101, s101, 0
	s_add_i32 s56, s56, s96
	s_cmpk_gt_i32 s56, 0xff
	s_cbranch_scc0 .LBB0_418
